# layer-2/3 weight conversions (mats 22-28) hosted by the scan phase's staging waves 5-7 in slices; idle-tail conversions re-balanced (R1 tail: mat 29, L1 GU tail: 30-31, L2 GU tail: none)
# speedup vs baseline: 1.0093x; 1.0017x over previous
;     __device__ __forceinline__ void ids() { lane = fresh_lane(); tid = wave * 64 + lane; }
; __device__ __forceinline__ void convert_mats(Frame& F, int m_lo, int m_hi, int gw, int NGW) {
;     ...
;     for (int mi = m_lo; mi < m_hi; ++mi) {
;         const MatI mt = kMats[mi]; const int cnt = (mt.Kp / 64) * (mt.Np / 64);
;         const float* src = in_ptr(F, mt.in_idx) + mt.src_off; const float* gain = mt.gain_idx >= 0 ? in_ptr(F, mt.gain_idx) + mt.gain_off : nullptr; bf16* dst = (bf16*)((unsigned char*)in_ptr(F, T_WS) + mt.dst_off);
;         while (it < base + cnt) {
; template <int L> __device__ __forceinline__ void layer_phases(Frame& F, const int lo, const int hi, const XcdBarrier& bar, const int bid) {
;     ...
;             {
;                 const int rem = (M / 256) * (6912 / 256) % F.G, nidle = rem ? F.G - rem : 0, ci = bid - rem;
;                 F.ids();
;                 if (nidle > 0) { if (ci >= 0) convert_mats(F, 22, 27, ci * NWAVES + F.wave, nidle * NWAVES); }
;                 else convert_mats(F, 22, 27, bid * NWAVES + F.wave, F.G * NWAVES);
;             }
.LBB0_1332:
	s_and_b64 vcc, exec, s[0:1]
	s_cbranch_vccz .LBB0_1449
	s_sub_i32 s0, s2, s33
	s_cmp_lt_i32 s0, 0
	s_mov_b32 s39, 0
	s_cbranch_scc1 .LBB0_1449
	s_lshl_b32 s0, s0, 3
	v_lshlrev_b32_e32 v0, 2, v141
	s_add_i32 s20, s0, s80
	s_lshl_b32 s0, s80, 14
	v_ashrrev_i32_e32 v143, 3, v141
	v_and_b32_e32 v145, 28, v0
	v_and_b32_e32 v0, 7, v141
	s_add_i32 s0, s0, 0
	v_mul_u32_u24_e32 v3, 0x420, v0
	v_lshlrev_b32_e32 v4, 2, v143
	v_lshl_add_u32 v1, v0, 4, s0
	v_add3_u32 v141, s0, v3, v4
	s_movk_i32 s0, 0x84
	v_lshlrev_b32_e32 v2, 3, v0
	v_mul_lo_u32 v3, v143, s0
	s_lshl_b32 s3, s3, 3
	v_mov_b32_e32 v0, 0
	v_add_u32_e32 v147, 8, v143
	v_add_u32_e32 v149, 16, v143
	v_add_u32_e32 v151, 24, v143
	s_mov_b32 s33, 29
	s_add_i32 s34, 0, 0x20520
	v_lshlrev_b32_e32 v132, 1, v2
	v_add_u32_e32 v152, v1, v3
	s_mov_b32 s35, 0
	s_branch .LBB0_1336
.LBB0_1335:
	s_add_i32 s33, s33, 1
	s_cmp_eq_u32 s33, 30
	s_mov_b32 s35, s43
	s_cbranch_scc1 .LBB0_1449

; #define LAS __attribute__((address_space(3)))
; __device__ __forceinline__ void rwkv_scan_phase(Frame& F, const bf16* RKV, const float* WAG, const bf16* AGB, const float* k_k, const float* k_a, const float* r_k, bf16* Y, float* BS, float* ST2) {
;     ...
;             const int row = lane >> 3, kg = lane & 7, vr = 8 * wave + row;
;             typedef float f32x2 __attribute__((ext_vector_type(2)));
;             f32x2 s[4];
; #pragma unroll
;             for (int i = 0; i < 4; ++i) s[i] = (f32x2){0.f, 0.f};
;             __syncthreads();
;             for (int ci = 0; ci < SEQ / SC_T; ++ci) {
;                 const LAS unsigned char* bp = F.lds + (ci & 1) * SC_BUF; LAS float* yb = (LAS float*)(F.lds + SC_YOFF + (ci & 1) * SC_YB);
;     ...
;                 f32x2 r0[4], w0[4], k0[4], a0[4], b0[4], r1[4], w1[4], k1[4], a1[4], b1[4]; float v0, v1;
;                 SC_LOAD(r0, w0, k0, a0, b0, v0, 0);
; #pragma unroll
;                 for (int t = 0; t < SC_T; t += 2) {
;                     SC_LOAD(r1, w1, k1, a1, b1, v1, t + 1);
;                     SC_STEP(r0, w0, k0, a0, b0, v0, t);
;                     if (t + 2 < SC_T) SC_LOAD(r0, w0, k0, a0, b0, v0, t + 2);
;                     SC_STEP(r1, w1, k1, a1, b1, v1, t + 1);
;                 }
.LBB0_1692:
	s_and_b32 s6, s0, 1
	s_mul_i32 s7, s6, 0xb000
	s_lshl_b32 s6, s6, 12
	v_mbcnt_lo_u32_b32 v130, -1, 0
	v_mbcnt_hi_u32_b32 v130, -1, v130
	v_and_b32_e32 v77, 15, v130
	v_lshl_add_u32 v74, v77, 4, s7
	v_lshrrev_b32_e32 v75, 4, v130
	v_lshl_add_u32 v75, s80, 2, v75
	v_lshlrev_b32_e32 v75, 3, v75
	v_lshl_add_u32 v76, v77, 2, v75
	v_add_u32_e32 v76, 0x16000, v76
	v_add_u32_e32 v75, s7, v75
	v_lshlrev_b32_e32 v6, 2, v130
	v_add_u32_e32 v6, 0x18000, v6
	v_add_u32_e32 v76, s6, v76
	v_cmp_gt_u32_e32 vcc, 2, v77
	s_nop 1
	v_cndmask_b32_e32 v76, v6, v76, vcc
	s_mov_b32 vcc_lo, 0xaaaaaaaa
	s_mov_b32 vcc_hi, 0xaaaaaaaa
	ds_read_b128 v[28:31], v74 offset:24576
	ds_read_b128 v[32:35], v74 offset:8192
	ds_read_b128 v[36:39], v74 offset:16384
	ds_read_b128 v[40:43], v74 offset:32768
	ds_read_b128 v[44:47], v74 offset:0
	ds_read_b64 v[48:49], v75 offset:40960
	ds_read_b128 v[106:109], v74 offset:24832
	ds_read_b128 v[110:113], v74 offset:8448
	ds_read_b128 v[114:117], v74 offset:16640
	ds_read_b128 v[118:121], v74 offset:33024
	ds_read_b128 v[122:125], v74 offset:256
	ds_read_b64 v[126:127], v75 offset:41088
	s_waitcnt lgkmcnt(6)
	v_pk_mul_f32 v[0:1], v[8:9], v[28:29] op_sel_hi:[1,0]
	v_pk_mul_f32 v[2:3], v[10:11], v[28:29] op_sel:[0,1]
	v_pk_fma_f32 v[0:1], v[20:21], v[30:31], v[0:1] op_sel_hi:[1,0,1]
	v_pk_fma_f32 v[2:3], v[22:23], v[30:31], v[2:3] op_sel:[0,1,0]
	v_pk_mul_f32 v[12:13], v[8:9], v[32:33] op_sel_hi:[1,0]
	v_pk_add_f32 v[0:1], v[0:1], v[2:3]
	v_pk_mul_f32 v[14:15], v[10:11], v[32:33] op_sel:[0,1]
	v_pk_mul_f32 v[16:17], v[20:21], v[34:35] op_sel_hi:[1,0]
	v_pk_mul_f32 v[18:19], v[22:23], v[34:35] op_sel:[0,1]
	v_add_f32_dpp v0, v0, v0 quad_perm:[1,0,3,2] row_mask:0xf bank_mask:0xf bound_ctrl:1
	v_add_f32_dpp v1, v1, v1 quad_perm:[1,0,3,2] row_mask:0xf bank_mask:0xf bound_ctrl:1
	v_pk_fma_f32 v[12:13], v[36:37], v[48:49], v[12:13] op_sel_hi:[0,1,1]
	v_pk_fma_f32 v[14:15], v[36:37], v[48:49], v[14:15] op_sel:[1,0,0]
	v_add_f32_dpp v0, v0, v0 quad_perm:[2,3,0,1] row_mask:0xf bank_mask:0xf bound_ctrl:1
	v_add_f32_dpp v1, v1, v1 quad_perm:[2,3,0,1] row_mask:0xf bank_mask:0xf bound_ctrl:1
	v_pk_fma_f32 v[16:17], v[38:39], v[48:49], v[16:17] op_sel_hi:[0,1,1]
	v_pk_fma_f32 v[18:19], v[38:39], v[48:49], v[18:19] op_sel:[1,0,0]
	v_add_f32_dpp v0, v0, v0 row_half_mirror row_mask:0xf bank_mask:0xf bound_ctrl:1
	v_add_f32_dpp v1, v1, v1 row_half_mirror row_mask:0xf bank_mask:0xf bound_ctrl:1
	s_nop 0
	v_add_f32_dpp v0, v0, v0 row_mirror row_mask:0xf bank_mask:0xf bound_ctrl:1
	v_add_f32_dpp v1, v1, v1 row_mirror row_mask:0xf bank_mask:0xf bound_ctrl:1
	v_pk_fma_f32 v[8:9], v[40:41], v[0:1], v[12:13] op_sel_hi:[0,1,1]
	v_pk_fma_f32 v[10:11], v[40:41], v[0:1], v[14:15] op_sel:[1,0,0]
	v_pk_fma_f32 v[20:21], v[42:43], v[0:1], v[16:17] op_sel_hi:[0,1,1]
	v_pk_fma_f32 v[22:23], v[42:43], v[0:1], v[18:19] op_sel:[1,0,0]
	v_pk_mul_f32 v[4:5], v[8:9], v[44:45] op_sel_hi:[1,0]
	v_pk_mul_f32 v[6:7], v[10:11], v[44:45] op_sel:[0,1]
	v_pk_fma_f32 v[4:5], v[20:21], v[46:47], v[4:5] op_sel_hi:[1,0,1]
	v_pk_fma_f32 v[6:7], v[22:23], v[46:47], v[6:7] op_sel:[0,1,0]
	ds_read_b128 v[28:31], v74 offset:25088
	ds_read_b128 v[32:35], v74 offset:8704
	ds_read_b128 v[36:39], v74 offset:16896
	ds_read_b128 v[40:43], v74 offset:33280
	ds_read_b128 v[44:47], v74 offset:512
	ds_read_b64 v[48:49], v75 offset:41216
	s_waitcnt lgkmcnt(6)
	v_pk_mul_f32 v[0:1], v[8:9], v[106:107] op_sel_hi:[1,0]
	v_pk_mul_f32 v[2:3], v[10:11], v[106:107] op_sel:[0,1]
	v_pk_fma_f32 v[0:1], v[20:21], v[108:109], v[0:1] op_sel_hi:[1,0,1]
	v_pk_fma_f32 v[2:3], v[22:23], v[108:109], v[2:3] op_sel:[0,1,0]
	v_pk_add_f32 v[4:5], v[4:5], v[6:7]
	v_pk_mul_f32 v[12:13], v[8:9], v[110:111] op_sel_hi:[1,0]
	v_pk_add_f32 v[0:1], v[0:1], v[2:3]
	v_pk_mul_f32 v[14:15], v[10:11], v[110:111] op_sel:[0,1]
	v_cndmask_b32_e32 v24, v4, v5, vcc
	v_cndmask_b32_e32 v25, v5, v4, vcc
	v_pk_mul_f32 v[16:17], v[20:21], v[112:113] op_sel_hi:[1,0]
	v_pk_mul_f32 v[18:19], v[22:23], v[112:113] op_sel:[0,1]
	v_add_f32_dpp v0, v0, v0 quad_perm:[1,0,3,2] row_mask:0xf bank_mask:0xf bound_ctrl:1
	v_add_f32_dpp v1, v1, v1 quad_perm:[1,0,3,2] row_mask:0xf bank_mask:0xf bound_ctrl:1
	v_add_f32_dpp v26, v25, v24 quad_perm:[1,0,3,2] row_mask:0xf bank_mask:0xf bound_ctrl:1
	v_pk_fma_f32 v[12:13], v[114:115], v[126:127], v[12:13] op_sel_hi:[0,1,1]
	v_pk_fma_f32 v[14:15], v[114:115], v[126:127], v[14:15] op_sel:[1,0,0]
	v_add_f32_dpp v0, v0, v0 quad_perm:[2,3,0,1] row_mask:0xf bank_mask:0xf bound_ctrl:1
	v_add_f32_dpp v1, v1, v1 quad_perm:[2,3,0,1] row_mask:0xf bank_mask:0xf bound_ctrl:1
	v_add_f32_dpp v26, v26, v26 quad_perm:[2,3,0,1] row_mask:0xf bank_mask:0xf bound_ctrl:1
	v_pk_fma_f32 v[16:17], v[116:117], v[126:127], v[16:17] op_sel_hi:[0,1,1]
	v_pk_fma_f32 v[18:19], v[116:117], v[126:127], v[18:19] op_sel:[1,0,0]
	v_add_f32_dpp v0, v0, v0 row_half_mirror row_mask:0xf bank_mask:0xf bound_ctrl:1
	v_add_f32_dpp v1, v1, v1 row_half_mirror row_mask:0xf bank_mask:0xf bound_ctrl:1
	v_add_f32_dpp v26, v26, v26 row_ror:4 row_mask:0xf bank_mask:0xf bound_ctrl:1
	s_nop 0
	v_add_f32_dpp v0, v0, v0 row_mirror row_mask:0xf bank_mask:0xf bound_ctrl:1
	v_add_f32_dpp v1, v1, v1 row_mirror row_mask:0xf bank_mask:0xf bound_ctrl:1
	v_add_f32_dpp v26, v26, v26 row_ror:8 row_mask:0xf bank_mask:0xf bound_ctrl:1
	ds_write_b32 v76, v26 offset:0
	v_pk_fma_f32 v[8:9], v[118:119], v[0:1], v[12:13] op_sel_hi:[0,1,1]
	v_pk_fma_f32 v[10:11], v[118:119], v[0:1], v[14:15] op_sel:[1,0,0]
	v_pk_fma_f32 v[20:21], v[120:121], v[0:1], v[16:17] op_sel_hi:[0,1,1]
	v_pk_fma_f32 v[22:23], v[120:121], v[0:1], v[18:19] op_sel:[1,0,0]
	v_pk_mul_f32 v[4:5], v[8:9], v[122:123] op_sel_hi:[1,0]
	v_pk_mul_f32 v[6:7], v[10:11], v[122:123] op_sel:[0,1]
	v_pk_fma_f32 v[4:5], v[20:21], v[124:125], v[4:5] op_sel_hi:[1,0,1]
	v_pk_fma_f32 v[6:7], v[22:23], v[124:125], v[6:7] op_sel:[0,1,0]
	ds_read_b128 v[106:109], v74 offset:25344
	ds_read_b128 v[110:113], v74 offset:8960
	ds_read_b128 v[114:117], v74 offset:17152
	ds_read_b128 v[118:121], v74 offset:33536
	ds_read_b128 v[122:125], v74 offset:768
	ds_read_b64 v[126:127], v75 offset:41344
	s_waitcnt lgkmcnt(7)
; __device__ __forceinline__ void rwkv_scan_phase(Frame& F, const bf16* RKV, const float* WAG, const bf16* AGB, const float* k_k, const float* k_a, const float* r_k, bf16* Y, float* BS, float* ST2) {
;     ...
;                 f32x2 r0[4], w0[4], k0[4], a0[4], b0[4], r1[4], w1[4], k1[4], a1[4], b1[4]; float v0, v1;
;                 SC_LOAD(r0, w0, k0, a0, b0, v0, 0);
; #pragma unroll
;                 for (int t = 0; t < SC_T; t += 2) {
;                     SC_LOAD(r1, w1, k1, a1, b1, v1, t + 1);
;                     SC_STEP(r0, w0, k0, a0, b0, v0, t);
;                     if (t + 2 < SC_T) SC_LOAD(r0, w0, k0, a0, b0, v0, t + 2);
;                     SC_STEP(r1, w1, k1, a1, b1, v1, t + 1);
	v_pk_mul_f32 v[0:1], v[8:9], v[28:29] op_sel_hi:[1,0]
	v_pk_mul_f32 v[2:3], v[10:11], v[28:29] op_sel:[0,1]
	v_pk_fma_f32 v[0:1], v[20:21], v[30:31], v[0:1] op_sel_hi:[1,0,1]
	v_pk_fma_f32 v[2:3], v[22:23], v[30:31], v[2:3] op_sel:[0,1,0]
	v_pk_add_f32 v[4:5], v[4:5], v[6:7]
	v_pk_mul_f32 v[12:13], v[8:9], v[32:33] op_sel_hi:[1,0]
	v_pk_add_f32 v[0:1], v[0:1], v[2:3]
	v_pk_mul_f32 v[14:15], v[10:11], v[32:33] op_sel:[0,1]
	v_cndmask_b32_e32 v24, v4, v5, vcc
	v_cndmask_b32_e32 v25, v5, v4, vcc
	v_pk_mul_f32 v[16:17], v[20:21], v[34:35] op_sel_hi:[1,0]
	v_pk_mul_f32 v[18:19], v[22:23], v[34:35] op_sel:[0,1]
	v_add_f32_dpp v0, v0, v0 quad_perm:[1,0,3,2] row_mask:0xf bank_mask:0xf bound_ctrl:1
	v_add_f32_dpp v1, v1, v1 quad_perm:[1,0,3,2] row_mask:0xf bank_mask:0xf bound_ctrl:1
	v_add_f32_dpp v26, v25, v24 quad_perm:[1,0,3,2] row_mask:0xf bank_mask:0xf bound_ctrl:1
	v_pk_fma_f32 v[12:13], v[36:37], v[48:49], v[12:13] op_sel_hi:[0,1,1]
	v_pk_fma_f32 v[14:15], v[36:37], v[48:49], v[14:15] op_sel:[1,0,0]
	v_add_f32_dpp v0, v0, v0 quad_perm:[2,3,0,1] row_mask:0xf bank_mask:0xf bound_ctrl:1
	v_add_f32_dpp v1, v1, v1 quad_perm:[2,3,0,1] row_mask:0xf bank_mask:0xf bound_ctrl:1
	v_add_f32_dpp v26, v26, v26 quad_perm:[2,3,0,1] row_mask:0xf bank_mask:0xf bound_ctrl:1
	v_pk_fma_f32 v[16:17], v[38:39], v[48:49], v[16:17] op_sel_hi:[0,1,1]
	v_pk_fma_f32 v[18:19], v[38:39], v[48:49], v[18:19] op_sel:[1,0,0]
	v_add_f32_dpp v0, v0, v0 row_half_mirror row_mask:0xf bank_mask:0xf bound_ctrl:1
	v_add_f32_dpp v1, v1, v1 row_half_mirror row_mask:0xf bank_mask:0xf bound_ctrl:1
	v_add_f32_dpp v26, v26, v26 row_ror:4 row_mask:0xf bank_mask:0xf bound_ctrl:1
	s_nop 0
	v_add_f32_dpp v0, v0, v0 row_mirror row_mask:0xf bank_mask:0xf bound_ctrl:1
	v_add_f32_dpp v1, v1, v1 row_mirror row_mask:0xf bank_mask:0xf bound_ctrl:1
	v_add_f32_dpp v26, v26, v26 row_ror:8 row_mask:0xf bank_mask:0xf bound_ctrl:1
	ds_write_b32 v76, v26 offset:128
	v_pk_fma_f32 v[8:9], v[40:41], v[0:1], v[12:13] op_sel_hi:[0,1,1]
	v_pk_fma_f32 v[10:11], v[40:41], v[0:1], v[14:15] op_sel:[1,0,0]
	v_pk_fma_f32 v[20:21], v[42:43], v[0:1], v[16:17] op_sel_hi:[0,1,1]
	v_pk_fma_f32 v[22:23], v[42:43], v[0:1], v[18:19] op_sel:[1,0,0]
	v_pk_mul_f32 v[4:5], v[8:9], v[44:45] op_sel_hi:[1,0]
	v_pk_mul_f32 v[6:7], v[10:11], v[44:45] op_sel:[0,1]
	v_pk_fma_f32 v[4:5], v[20:21], v[46:47], v[4:5] op_sel_hi:[1,0,1]
	v_pk_fma_f32 v[6:7], v[22:23], v[46:47], v[6:7] op_sel:[0,1,0]
	ds_read_b128 v[28:31], v74 offset:25600
	ds_read_b128 v[32:35], v74 offset:9216
	ds_read_b128 v[36:39], v74 offset:17408
	ds_read_b128 v[40:43], v74 offset:33792
	ds_read_b128 v[44:47], v74 offset:1024
	ds_read_b64 v[48:49], v75 offset:41472
	s_waitcnt lgkmcnt(7)
	v_pk_mul_f32 v[0:1], v[8:9], v[106:107] op_sel_hi:[1,0]
	v_pk_mul_f32 v[2:3], v[10:11], v[106:107] op_sel:[0,1]
	v_pk_fma_f32 v[0:1], v[20:21], v[108:109], v[0:1] op_sel_hi:[1,0,1]
	v_pk_fma_f32 v[2:3], v[22:23], v[108:109], v[2:3] op_sel:[0,1,0]
	v_pk_add_f32 v[4:5], v[4:5], v[6:7]
	v_pk_mul_f32 v[12:13], v[8:9], v[110:111] op_sel_hi:[1,0]
	v_pk_add_f32 v[0:1], v[0:1], v[2:3]
	v_pk_mul_f32 v[14:15], v[10:11], v[110:111] op_sel:[0,1]
	v_cndmask_b32_e32 v24, v4, v5, vcc
	v_cndmask_b32_e32 v25, v5, v4, vcc
	v_pk_mul_f32 v[16:17], v[20:21], v[112:113] op_sel_hi:[1,0]
	v_pk_mul_f32 v[18:19], v[22:23], v[112:113] op_sel:[0,1]
	v_add_f32_dpp v0, v0, v0 quad_perm:[1,0,3,2] row_mask:0xf bank_mask:0xf bound_ctrl:1
	v_add_f32_dpp v1, v1, v1 quad_perm:[1,0,3,2] row_mask:0xf bank_mask:0xf bound_ctrl:1
	v_add_f32_dpp v26, v25, v24 quad_perm:[1,0,3,2] row_mask:0xf bank_mask:0xf bound_ctrl:1
	v_pk_fma_f32 v[12:13], v[114:115], v[126:127], v[12:13] op_sel_hi:[0,1,1]
	v_pk_fma_f32 v[14:15], v[114:115], v[126:127], v[14:15] op_sel:[1,0,0]
	v_add_f32_dpp v0, v0, v0 quad_perm:[2,3,0,1] row_mask:0xf bank_mask:0xf bound_ctrl:1
	v_add_f32_dpp v1, v1, v1 quad_perm:[2,3,0,1] row_mask:0xf bank_mask:0xf bound_ctrl:1
	v_add_f32_dpp v26, v26, v26 quad_perm:[2,3,0,1] row_mask:0xf bank_mask:0xf bound_ctrl:1
	v_pk_fma_f32 v[16:17], v[116:117], v[126:127], v[16:17] op_sel_hi:[0,1,1]
	v_pk_fma_f32 v[18:19], v[116:117], v[126:127], v[18:19] op_sel:[1,0,0]
	v_add_f32_dpp v0, v0, v0 row_half_mirror row_mask:0xf bank_mask:0xf bound_ctrl:1
	v_add_f32_dpp v1, v1, v1 row_half_mirror row_mask:0xf bank_mask:0xf bound_ctrl:1
	v_add_f32_dpp v26, v26, v26 row_ror:4 row_mask:0xf bank_mask:0xf bound_ctrl:1
	s_nop 0
	v_add_f32_dpp v0, v0, v0 row_mirror row_mask:0xf bank_mask:0xf bound_ctrl:1
	v_add_f32_dpp v1, v1, v1 row_mirror row_mask:0xf bank_mask:0xf bound_ctrl:1
	v_add_f32_dpp v26, v26, v26 row_ror:8 row_mask:0xf bank_mask:0xf bound_ctrl:1
	ds_write_b32 v76, v26 offset:256
	v_pk_fma_f32 v[8:9], v[118:119], v[0:1], v[12:13] op_sel_hi:[0,1,1]
	v_pk_fma_f32 v[10:11], v[118:119], v[0:1], v[14:15] op_sel:[1,0,0]
	v_pk_fma_f32 v[20:21], v[120:121], v[0:1], v[16:17] op_sel_hi:[0,1,1]
	v_pk_fma_f32 v[22:23], v[120:121], v[0:1], v[18:19] op_sel:[1,0,0]
	v_pk_mul_f32 v[4:5], v[8:9], v[122:123] op_sel_hi:[1,0]
	v_pk_mul_f32 v[6:7], v[10:11], v[122:123] op_sel:[0,1]
	v_pk_fma_f32 v[4:5], v[20:21], v[124:125], v[4:5] op_sel_hi:[1,0,1]
	v_pk_fma_f32 v[6:7], v[22:23], v[124:125], v[6:7] op_sel:[0,1,0]
	ds_read_b128 v[106:109], v74 offset:25856
	ds_read_b128 v[110:113], v74 offset:9472
	ds_read_b128 v[114:117], v74 offset:17664
	ds_read_b128 v[118:121], v74 offset:34048
	ds_read_b128 v[122:125], v74 offset:1280
	ds_read_b64 v[126:127], v75 offset:41600
	s_waitcnt lgkmcnt(7)
; __device__ __forceinline__ void rwkv_scan_phase(Frame& F, const bf16* RKV, const float* WAG, const bf16* AGB, const float* k_k, const float* k_a, const float* r_k, bf16* Y, float* BS, float* ST2) {
;     ...
;                 f32x2 r0[4], w0[4], k0[4], a0[4], b0[4], r1[4], w1[4], k1[4], a1[4], b1[4]; float v0, v1;
;                 SC_LOAD(r0, w0, k0, a0, b0, v0, 0);
; #pragma unroll
;                 for (int t = 0; t < SC_T; t += 2) {
;                     SC_LOAD(r1, w1, k1, a1, b1, v1, t + 1);
;                     SC_STEP(r0, w0, k0, a0, b0, v0, t);
;                     if (t + 2 < SC_T) SC_LOAD(r0, w0, k0, a0, b0, v0, t + 2);
;                     SC_STEP(r1, w1, k1, a1, b1, v1, t + 1);
	v_pk_mul_f32 v[0:1], v[8:9], v[28:29] op_sel_hi:[1,0]
	v_pk_mul_f32 v[2:3], v[10:11], v[28:29] op_sel:[0,1]
	v_pk_fma_f32 v[0:1], v[20:21], v[30:31], v[0:1] op_sel_hi:[1,0,1]
	v_pk_fma_f32 v[2:3], v[22:23], v[30:31], v[2:3] op_sel:[0,1,0]
	v_pk_add_f32 v[4:5], v[4:5], v[6:7]
	v_pk_mul_f32 v[12:13], v[8:9], v[32:33] op_sel_hi:[1,0]
	v_pk_add_f32 v[0:1], v[0:1], v[2:3]
	v_pk_mul_f32 v[14:15], v[10:11], v[32:33] op_sel:[0,1]
	v_cndmask_b32_e32 v24, v4, v5, vcc
	v_cndmask_b32_e32 v25, v5, v4, vcc
	v_pk_mul_f32 v[16:17], v[20:21], v[34:35] op_sel_hi:[1,0]
	v_pk_mul_f32 v[18:19], v[22:23], v[34:35] op_sel:[0,1]
	v_add_f32_dpp v0, v0, v0 quad_perm:[1,0,3,2] row_mask:0xf bank_mask:0xf bound_ctrl:1
	v_add_f32_dpp v1, v1, v1 quad_perm:[1,0,3,2] row_mask:0xf bank_mask:0xf bound_ctrl:1
	v_add_f32_dpp v26, v25, v24 quad_perm:[1,0,3,2] row_mask:0xf bank_mask:0xf bound_ctrl:1
	v_pk_fma_f32 v[12:13], v[36:37], v[48:49], v[12:13] op_sel_hi:[0,1,1]
	v_pk_fma_f32 v[14:15], v[36:37], v[48:49], v[14:15] op_sel:[1,0,0]
	v_add_f32_dpp v0, v0, v0 quad_perm:[2,3,0,1] row_mask:0xf bank_mask:0xf bound_ctrl:1
	v_add_f32_dpp v1, v1, v1 quad_perm:[2,3,0,1] row_mask:0xf bank_mask:0xf bound_ctrl:1
	v_add_f32_dpp v26, v26, v26 quad_perm:[2,3,0,1] row_mask:0xf bank_mask:0xf bound_ctrl:1
	v_pk_fma_f32 v[16:17], v[38:39], v[48:49], v[16:17] op_sel_hi:[0,1,1]
	v_pk_fma_f32 v[18:19], v[38:39], v[48:49], v[18:19] op_sel:[1,0,0]
	v_add_f32_dpp v0, v0, v0 row_half_mirror row_mask:0xf bank_mask:0xf bound_ctrl:1
	v_add_f32_dpp v1, v1, v1 row_half_mirror row_mask:0xf bank_mask:0xf bound_ctrl:1
	v_add_f32_dpp v26, v26, v26 row_ror:4 row_mask:0xf bank_mask:0xf bound_ctrl:1
	s_nop 0
	v_add_f32_dpp v0, v0, v0 row_mirror row_mask:0xf bank_mask:0xf bound_ctrl:1
	v_add_f32_dpp v1, v1, v1 row_mirror row_mask:0xf bank_mask:0xf bound_ctrl:1
	v_add_f32_dpp v26, v26, v26 row_ror:8 row_mask:0xf bank_mask:0xf bound_ctrl:1
	ds_write_b32 v76, v26 offset:384
	v_pk_fma_f32 v[8:9], v[40:41], v[0:1], v[12:13] op_sel_hi:[0,1,1]
	v_pk_fma_f32 v[10:11], v[40:41], v[0:1], v[14:15] op_sel:[1,0,0]
	v_pk_fma_f32 v[20:21], v[42:43], v[0:1], v[16:17] op_sel_hi:[0,1,1]
	v_pk_fma_f32 v[22:23], v[42:43], v[0:1], v[18:19] op_sel:[1,0,0]
	v_pk_mul_f32 v[4:5], v[8:9], v[44:45] op_sel_hi:[1,0]
	v_pk_mul_f32 v[6:7], v[10:11], v[44:45] op_sel:[0,1]
	v_pk_fma_f32 v[4:5], v[20:21], v[46:47], v[4:5] op_sel_hi:[1,0,1]
	v_pk_fma_f32 v[6:7], v[22:23], v[46:47], v[6:7] op_sel:[0,1,0]
	ds_read_b128 v[28:31], v74 offset:26112
	ds_read_b128 v[32:35], v74 offset:9728
	ds_read_b128 v[36:39], v74 offset:17920
	ds_read_b128 v[40:43], v74 offset:34304
	ds_read_b128 v[44:47], v74 offset:1536
	ds_read_b64 v[48:49], v75 offset:41728
	s_waitcnt lgkmcnt(7)
	v_pk_mul_f32 v[0:1], v[8:9], v[106:107] op_sel_hi:[1,0]
	v_pk_mul_f32 v[2:3], v[10:11], v[106:107] op_sel:[0,1]
	v_pk_fma_f32 v[0:1], v[20:21], v[108:109], v[0:1] op_sel_hi:[1,0,1]
	v_pk_fma_f32 v[2:3], v[22:23], v[108:109], v[2:3] op_sel:[0,1,0]
	v_pk_add_f32 v[4:5], v[4:5], v[6:7]
	v_pk_mul_f32 v[12:13], v[8:9], v[110:111] op_sel_hi:[1,0]
	v_pk_add_f32 v[0:1], v[0:1], v[2:3]
	v_pk_mul_f32 v[14:15], v[10:11], v[110:111] op_sel:[0,1]
	v_cndmask_b32_e32 v24, v4, v5, vcc
	v_cndmask_b32_e32 v25, v5, v4, vcc
	v_pk_mul_f32 v[16:17], v[20:21], v[112:113] op_sel_hi:[1,0]
	v_pk_mul_f32 v[18:19], v[22:23], v[112:113] op_sel:[0,1]
	v_add_f32_dpp v0, v0, v0 quad_perm:[1,0,3,2] row_mask:0xf bank_mask:0xf bound_ctrl:1
	v_add_f32_dpp v1, v1, v1 quad_perm:[1,0,3,2] row_mask:0xf bank_mask:0xf bound_ctrl:1
	v_add_f32_dpp v26, v25, v24 quad_perm:[1,0,3,2] row_mask:0xf bank_mask:0xf bound_ctrl:1
	v_pk_fma_f32 v[12:13], v[114:115], v[126:127], v[12:13] op_sel_hi:[0,1,1]
	v_pk_fma_f32 v[14:15], v[114:115], v[126:127], v[14:15] op_sel:[1,0,0]
	v_add_f32_dpp v0, v0, v0 quad_perm:[2,3,0,1] row_mask:0xf bank_mask:0xf bound_ctrl:1
	v_add_f32_dpp v1, v1, v1 quad_perm:[2,3,0,1] row_mask:0xf bank_mask:0xf bound_ctrl:1
	v_add_f32_dpp v26, v26, v26 quad_perm:[2,3,0,1] row_mask:0xf bank_mask:0xf bound_ctrl:1
	v_pk_fma_f32 v[16:17], v[116:117], v[126:127], v[16:17] op_sel_hi:[0,1,1]
	v_pk_fma_f32 v[18:19], v[116:117], v[126:127], v[18:19] op_sel:[1,0,0]
	v_add_f32_dpp v0, v0, v0 row_half_mirror row_mask:0xf bank_mask:0xf bound_ctrl:1
	v_add_f32_dpp v1, v1, v1 row_half_mirror row_mask:0xf bank_mask:0xf bound_ctrl:1
	v_add_f32_dpp v26, v26, v26 row_ror:4 row_mask:0xf bank_mask:0xf bound_ctrl:1
	s_nop 0
	v_add_f32_dpp v0, v0, v0 row_mirror row_mask:0xf bank_mask:0xf bound_ctrl:1
	v_add_f32_dpp v1, v1, v1 row_mirror row_mask:0xf bank_mask:0xf bound_ctrl:1
	v_add_f32_dpp v26, v26, v26 row_ror:8 row_mask:0xf bank_mask:0xf bound_ctrl:1
	ds_write_b32 v76, v26 offset:512
	v_pk_fma_f32 v[8:9], v[118:119], v[0:1], v[12:13] op_sel_hi:[0,1,1]
	v_pk_fma_f32 v[10:11], v[118:119], v[0:1], v[14:15] op_sel:[1,0,0]
	v_pk_fma_f32 v[20:21], v[120:121], v[0:1], v[16:17] op_sel_hi:[0,1,1]
	v_pk_fma_f32 v[22:23], v[120:121], v[0:1], v[18:19] op_sel:[1,0,0]
	v_pk_mul_f32 v[4:5], v[8:9], v[122:123] op_sel_hi:[1,0]
	v_pk_mul_f32 v[6:7], v[10:11], v[122:123] op_sel:[0,1]
	v_pk_fma_f32 v[4:5], v[20:21], v[124:125], v[4:5] op_sel_hi:[1,0,1]
	v_pk_fma_f32 v[6:7], v[22:23], v[124:125], v[6:7] op_sel:[0,1,0]
	ds_read_b128 v[106:109], v74 offset:26368
	ds_read_b128 v[110:113], v74 offset:9984
	ds_read_b128 v[114:117], v74 offset:18176
	ds_read_b128 v[118:121], v74 offset:34560
	ds_read_b128 v[122:125], v74 offset:1792
	ds_read_b64 v[126:127], v75 offset:41856
	s_waitcnt lgkmcnt(7)
; __device__ __forceinline__ void rwkv_scan_phase(Frame& F, const bf16* RKV, const float* WAG, const bf16* AGB, const float* k_k, const float* k_a, const float* r_k, bf16* Y, float* BS, float* ST2) {
;     ...
;                 f32x2 r0[4], w0[4], k0[4], a0[4], b0[4], r1[4], w1[4], k1[4], a1[4], b1[4]; float v0, v1;
;                 SC_LOAD(r0, w0, k0, a0, b0, v0, 0);
; #pragma unroll
;                 for (int t = 0; t < SC_T; t += 2) {
;                     SC_LOAD(r1, w1, k1, a1, b1, v1, t + 1);
;                     SC_STEP(r0, w0, k0, a0, b0, v0, t);
;                     if (t + 2 < SC_T) SC_LOAD(r0, w0, k0, a0, b0, v0, t + 2);
;                     SC_STEP(r1, w1, k1, a1, b1, v1, t + 1);
	v_pk_mul_f32 v[0:1], v[8:9], v[28:29] op_sel_hi:[1,0]
	v_pk_mul_f32 v[2:3], v[10:11], v[28:29] op_sel:[0,1]
	v_pk_fma_f32 v[0:1], v[20:21], v[30:31], v[0:1] op_sel_hi:[1,0,1]
	v_pk_fma_f32 v[2:3], v[22:23], v[30:31], v[2:3] op_sel:[0,1,0]
	v_pk_add_f32 v[4:5], v[4:5], v[6:7]
	v_pk_mul_f32 v[12:13], v[8:9], v[32:33] op_sel_hi:[1,0]
	v_pk_add_f32 v[0:1], v[0:1], v[2:3]
	v_pk_mul_f32 v[14:15], v[10:11], v[32:33] op_sel:[0,1]
	v_cndmask_b32_e32 v24, v4, v5, vcc
	v_cndmask_b32_e32 v25, v5, v4, vcc
	v_pk_mul_f32 v[16:17], v[20:21], v[34:35] op_sel_hi:[1,0]
	v_pk_mul_f32 v[18:19], v[22:23], v[34:35] op_sel:[0,1]
	v_add_f32_dpp v0, v0, v0 quad_perm:[1,0,3,2] row_mask:0xf bank_mask:0xf bound_ctrl:1
	v_add_f32_dpp v1, v1, v1 quad_perm:[1,0,3,2] row_mask:0xf bank_mask:0xf bound_ctrl:1
	v_add_f32_dpp v26, v25, v24 quad_perm:[1,0,3,2] row_mask:0xf bank_mask:0xf bound_ctrl:1
	v_pk_fma_f32 v[12:13], v[36:37], v[48:49], v[12:13] op_sel_hi:[0,1,1]
	v_pk_fma_f32 v[14:15], v[36:37], v[48:49], v[14:15] op_sel:[1,0,0]
	v_add_f32_dpp v0, v0, v0 quad_perm:[2,3,0,1] row_mask:0xf bank_mask:0xf bound_ctrl:1
	v_add_f32_dpp v1, v1, v1 quad_perm:[2,3,0,1] row_mask:0xf bank_mask:0xf bound_ctrl:1
	v_add_f32_dpp v26, v26, v26 quad_perm:[2,3,0,1] row_mask:0xf bank_mask:0xf bound_ctrl:1
	v_pk_fma_f32 v[16:17], v[38:39], v[48:49], v[16:17] op_sel_hi:[0,1,1]
	v_pk_fma_f32 v[18:19], v[38:39], v[48:49], v[18:19] op_sel:[1,0,0]
	v_add_f32_dpp v0, v0, v0 row_half_mirror row_mask:0xf bank_mask:0xf bound_ctrl:1
	v_add_f32_dpp v1, v1, v1 row_half_mirror row_mask:0xf bank_mask:0xf bound_ctrl:1
	v_add_f32_dpp v26, v26, v26 row_ror:4 row_mask:0xf bank_mask:0xf bound_ctrl:1
	s_nop 0
	v_add_f32_dpp v0, v0, v0 row_mirror row_mask:0xf bank_mask:0xf bound_ctrl:1
	v_add_f32_dpp v1, v1, v1 row_mirror row_mask:0xf bank_mask:0xf bound_ctrl:1
	v_add_f32_dpp v26, v26, v26 row_ror:8 row_mask:0xf bank_mask:0xf bound_ctrl:1
	ds_write_b32 v76, v26 offset:640
	v_pk_fma_f32 v[8:9], v[40:41], v[0:1], v[12:13] op_sel_hi:[0,1,1]
	v_pk_fma_f32 v[10:11], v[40:41], v[0:1], v[14:15] op_sel:[1,0,0]
	v_pk_fma_f32 v[20:21], v[42:43], v[0:1], v[16:17] op_sel_hi:[0,1,1]
	v_pk_fma_f32 v[22:23], v[42:43], v[0:1], v[18:19] op_sel:[1,0,0]
	v_pk_mul_f32 v[4:5], v[8:9], v[44:45] op_sel_hi:[1,0]
	v_pk_mul_f32 v[6:7], v[10:11], v[44:45] op_sel:[0,1]
	v_pk_fma_f32 v[4:5], v[20:21], v[46:47], v[4:5] op_sel_hi:[1,0,1]
	v_pk_fma_f32 v[6:7], v[22:23], v[46:47], v[6:7] op_sel:[0,1,0]
	ds_read_b128 v[28:31], v74 offset:26624
	ds_read_b128 v[32:35], v74 offset:10240
	ds_read_b128 v[36:39], v74 offset:18432
	ds_read_b128 v[40:43], v74 offset:34816
	ds_read_b128 v[44:47], v74 offset:2048
	ds_read_b64 v[48:49], v75 offset:41984
	s_waitcnt lgkmcnt(7)
	v_pk_mul_f32 v[0:1], v[8:9], v[106:107] op_sel_hi:[1,0]
	v_pk_mul_f32 v[2:3], v[10:11], v[106:107] op_sel:[0,1]
	v_pk_fma_f32 v[0:1], v[20:21], v[108:109], v[0:1] op_sel_hi:[1,0,1]
	v_pk_fma_f32 v[2:3], v[22:23], v[108:109], v[2:3] op_sel:[0,1,0]
	v_pk_add_f32 v[4:5], v[4:5], v[6:7]
	v_pk_mul_f32 v[12:13], v[8:9], v[110:111] op_sel_hi:[1,0]
	v_pk_add_f32 v[0:1], v[0:1], v[2:3]
	v_pk_mul_f32 v[14:15], v[10:11], v[110:111] op_sel:[0,1]
	v_cndmask_b32_e32 v24, v4, v5, vcc
	v_cndmask_b32_e32 v25, v5, v4, vcc
	v_pk_mul_f32 v[16:17], v[20:21], v[112:113] op_sel_hi:[1,0]
	v_pk_mul_f32 v[18:19], v[22:23], v[112:113] op_sel:[0,1]
	v_add_f32_dpp v0, v0, v0 quad_perm:[1,0,3,2] row_mask:0xf bank_mask:0xf bound_ctrl:1
	v_add_f32_dpp v1, v1, v1 quad_perm:[1,0,3,2] row_mask:0xf bank_mask:0xf bound_ctrl:1
	v_add_f32_dpp v26, v25, v24 quad_perm:[1,0,3,2] row_mask:0xf bank_mask:0xf bound_ctrl:1
	v_pk_fma_f32 v[12:13], v[114:115], v[126:127], v[12:13] op_sel_hi:[0,1,1]
	v_pk_fma_f32 v[14:15], v[114:115], v[126:127], v[14:15] op_sel:[1,0,0]
	v_add_f32_dpp v0, v0, v0 quad_perm:[2,3,0,1] row_mask:0xf bank_mask:0xf bound_ctrl:1
	v_add_f32_dpp v1, v1, v1 quad_perm:[2,3,0,1] row_mask:0xf bank_mask:0xf bound_ctrl:1
	v_add_f32_dpp v26, v26, v26 quad_perm:[2,3,0,1] row_mask:0xf bank_mask:0xf bound_ctrl:1
	v_pk_fma_f32 v[16:17], v[116:117], v[126:127], v[16:17] op_sel_hi:[0,1,1]
	v_pk_fma_f32 v[18:19], v[116:117], v[126:127], v[18:19] op_sel:[1,0,0]
	v_add_f32_dpp v0, v0, v0 row_half_mirror row_mask:0xf bank_mask:0xf bound_ctrl:1
	v_add_f32_dpp v1, v1, v1 row_half_mirror row_mask:0xf bank_mask:0xf bound_ctrl:1
	v_add_f32_dpp v26, v26, v26 row_ror:4 row_mask:0xf bank_mask:0xf bound_ctrl:1
	s_nop 0
	v_add_f32_dpp v0, v0, v0 row_mirror row_mask:0xf bank_mask:0xf bound_ctrl:1
	v_add_f32_dpp v1, v1, v1 row_mirror row_mask:0xf bank_mask:0xf bound_ctrl:1
	v_add_f32_dpp v26, v26, v26 row_ror:8 row_mask:0xf bank_mask:0xf bound_ctrl:1
	ds_write_b32 v76, v26 offset:768
	v_pk_fma_f32 v[8:9], v[118:119], v[0:1], v[12:13] op_sel_hi:[0,1,1]
	v_pk_fma_f32 v[10:11], v[118:119], v[0:1], v[14:15] op_sel:[1,0,0]
	v_pk_fma_f32 v[20:21], v[120:121], v[0:1], v[16:17] op_sel_hi:[0,1,1]
	v_pk_fma_f32 v[22:23], v[120:121], v[0:1], v[18:19] op_sel:[1,0,0]
	v_pk_mul_f32 v[4:5], v[8:9], v[122:123] op_sel_hi:[1,0]
	v_pk_mul_f32 v[6:7], v[10:11], v[122:123] op_sel:[0,1]
	v_pk_fma_f32 v[4:5], v[20:21], v[124:125], v[4:5] op_sel_hi:[1,0,1]
	v_pk_fma_f32 v[6:7], v[22:23], v[124:125], v[6:7] op_sel:[0,1,0]
	ds_read_b128 v[106:109], v74 offset:26880
	ds_read_b128 v[110:113], v74 offset:10496
	ds_read_b128 v[114:117], v74 offset:18688
	ds_read_b128 v[118:121], v74 offset:35072
	ds_read_b128 v[122:125], v74 offset:2304
	ds_read_b64 v[126:127], v75 offset:42112
	s_waitcnt lgkmcnt(7)
; __device__ __forceinline__ void rwkv_scan_phase(Frame& F, const bf16* RKV, const float* WAG, const bf16* AGB, const float* k_k, const float* k_a, const float* r_k, bf16* Y, float* BS, float* ST2) {
;     ...
;                 f32x2 r0[4], w0[4], k0[4], a0[4], b0[4], r1[4], w1[4], k1[4], a1[4], b1[4]; float v0, v1;
;                 SC_LOAD(r0, w0, k0, a0, b0, v0, 0);
; #pragma unroll
;                 for (int t = 0; t < SC_T; t += 2) {
;                     SC_LOAD(r1, w1, k1, a1, b1, v1, t + 1);
;                     SC_STEP(r0, w0, k0, a0, b0, v0, t);
;                     if (t + 2 < SC_T) SC_LOAD(r0, w0, k0, a0, b0, v0, t + 2);
;                     SC_STEP(r1, w1, k1, a1, b1, v1, t + 1);
	v_pk_mul_f32 v[0:1], v[8:9], v[28:29] op_sel_hi:[1,0]
	v_pk_mul_f32 v[2:3], v[10:11], v[28:29] op_sel:[0,1]
	v_pk_fma_f32 v[0:1], v[20:21], v[30:31], v[0:1] op_sel_hi:[1,0,1]
	v_pk_fma_f32 v[2:3], v[22:23], v[30:31], v[2:3] op_sel:[0,1,0]
	v_pk_add_f32 v[4:5], v[4:5], v[6:7]
	v_pk_mul_f32 v[12:13], v[8:9], v[32:33] op_sel_hi:[1,0]
	v_pk_add_f32 v[0:1], v[0:1], v[2:3]
	v_pk_mul_f32 v[14:15], v[10:11], v[32:33] op_sel:[0,1]
	v_cndmask_b32_e32 v24, v4, v5, vcc
	v_cndmask_b32_e32 v25, v5, v4, vcc
	v_pk_mul_f32 v[16:17], v[20:21], v[34:35] op_sel_hi:[1,0]
	v_pk_mul_f32 v[18:19], v[22:23], v[34:35] op_sel:[0,1]
	v_add_f32_dpp v0, v0, v0 quad_perm:[1,0,3,2] row_mask:0xf bank_mask:0xf bound_ctrl:1
	v_add_f32_dpp v1, v1, v1 quad_perm:[1,0,3,2] row_mask:0xf bank_mask:0xf bound_ctrl:1
	v_add_f32_dpp v26, v25, v24 quad_perm:[1,0,3,2] row_mask:0xf bank_mask:0xf bound_ctrl:1
	v_pk_fma_f32 v[12:13], v[36:37], v[48:49], v[12:13] op_sel_hi:[0,1,1]
	v_pk_fma_f32 v[14:15], v[36:37], v[48:49], v[14:15] op_sel:[1,0,0]
	v_add_f32_dpp v0, v0, v0 quad_perm:[2,3,0,1] row_mask:0xf bank_mask:0xf bound_ctrl:1
	v_add_f32_dpp v1, v1, v1 quad_perm:[2,3,0,1] row_mask:0xf bank_mask:0xf bound_ctrl:1
	v_add_f32_dpp v26, v26, v26 quad_perm:[2,3,0,1] row_mask:0xf bank_mask:0xf bound_ctrl:1
	v_pk_fma_f32 v[16:17], v[38:39], v[48:49], v[16:17] op_sel_hi:[0,1,1]
	v_pk_fma_f32 v[18:19], v[38:39], v[48:49], v[18:19] op_sel:[1,0,0]
	v_add_f32_dpp v0, v0, v0 row_half_mirror row_mask:0xf bank_mask:0xf bound_ctrl:1
	v_add_f32_dpp v1, v1, v1 row_half_mirror row_mask:0xf bank_mask:0xf bound_ctrl:1
	v_add_f32_dpp v26, v26, v26 row_ror:4 row_mask:0xf bank_mask:0xf bound_ctrl:1
	s_nop 0
	v_add_f32_dpp v0, v0, v0 row_mirror row_mask:0xf bank_mask:0xf bound_ctrl:1
	v_add_f32_dpp v1, v1, v1 row_mirror row_mask:0xf bank_mask:0xf bound_ctrl:1
	v_add_f32_dpp v26, v26, v26 row_ror:8 row_mask:0xf bank_mask:0xf bound_ctrl:1
	ds_write_b32 v76, v26 offset:896
	v_pk_fma_f32 v[8:9], v[40:41], v[0:1], v[12:13] op_sel_hi:[0,1,1]
	v_pk_fma_f32 v[10:11], v[40:41], v[0:1], v[14:15] op_sel:[1,0,0]
	v_pk_fma_f32 v[20:21], v[42:43], v[0:1], v[16:17] op_sel_hi:[0,1,1]
	v_pk_fma_f32 v[22:23], v[42:43], v[0:1], v[18:19] op_sel:[1,0,0]
	v_pk_mul_f32 v[4:5], v[8:9], v[44:45] op_sel_hi:[1,0]
	v_pk_mul_f32 v[6:7], v[10:11], v[44:45] op_sel:[0,1]
	v_pk_fma_f32 v[4:5], v[20:21], v[46:47], v[4:5] op_sel_hi:[1,0,1]
	v_pk_fma_f32 v[6:7], v[22:23], v[46:47], v[6:7] op_sel:[0,1,0]
	ds_read_b128 v[28:31], v74 offset:27136
	ds_read_b128 v[32:35], v74 offset:10752
	ds_read_b128 v[36:39], v74 offset:18944
	ds_read_b128 v[40:43], v74 offset:35328
	ds_read_b128 v[44:47], v74 offset:2560
	ds_read_b64 v[48:49], v75 offset:42240
	s_waitcnt lgkmcnt(7)
	v_pk_mul_f32 v[0:1], v[8:9], v[106:107] op_sel_hi:[1,0]
	v_pk_mul_f32 v[2:3], v[10:11], v[106:107] op_sel:[0,1]
	v_pk_fma_f32 v[0:1], v[20:21], v[108:109], v[0:1] op_sel_hi:[1,0,1]
	v_pk_fma_f32 v[2:3], v[22:23], v[108:109], v[2:3] op_sel:[0,1,0]
	v_pk_add_f32 v[4:5], v[4:5], v[6:7]
	v_pk_mul_f32 v[12:13], v[8:9], v[110:111] op_sel_hi:[1,0]
	v_pk_add_f32 v[0:1], v[0:1], v[2:3]
	v_pk_mul_f32 v[14:15], v[10:11], v[110:111] op_sel:[0,1]
	v_cndmask_b32_e32 v24, v4, v5, vcc
	v_cndmask_b32_e32 v25, v5, v4, vcc
	v_pk_mul_f32 v[16:17], v[20:21], v[112:113] op_sel_hi:[1,0]
	v_pk_mul_f32 v[18:19], v[22:23], v[112:113] op_sel:[0,1]
	v_add_f32_dpp v0, v0, v0 quad_perm:[1,0,3,2] row_mask:0xf bank_mask:0xf bound_ctrl:1
	v_add_f32_dpp v1, v1, v1 quad_perm:[1,0,3,2] row_mask:0xf bank_mask:0xf bound_ctrl:1
	v_add_f32_dpp v26, v25, v24 quad_perm:[1,0,3,2] row_mask:0xf bank_mask:0xf bound_ctrl:1
	v_pk_fma_f32 v[12:13], v[114:115], v[126:127], v[12:13] op_sel_hi:[0,1,1]
	v_pk_fma_f32 v[14:15], v[114:115], v[126:127], v[14:15] op_sel:[1,0,0]
	v_add_f32_dpp v0, v0, v0 quad_perm:[2,3,0,1] row_mask:0xf bank_mask:0xf bound_ctrl:1
	v_add_f32_dpp v1, v1, v1 quad_perm:[2,3,0,1] row_mask:0xf bank_mask:0xf bound_ctrl:1
	v_add_f32_dpp v26, v26, v26 quad_perm:[2,3,0,1] row_mask:0xf bank_mask:0xf bound_ctrl:1
	v_pk_fma_f32 v[16:17], v[116:117], v[126:127], v[16:17] op_sel_hi:[0,1,1]
	v_pk_fma_f32 v[18:19], v[116:117], v[126:127], v[18:19] op_sel:[1,0,0]
	v_add_f32_dpp v0, v0, v0 row_half_mirror row_mask:0xf bank_mask:0xf bound_ctrl:1
	v_add_f32_dpp v1, v1, v1 row_half_mirror row_mask:0xf bank_mask:0xf bound_ctrl:1
	v_add_f32_dpp v26, v26, v26 row_ror:4 row_mask:0xf bank_mask:0xf bound_ctrl:1
	s_nop 0
	v_add_f32_dpp v0, v0, v0 row_mirror row_mask:0xf bank_mask:0xf bound_ctrl:1
	v_add_f32_dpp v1, v1, v1 row_mirror row_mask:0xf bank_mask:0xf bound_ctrl:1
	v_add_f32_dpp v26, v26, v26 row_ror:8 row_mask:0xf bank_mask:0xf bound_ctrl:1
	ds_write_b32 v76, v26 offset:1024
	v_pk_fma_f32 v[8:9], v[118:119], v[0:1], v[12:13] op_sel_hi:[0,1,1]
	v_pk_fma_f32 v[10:11], v[118:119], v[0:1], v[14:15] op_sel:[1,0,0]
	v_pk_fma_f32 v[20:21], v[120:121], v[0:1], v[16:17] op_sel_hi:[0,1,1]
	v_pk_fma_f32 v[22:23], v[120:121], v[0:1], v[18:19] op_sel:[1,0,0]
	v_pk_mul_f32 v[4:5], v[8:9], v[122:123] op_sel_hi:[1,0]
	v_pk_mul_f32 v[6:7], v[10:11], v[122:123] op_sel:[0,1]
	v_pk_fma_f32 v[4:5], v[20:21], v[124:125], v[4:5] op_sel_hi:[1,0,1]
	v_pk_fma_f32 v[6:7], v[22:23], v[124:125], v[6:7] op_sel:[0,1,0]
	ds_read_b128 v[106:109], v74 offset:27392
	ds_read_b128 v[110:113], v74 offset:11008
	ds_read_b128 v[114:117], v74 offset:19200
	ds_read_b128 v[118:121], v74 offset:35584
	ds_read_b128 v[122:125], v74 offset:2816
	ds_read_b64 v[126:127], v75 offset:42368
	s_waitcnt lgkmcnt(7)
; __device__ __forceinline__ void rwkv_scan_phase(Frame& F, const bf16* RKV, const float* WAG, const bf16* AGB, const float* k_k, const float* k_a, const float* r_k, bf16* Y, float* BS, float* ST2) {
;     ...
;                 f32x2 r0[4], w0[4], k0[4], a0[4], b0[4], r1[4], w1[4], k1[4], a1[4], b1[4]; float v0, v1;
;                 SC_LOAD(r0, w0, k0, a0, b0, v0, 0);
; #pragma unroll
;                 for (int t = 0; t < SC_T; t += 2) {
;                     SC_LOAD(r1, w1, k1, a1, b1, v1, t + 1);
;                     SC_STEP(r0, w0, k0, a0, b0, v0, t);
;                     if (t + 2 < SC_T) SC_LOAD(r0, w0, k0, a0, b0, v0, t + 2);
;                     SC_STEP(r1, w1, k1, a1, b1, v1, t + 1);
	v_pk_mul_f32 v[0:1], v[8:9], v[28:29] op_sel_hi:[1,0]
	v_pk_mul_f32 v[2:3], v[10:11], v[28:29] op_sel:[0,1]
	v_pk_fma_f32 v[0:1], v[20:21], v[30:31], v[0:1] op_sel_hi:[1,0,1]
	v_pk_fma_f32 v[2:3], v[22:23], v[30:31], v[2:3] op_sel:[0,1,0]
	v_pk_add_f32 v[4:5], v[4:5], v[6:7]
	v_pk_mul_f32 v[12:13], v[8:9], v[32:33] op_sel_hi:[1,0]
	v_pk_add_f32 v[0:1], v[0:1], v[2:3]
	v_pk_mul_f32 v[14:15], v[10:11], v[32:33] op_sel:[0,1]
	v_cndmask_b32_e32 v24, v4, v5, vcc
	v_cndmask_b32_e32 v25, v5, v4, vcc
	v_pk_mul_f32 v[16:17], v[20:21], v[34:35] op_sel_hi:[1,0]
	v_pk_mul_f32 v[18:19], v[22:23], v[34:35] op_sel:[0,1]
	v_add_f32_dpp v0, v0, v0 quad_perm:[1,0,3,2] row_mask:0xf bank_mask:0xf bound_ctrl:1
	v_add_f32_dpp v1, v1, v1 quad_perm:[1,0,3,2] row_mask:0xf bank_mask:0xf bound_ctrl:1
	v_add_f32_dpp v26, v25, v24 quad_perm:[1,0,3,2] row_mask:0xf bank_mask:0xf bound_ctrl:1
	v_pk_fma_f32 v[12:13], v[36:37], v[48:49], v[12:13] op_sel_hi:[0,1,1]
	v_pk_fma_f32 v[14:15], v[36:37], v[48:49], v[14:15] op_sel:[1,0,0]
	v_add_f32_dpp v0, v0, v0 quad_perm:[2,3,0,1] row_mask:0xf bank_mask:0xf bound_ctrl:1
	v_add_f32_dpp v1, v1, v1 quad_perm:[2,3,0,1] row_mask:0xf bank_mask:0xf bound_ctrl:1
	v_add_f32_dpp v26, v26, v26 quad_perm:[2,3,0,1] row_mask:0xf bank_mask:0xf bound_ctrl:1
	v_pk_fma_f32 v[16:17], v[38:39], v[48:49], v[16:17] op_sel_hi:[0,1,1]
	v_pk_fma_f32 v[18:19], v[38:39], v[48:49], v[18:19] op_sel:[1,0,0]
	v_add_f32_dpp v0, v0, v0 row_half_mirror row_mask:0xf bank_mask:0xf bound_ctrl:1
	v_add_f32_dpp v1, v1, v1 row_half_mirror row_mask:0xf bank_mask:0xf bound_ctrl:1
	v_add_f32_dpp v26, v26, v26 row_ror:4 row_mask:0xf bank_mask:0xf bound_ctrl:1
	s_nop 0
	v_add_f32_dpp v0, v0, v0 row_mirror row_mask:0xf bank_mask:0xf bound_ctrl:1
	v_add_f32_dpp v1, v1, v1 row_mirror row_mask:0xf bank_mask:0xf bound_ctrl:1
	v_add_f32_dpp v26, v26, v26 row_ror:8 row_mask:0xf bank_mask:0xf bound_ctrl:1
	ds_write_b32 v76, v26 offset:1152
	v_pk_fma_f32 v[8:9], v[40:41], v[0:1], v[12:13] op_sel_hi:[0,1,1]
	v_pk_fma_f32 v[10:11], v[40:41], v[0:1], v[14:15] op_sel:[1,0,0]
	v_pk_fma_f32 v[20:21], v[42:43], v[0:1], v[16:17] op_sel_hi:[0,1,1]
	v_pk_fma_f32 v[22:23], v[42:43], v[0:1], v[18:19] op_sel:[1,0,0]
	v_pk_mul_f32 v[4:5], v[8:9], v[44:45] op_sel_hi:[1,0]
	v_pk_mul_f32 v[6:7], v[10:11], v[44:45] op_sel:[0,1]
	v_pk_fma_f32 v[4:5], v[20:21], v[46:47], v[4:5] op_sel_hi:[1,0,1]
	v_pk_fma_f32 v[6:7], v[22:23], v[46:47], v[6:7] op_sel:[0,1,0]
	ds_read_b128 v[28:31], v74 offset:27648
	ds_read_b128 v[32:35], v74 offset:11264
	ds_read_b128 v[36:39], v74 offset:19456
	ds_read_b128 v[40:43], v74 offset:35840
	ds_read_b128 v[44:47], v74 offset:3072
	ds_read_b64 v[48:49], v75 offset:42496
	s_waitcnt lgkmcnt(7)
	v_pk_mul_f32 v[0:1], v[8:9], v[106:107] op_sel_hi:[1,0]
	v_pk_mul_f32 v[2:3], v[10:11], v[106:107] op_sel:[0,1]
	v_pk_fma_f32 v[0:1], v[20:21], v[108:109], v[0:1] op_sel_hi:[1,0,1]
	v_pk_fma_f32 v[2:3], v[22:23], v[108:109], v[2:3] op_sel:[0,1,0]
	v_pk_add_f32 v[4:5], v[4:5], v[6:7]
	v_pk_mul_f32 v[12:13], v[8:9], v[110:111] op_sel_hi:[1,0]
	v_pk_add_f32 v[0:1], v[0:1], v[2:3]
	v_pk_mul_f32 v[14:15], v[10:11], v[110:111] op_sel:[0,1]
	v_cndmask_b32_e32 v24, v4, v5, vcc
	v_cndmask_b32_e32 v25, v5, v4, vcc
	v_pk_mul_f32 v[16:17], v[20:21], v[112:113] op_sel_hi:[1,0]
	v_pk_mul_f32 v[18:19], v[22:23], v[112:113] op_sel:[0,1]
	v_add_f32_dpp v0, v0, v0 quad_perm:[1,0,3,2] row_mask:0xf bank_mask:0xf bound_ctrl:1
	v_add_f32_dpp v1, v1, v1 quad_perm:[1,0,3,2] row_mask:0xf bank_mask:0xf bound_ctrl:1
	v_add_f32_dpp v26, v25, v24 quad_perm:[1,0,3,2] row_mask:0xf bank_mask:0xf bound_ctrl:1
	v_pk_fma_f32 v[12:13], v[114:115], v[126:127], v[12:13] op_sel_hi:[0,1,1]
	v_pk_fma_f32 v[14:15], v[114:115], v[126:127], v[14:15] op_sel:[1,0,0]
	v_add_f32_dpp v0, v0, v0 quad_perm:[2,3,0,1] row_mask:0xf bank_mask:0xf bound_ctrl:1
	v_add_f32_dpp v1, v1, v1 quad_perm:[2,3,0,1] row_mask:0xf bank_mask:0xf bound_ctrl:1
	v_add_f32_dpp v26, v26, v26 quad_perm:[2,3,0,1] row_mask:0xf bank_mask:0xf bound_ctrl:1
	v_pk_fma_f32 v[16:17], v[116:117], v[126:127], v[16:17] op_sel_hi:[0,1,1]
	v_pk_fma_f32 v[18:19], v[116:117], v[126:127], v[18:19] op_sel:[1,0,0]
	v_add_f32_dpp v0, v0, v0 row_half_mirror row_mask:0xf bank_mask:0xf bound_ctrl:1
	v_add_f32_dpp v1, v1, v1 row_half_mirror row_mask:0xf bank_mask:0xf bound_ctrl:1
	v_add_f32_dpp v26, v26, v26 row_ror:4 row_mask:0xf bank_mask:0xf bound_ctrl:1
	s_nop 0
	v_add_f32_dpp v0, v0, v0 row_mirror row_mask:0xf bank_mask:0xf bound_ctrl:1
	v_add_f32_dpp v1, v1, v1 row_mirror row_mask:0xf bank_mask:0xf bound_ctrl:1
	v_add_f32_dpp v26, v26, v26 row_ror:8 row_mask:0xf bank_mask:0xf bound_ctrl:1
	ds_write_b32 v76, v26 offset:1280
	v_pk_fma_f32 v[8:9], v[118:119], v[0:1], v[12:13] op_sel_hi:[0,1,1]
	v_pk_fma_f32 v[10:11], v[118:119], v[0:1], v[14:15] op_sel:[1,0,0]
	v_pk_fma_f32 v[20:21], v[120:121], v[0:1], v[16:17] op_sel_hi:[0,1,1]
	v_pk_fma_f32 v[22:23], v[120:121], v[0:1], v[18:19] op_sel:[1,0,0]
	v_pk_mul_f32 v[4:5], v[8:9], v[122:123] op_sel_hi:[1,0]
	v_pk_mul_f32 v[6:7], v[10:11], v[122:123] op_sel:[0,1]
	v_pk_fma_f32 v[4:5], v[20:21], v[124:125], v[4:5] op_sel_hi:[1,0,1]
	v_pk_fma_f32 v[6:7], v[22:23], v[124:125], v[6:7] op_sel:[0,1,0]
	ds_read_b128 v[106:109], v74 offset:27904
	ds_read_b128 v[110:113], v74 offset:11520
	ds_read_b128 v[114:117], v74 offset:19712
	ds_read_b128 v[118:121], v74 offset:36096
	ds_read_b128 v[122:125], v74 offset:3328
	ds_read_b64 v[126:127], v75 offset:42624
	s_waitcnt lgkmcnt(7)
; __device__ __forceinline__ void rwkv_scan_phase(Frame& F, const bf16* RKV, const float* WAG, const bf16* AGB, const float* k_k, const float* k_a, const float* r_k, bf16* Y, float* BS, float* ST2) {
;     ...
;                 f32x2 r0[4], w0[4], k0[4], a0[4], b0[4], r1[4], w1[4], k1[4], a1[4], b1[4]; float v0, v1;
;                 SC_LOAD(r0, w0, k0, a0, b0, v0, 0);
; #pragma unroll
;                 for (int t = 0; t < SC_T; t += 2) {
;                     SC_LOAD(r1, w1, k1, a1, b1, v1, t + 1);
;                     SC_STEP(r0, w0, k0, a0, b0, v0, t);
;                     if (t + 2 < SC_T) SC_LOAD(r0, w0, k0, a0, b0, v0, t + 2);
;                     SC_STEP(r1, w1, k1, a1, b1, v1, t + 1);
	v_pk_mul_f32 v[0:1], v[8:9], v[28:29] op_sel_hi:[1,0]
	v_pk_mul_f32 v[2:3], v[10:11], v[28:29] op_sel:[0,1]
	v_pk_fma_f32 v[0:1], v[20:21], v[30:31], v[0:1] op_sel_hi:[1,0,1]
	v_pk_fma_f32 v[2:3], v[22:23], v[30:31], v[2:3] op_sel:[0,1,0]
	v_pk_add_f32 v[4:5], v[4:5], v[6:7]
	v_pk_mul_f32 v[12:13], v[8:9], v[32:33] op_sel_hi:[1,0]
	v_pk_add_f32 v[0:1], v[0:1], v[2:3]
	v_pk_mul_f32 v[14:15], v[10:11], v[32:33] op_sel:[0,1]
	v_cndmask_b32_e32 v24, v4, v5, vcc
	v_cndmask_b32_e32 v25, v5, v4, vcc
	v_pk_mul_f32 v[16:17], v[20:21], v[34:35] op_sel_hi:[1,0]
	v_pk_mul_f32 v[18:19], v[22:23], v[34:35] op_sel:[0,1]
	v_add_f32_dpp v0, v0, v0 quad_perm:[1,0,3,2] row_mask:0xf bank_mask:0xf bound_ctrl:1
	v_add_f32_dpp v1, v1, v1 quad_perm:[1,0,3,2] row_mask:0xf bank_mask:0xf bound_ctrl:1
	v_add_f32_dpp v26, v25, v24 quad_perm:[1,0,3,2] row_mask:0xf bank_mask:0xf bound_ctrl:1
	v_pk_fma_f32 v[12:13], v[36:37], v[48:49], v[12:13] op_sel_hi:[0,1,1]
	v_pk_fma_f32 v[14:15], v[36:37], v[48:49], v[14:15] op_sel:[1,0,0]
	v_add_f32_dpp v0, v0, v0 quad_perm:[2,3,0,1] row_mask:0xf bank_mask:0xf bound_ctrl:1
	v_add_f32_dpp v1, v1, v1 quad_perm:[2,3,0,1] row_mask:0xf bank_mask:0xf bound_ctrl:1
	v_add_f32_dpp v26, v26, v26 quad_perm:[2,3,0,1] row_mask:0xf bank_mask:0xf bound_ctrl:1
	v_pk_fma_f32 v[16:17], v[38:39], v[48:49], v[16:17] op_sel_hi:[0,1,1]
	v_pk_fma_f32 v[18:19], v[38:39], v[48:49], v[18:19] op_sel:[1,0,0]
	v_add_f32_dpp v0, v0, v0 row_half_mirror row_mask:0xf bank_mask:0xf bound_ctrl:1
	v_add_f32_dpp v1, v1, v1 row_half_mirror row_mask:0xf bank_mask:0xf bound_ctrl:1
	v_add_f32_dpp v26, v26, v26 row_ror:4 row_mask:0xf bank_mask:0xf bound_ctrl:1
	s_nop 0
	v_add_f32_dpp v0, v0, v0 row_mirror row_mask:0xf bank_mask:0xf bound_ctrl:1
	v_add_f32_dpp v1, v1, v1 row_mirror row_mask:0xf bank_mask:0xf bound_ctrl:1
	v_add_f32_dpp v26, v26, v26 row_ror:8 row_mask:0xf bank_mask:0xf bound_ctrl:1
	ds_write_b32 v76, v26 offset:1408
	v_pk_fma_f32 v[8:9], v[40:41], v[0:1], v[12:13] op_sel_hi:[0,1,1]
	v_pk_fma_f32 v[10:11], v[40:41], v[0:1], v[14:15] op_sel:[1,0,0]
	v_pk_fma_f32 v[20:21], v[42:43], v[0:1], v[16:17] op_sel_hi:[0,1,1]
	v_pk_fma_f32 v[22:23], v[42:43], v[0:1], v[18:19] op_sel:[1,0,0]
	v_pk_mul_f32 v[4:5], v[8:9], v[44:45] op_sel_hi:[1,0]
	v_pk_mul_f32 v[6:7], v[10:11], v[44:45] op_sel:[0,1]
	v_pk_fma_f32 v[4:5], v[20:21], v[46:47], v[4:5] op_sel_hi:[1,0,1]
	v_pk_fma_f32 v[6:7], v[22:23], v[46:47], v[6:7] op_sel:[0,1,0]
	ds_read_b128 v[28:31], v74 offset:28160
	ds_read_b128 v[32:35], v74 offset:11776
	ds_read_b128 v[36:39], v74 offset:19968
	ds_read_b128 v[40:43], v74 offset:36352
	ds_read_b128 v[44:47], v74 offset:3584
	ds_read_b64 v[48:49], v75 offset:42752
	s_waitcnt lgkmcnt(7)
	v_pk_mul_f32 v[0:1], v[8:9], v[106:107] op_sel_hi:[1,0]
	v_pk_mul_f32 v[2:3], v[10:11], v[106:107] op_sel:[0,1]
	v_pk_fma_f32 v[0:1], v[20:21], v[108:109], v[0:1] op_sel_hi:[1,0,1]
	v_pk_fma_f32 v[2:3], v[22:23], v[108:109], v[2:3] op_sel:[0,1,0]
	v_pk_add_f32 v[4:5], v[4:5], v[6:7]
	v_pk_mul_f32 v[12:13], v[8:9], v[110:111] op_sel_hi:[1,0]
	v_pk_add_f32 v[0:1], v[0:1], v[2:3]
	v_pk_mul_f32 v[14:15], v[10:11], v[110:111] op_sel:[0,1]
	v_cndmask_b32_e32 v24, v4, v5, vcc
	v_cndmask_b32_e32 v25, v5, v4, vcc
	v_pk_mul_f32 v[16:17], v[20:21], v[112:113] op_sel_hi:[1,0]
	v_pk_mul_f32 v[18:19], v[22:23], v[112:113] op_sel:[0,1]
	v_add_f32_dpp v0, v0, v0 quad_perm:[1,0,3,2] row_mask:0xf bank_mask:0xf bound_ctrl:1
	v_add_f32_dpp v1, v1, v1 quad_perm:[1,0,3,2] row_mask:0xf bank_mask:0xf bound_ctrl:1
	v_add_f32_dpp v26, v25, v24 quad_perm:[1,0,3,2] row_mask:0xf bank_mask:0xf bound_ctrl:1
	v_pk_fma_f32 v[12:13], v[114:115], v[126:127], v[12:13] op_sel_hi:[0,1,1]
	v_pk_fma_f32 v[14:15], v[114:115], v[126:127], v[14:15] op_sel:[1,0,0]
	v_add_f32_dpp v0, v0, v0 quad_perm:[2,3,0,1] row_mask:0xf bank_mask:0xf bound_ctrl:1
	v_add_f32_dpp v1, v1, v1 quad_perm:[2,3,0,1] row_mask:0xf bank_mask:0xf bound_ctrl:1
	v_add_f32_dpp v26, v26, v26 quad_perm:[2,3,0,1] row_mask:0xf bank_mask:0xf bound_ctrl:1
	v_pk_fma_f32 v[16:17], v[116:117], v[126:127], v[16:17] op_sel_hi:[0,1,1]
	v_pk_fma_f32 v[18:19], v[116:117], v[126:127], v[18:19] op_sel:[1,0,0]
	v_add_f32_dpp v0, v0, v0 row_half_mirror row_mask:0xf bank_mask:0xf bound_ctrl:1
	v_add_f32_dpp v1, v1, v1 row_half_mirror row_mask:0xf bank_mask:0xf bound_ctrl:1
	v_add_f32_dpp v26, v26, v26 row_ror:4 row_mask:0xf bank_mask:0xf bound_ctrl:1
	s_nop 0
	v_add_f32_dpp v0, v0, v0 row_mirror row_mask:0xf bank_mask:0xf bound_ctrl:1
	v_add_f32_dpp v1, v1, v1 row_mirror row_mask:0xf bank_mask:0xf bound_ctrl:1
	v_add_f32_dpp v26, v26, v26 row_ror:8 row_mask:0xf bank_mask:0xf bound_ctrl:1
	ds_write_b32 v76, v26 offset:1536
	v_pk_fma_f32 v[8:9], v[118:119], v[0:1], v[12:13] op_sel_hi:[0,1,1]
	v_pk_fma_f32 v[10:11], v[118:119], v[0:1], v[14:15] op_sel:[1,0,0]
	v_pk_fma_f32 v[20:21], v[120:121], v[0:1], v[16:17] op_sel_hi:[0,1,1]
	v_pk_fma_f32 v[22:23], v[120:121], v[0:1], v[18:19] op_sel:[1,0,0]
	v_pk_mul_f32 v[4:5], v[8:9], v[122:123] op_sel_hi:[1,0]
	v_pk_mul_f32 v[6:7], v[10:11], v[122:123] op_sel:[0,1]
	v_pk_fma_f32 v[4:5], v[20:21], v[124:125], v[4:5] op_sel_hi:[1,0,1]
	v_pk_fma_f32 v[6:7], v[22:23], v[124:125], v[6:7] op_sel:[0,1,0]
	ds_read_b128 v[106:109], v74 offset:28416
	ds_read_b128 v[110:113], v74 offset:12032
	ds_read_b128 v[114:117], v74 offset:20224
	ds_read_b128 v[118:121], v74 offset:36608
	ds_read_b128 v[122:125], v74 offset:3840
	ds_read_b64 v[126:127], v75 offset:42880
	s_waitcnt lgkmcnt(7)
; __device__ __forceinline__ void rwkv_scan_phase(Frame& F, const bf16* RKV, const float* WAG, const bf16* AGB, const float* k_k, const float* k_a, const float* r_k, bf16* Y, float* BS, float* ST2) {
;     ...
;                 f32x2 r0[4], w0[4], k0[4], a0[4], b0[4], r1[4], w1[4], k1[4], a1[4], b1[4]; float v0, v1;
;                 SC_LOAD(r0, w0, k0, a0, b0, v0, 0);
; #pragma unroll
;                 for (int t = 0; t < SC_T; t += 2) {
;                     SC_LOAD(r1, w1, k1, a1, b1, v1, t + 1);
;                     SC_STEP(r0, w0, k0, a0, b0, v0, t);
;                     if (t + 2 < SC_T) SC_LOAD(r0, w0, k0, a0, b0, v0, t + 2);
;                     SC_STEP(r1, w1, k1, a1, b1, v1, t + 1);
	v_pk_mul_f32 v[0:1], v[8:9], v[28:29] op_sel_hi:[1,0]
	v_pk_mul_f32 v[2:3], v[10:11], v[28:29] op_sel:[0,1]
	v_pk_fma_f32 v[0:1], v[20:21], v[30:31], v[0:1] op_sel_hi:[1,0,1]
	v_pk_fma_f32 v[2:3], v[22:23], v[30:31], v[2:3] op_sel:[0,1,0]
	v_pk_add_f32 v[4:5], v[4:5], v[6:7]
	v_pk_mul_f32 v[12:13], v[8:9], v[32:33] op_sel_hi:[1,0]
	v_pk_add_f32 v[0:1], v[0:1], v[2:3]
	v_pk_mul_f32 v[14:15], v[10:11], v[32:33] op_sel:[0,1]
	v_cndmask_b32_e32 v24, v4, v5, vcc
	v_cndmask_b32_e32 v25, v5, v4, vcc
	v_pk_mul_f32 v[16:17], v[20:21], v[34:35] op_sel_hi:[1,0]
	v_pk_mul_f32 v[18:19], v[22:23], v[34:35] op_sel:[0,1]
	v_add_f32_dpp v0, v0, v0 quad_perm:[1,0,3,2] row_mask:0xf bank_mask:0xf bound_ctrl:1
	v_add_f32_dpp v1, v1, v1 quad_perm:[1,0,3,2] row_mask:0xf bank_mask:0xf bound_ctrl:1
	v_add_f32_dpp v26, v25, v24 quad_perm:[1,0,3,2] row_mask:0xf bank_mask:0xf bound_ctrl:1
	v_pk_fma_f32 v[12:13], v[36:37], v[48:49], v[12:13] op_sel_hi:[0,1,1]
	v_pk_fma_f32 v[14:15], v[36:37], v[48:49], v[14:15] op_sel:[1,0,0]
	v_add_f32_dpp v0, v0, v0 quad_perm:[2,3,0,1] row_mask:0xf bank_mask:0xf bound_ctrl:1
	v_add_f32_dpp v1, v1, v1 quad_perm:[2,3,0,1] row_mask:0xf bank_mask:0xf bound_ctrl:1
	v_add_f32_dpp v26, v26, v26 quad_perm:[2,3,0,1] row_mask:0xf bank_mask:0xf bound_ctrl:1
	v_pk_fma_f32 v[16:17], v[38:39], v[48:49], v[16:17] op_sel_hi:[0,1,1]
	v_pk_fma_f32 v[18:19], v[38:39], v[48:49], v[18:19] op_sel:[1,0,0]
	v_add_f32_dpp v0, v0, v0 row_half_mirror row_mask:0xf bank_mask:0xf bound_ctrl:1
	v_add_f32_dpp v1, v1, v1 row_half_mirror row_mask:0xf bank_mask:0xf bound_ctrl:1
	v_add_f32_dpp v26, v26, v26 row_ror:4 row_mask:0xf bank_mask:0xf bound_ctrl:1
	s_nop 0
	v_add_f32_dpp v0, v0, v0 row_mirror row_mask:0xf bank_mask:0xf bound_ctrl:1
	v_add_f32_dpp v1, v1, v1 row_mirror row_mask:0xf bank_mask:0xf bound_ctrl:1
	v_add_f32_dpp v26, v26, v26 row_ror:8 row_mask:0xf bank_mask:0xf bound_ctrl:1
	ds_write_b32 v76, v26 offset:1664
	v_pk_fma_f32 v[8:9], v[40:41], v[0:1], v[12:13] op_sel_hi:[0,1,1]
	v_pk_fma_f32 v[10:11], v[40:41], v[0:1], v[14:15] op_sel:[1,0,0]
	v_pk_fma_f32 v[20:21], v[42:43], v[0:1], v[16:17] op_sel_hi:[0,1,1]
	v_pk_fma_f32 v[22:23], v[42:43], v[0:1], v[18:19] op_sel:[1,0,0]
	v_pk_mul_f32 v[4:5], v[8:9], v[44:45] op_sel_hi:[1,0]
	v_pk_mul_f32 v[6:7], v[10:11], v[44:45] op_sel:[0,1]
	v_pk_fma_f32 v[4:5], v[20:21], v[46:47], v[4:5] op_sel_hi:[1,0,1]
	v_pk_fma_f32 v[6:7], v[22:23], v[46:47], v[6:7] op_sel:[0,1,0]
	ds_read_b128 v[28:31], v74 offset:28672
	ds_read_b128 v[32:35], v74 offset:12288
	ds_read_b128 v[36:39], v74 offset:20480
	ds_read_b128 v[40:43], v74 offset:36864
	ds_read_b128 v[44:47], v74 offset:4096
	ds_read_b64 v[48:49], v75 offset:43008
	s_waitcnt lgkmcnt(7)
	v_pk_mul_f32 v[0:1], v[8:9], v[106:107] op_sel_hi:[1,0]
	v_pk_mul_f32 v[2:3], v[10:11], v[106:107] op_sel:[0,1]
	v_pk_fma_f32 v[0:1], v[20:21], v[108:109], v[0:1] op_sel_hi:[1,0,1]
	v_pk_fma_f32 v[2:3], v[22:23], v[108:109], v[2:3] op_sel:[0,1,0]
	v_pk_add_f32 v[4:5], v[4:5], v[6:7]
	v_pk_mul_f32 v[12:13], v[8:9], v[110:111] op_sel_hi:[1,0]
	v_pk_add_f32 v[0:1], v[0:1], v[2:3]
	v_pk_mul_f32 v[14:15], v[10:11], v[110:111] op_sel:[0,1]
	v_cndmask_b32_e32 v24, v4, v5, vcc
	v_cndmask_b32_e32 v25, v5, v4, vcc
	v_pk_mul_f32 v[16:17], v[20:21], v[112:113] op_sel_hi:[1,0]
	v_pk_mul_f32 v[18:19], v[22:23], v[112:113] op_sel:[0,1]
	v_add_f32_dpp v0, v0, v0 quad_perm:[1,0,3,2] row_mask:0xf bank_mask:0xf bound_ctrl:1
	v_add_f32_dpp v1, v1, v1 quad_perm:[1,0,3,2] row_mask:0xf bank_mask:0xf bound_ctrl:1
	v_add_f32_dpp v26, v25, v24 quad_perm:[1,0,3,2] row_mask:0xf bank_mask:0xf bound_ctrl:1
	v_pk_fma_f32 v[12:13], v[114:115], v[126:127], v[12:13] op_sel_hi:[0,1,1]
	v_pk_fma_f32 v[14:15], v[114:115], v[126:127], v[14:15] op_sel:[1,0,0]
	v_add_f32_dpp v0, v0, v0 quad_perm:[2,3,0,1] row_mask:0xf bank_mask:0xf bound_ctrl:1
	v_add_f32_dpp v1, v1, v1 quad_perm:[2,3,0,1] row_mask:0xf bank_mask:0xf bound_ctrl:1
	v_add_f32_dpp v26, v26, v26 quad_perm:[2,3,0,1] row_mask:0xf bank_mask:0xf bound_ctrl:1
	v_pk_fma_f32 v[16:17], v[116:117], v[126:127], v[16:17] op_sel_hi:[0,1,1]
	v_pk_fma_f32 v[18:19], v[116:117], v[126:127], v[18:19] op_sel:[1,0,0]
	v_add_f32_dpp v0, v0, v0 row_half_mirror row_mask:0xf bank_mask:0xf bound_ctrl:1
	v_add_f32_dpp v1, v1, v1 row_half_mirror row_mask:0xf bank_mask:0xf bound_ctrl:1
	v_add_f32_dpp v26, v26, v26 row_ror:4 row_mask:0xf bank_mask:0xf bound_ctrl:1
	s_nop 0
	v_add_f32_dpp v0, v0, v0 row_mirror row_mask:0xf bank_mask:0xf bound_ctrl:1
	v_add_f32_dpp v1, v1, v1 row_mirror row_mask:0xf bank_mask:0xf bound_ctrl:1
	v_add_f32_dpp v26, v26, v26 row_ror:8 row_mask:0xf bank_mask:0xf bound_ctrl:1
	ds_write_b32 v76, v26 offset:1792
	v_pk_fma_f32 v[8:9], v[118:119], v[0:1], v[12:13] op_sel_hi:[0,1,1]
	v_pk_fma_f32 v[10:11], v[118:119], v[0:1], v[14:15] op_sel:[1,0,0]
	v_pk_fma_f32 v[20:21], v[120:121], v[0:1], v[16:17] op_sel_hi:[0,1,1]
	v_pk_fma_f32 v[22:23], v[120:121], v[0:1], v[18:19] op_sel:[1,0,0]
	v_pk_mul_f32 v[4:5], v[8:9], v[122:123] op_sel_hi:[1,0]
	v_pk_mul_f32 v[6:7], v[10:11], v[122:123] op_sel:[0,1]
	v_pk_fma_f32 v[4:5], v[20:21], v[124:125], v[4:5] op_sel_hi:[1,0,1]
	v_pk_fma_f32 v[6:7], v[22:23], v[124:125], v[6:7] op_sel:[0,1,0]
	ds_read_b128 v[106:109], v74 offset:28928
	ds_read_b128 v[110:113], v74 offset:12544
	ds_read_b128 v[114:117], v74 offset:20736
	ds_read_b128 v[118:121], v74 offset:37120
	ds_read_b128 v[122:125], v74 offset:4352
	ds_read_b64 v[126:127], v75 offset:43136
	s_waitcnt lgkmcnt(7)
; __device__ __forceinline__ void rwkv_scan_phase(Frame& F, const bf16* RKV, const float* WAG, const bf16* AGB, const float* k_k, const float* k_a, const float* r_k, bf16* Y, float* BS, float* ST2) {
;     ...
;                 f32x2 r0[4], w0[4], k0[4], a0[4], b0[4], r1[4], w1[4], k1[4], a1[4], b1[4]; float v0, v1;
;                 SC_LOAD(r0, w0, k0, a0, b0, v0, 0);
; #pragma unroll
;                 for (int t = 0; t < SC_T; t += 2) {
;                     SC_LOAD(r1, w1, k1, a1, b1, v1, t + 1);
;                     SC_STEP(r0, w0, k0, a0, b0, v0, t);
;                     if (t + 2 < SC_T) SC_LOAD(r0, w0, k0, a0, b0, v0, t + 2);
;                     SC_STEP(r1, w1, k1, a1, b1, v1, t + 1);
	v_pk_mul_f32 v[0:1], v[8:9], v[28:29] op_sel_hi:[1,0]
	v_pk_mul_f32 v[2:3], v[10:11], v[28:29] op_sel:[0,1]
	v_pk_fma_f32 v[0:1], v[20:21], v[30:31], v[0:1] op_sel_hi:[1,0,1]
	v_pk_fma_f32 v[2:3], v[22:23], v[30:31], v[2:3] op_sel:[0,1,0]
	v_pk_add_f32 v[4:5], v[4:5], v[6:7]
	v_pk_mul_f32 v[12:13], v[8:9], v[32:33] op_sel_hi:[1,0]
	v_pk_add_f32 v[0:1], v[0:1], v[2:3]
	v_pk_mul_f32 v[14:15], v[10:11], v[32:33] op_sel:[0,1]
	v_cndmask_b32_e32 v24, v4, v5, vcc
	v_cndmask_b32_e32 v25, v5, v4, vcc
	v_pk_mul_f32 v[16:17], v[20:21], v[34:35] op_sel_hi:[1,0]
	v_pk_mul_f32 v[18:19], v[22:23], v[34:35] op_sel:[0,1]
	v_add_f32_dpp v0, v0, v0 quad_perm:[1,0,3,2] row_mask:0xf bank_mask:0xf bound_ctrl:1
	v_add_f32_dpp v1, v1, v1 quad_perm:[1,0,3,2] row_mask:0xf bank_mask:0xf bound_ctrl:1
	v_add_f32_dpp v26, v25, v24 quad_perm:[1,0,3,2] row_mask:0xf bank_mask:0xf bound_ctrl:1
	v_pk_fma_f32 v[12:13], v[36:37], v[48:49], v[12:13] op_sel_hi:[0,1,1]
	v_pk_fma_f32 v[14:15], v[36:37], v[48:49], v[14:15] op_sel:[1,0,0]
	v_add_f32_dpp v0, v0, v0 quad_perm:[2,3,0,1] row_mask:0xf bank_mask:0xf bound_ctrl:1
	v_add_f32_dpp v1, v1, v1 quad_perm:[2,3,0,1] row_mask:0xf bank_mask:0xf bound_ctrl:1
	v_add_f32_dpp v26, v26, v26 quad_perm:[2,3,0,1] row_mask:0xf bank_mask:0xf bound_ctrl:1
	v_pk_fma_f32 v[16:17], v[38:39], v[48:49], v[16:17] op_sel_hi:[0,1,1]
	v_pk_fma_f32 v[18:19], v[38:39], v[48:49], v[18:19] op_sel:[1,0,0]
	v_add_f32_dpp v0, v0, v0 row_half_mirror row_mask:0xf bank_mask:0xf bound_ctrl:1
	v_add_f32_dpp v1, v1, v1 row_half_mirror row_mask:0xf bank_mask:0xf bound_ctrl:1
	v_add_f32_dpp v26, v26, v26 row_ror:4 row_mask:0xf bank_mask:0xf bound_ctrl:1
	s_nop 0
	v_add_f32_dpp v0, v0, v0 row_mirror row_mask:0xf bank_mask:0xf bound_ctrl:1
	v_add_f32_dpp v1, v1, v1 row_mirror row_mask:0xf bank_mask:0xf bound_ctrl:1
	v_add_f32_dpp v26, v26, v26 row_ror:8 row_mask:0xf bank_mask:0xf bound_ctrl:1
	ds_write_b32 v76, v26 offset:1920
	v_pk_fma_f32 v[8:9], v[40:41], v[0:1], v[12:13] op_sel_hi:[0,1,1]
	v_pk_fma_f32 v[10:11], v[40:41], v[0:1], v[14:15] op_sel:[1,0,0]
	v_pk_fma_f32 v[20:21], v[42:43], v[0:1], v[16:17] op_sel_hi:[0,1,1]
	v_pk_fma_f32 v[22:23], v[42:43], v[0:1], v[18:19] op_sel:[1,0,0]
	v_pk_mul_f32 v[4:5], v[8:9], v[44:45] op_sel_hi:[1,0]
	v_pk_mul_f32 v[6:7], v[10:11], v[44:45] op_sel:[0,1]
	v_pk_fma_f32 v[4:5], v[20:21], v[46:47], v[4:5] op_sel_hi:[1,0,1]
	v_pk_fma_f32 v[6:7], v[22:23], v[46:47], v[6:7] op_sel:[0,1,0]
	ds_read_b128 v[28:31], v74 offset:29184
	ds_read_b128 v[32:35], v74 offset:12800
	ds_read_b128 v[36:39], v74 offset:20992
	ds_read_b128 v[40:43], v74 offset:37376
	ds_read_b128 v[44:47], v74 offset:4608
	ds_read_b64 v[48:49], v75 offset:43264
	s_waitcnt lgkmcnt(7)
	v_pk_mul_f32 v[0:1], v[8:9], v[106:107] op_sel_hi:[1,0]
	v_pk_mul_f32 v[2:3], v[10:11], v[106:107] op_sel:[0,1]
	v_pk_fma_f32 v[0:1], v[20:21], v[108:109], v[0:1] op_sel_hi:[1,0,1]
	v_pk_fma_f32 v[2:3], v[22:23], v[108:109], v[2:3] op_sel:[0,1,0]
	v_pk_add_f32 v[4:5], v[4:5], v[6:7]
	v_pk_mul_f32 v[12:13], v[8:9], v[110:111] op_sel_hi:[1,0]
	v_pk_add_f32 v[0:1], v[0:1], v[2:3]
	v_pk_mul_f32 v[14:15], v[10:11], v[110:111] op_sel:[0,1]
	v_cndmask_b32_e32 v24, v4, v5, vcc
	v_cndmask_b32_e32 v25, v5, v4, vcc
	v_pk_mul_f32 v[16:17], v[20:21], v[112:113] op_sel_hi:[1,0]
	v_pk_mul_f32 v[18:19], v[22:23], v[112:113] op_sel:[0,1]
	v_add_f32_dpp v0, v0, v0 quad_perm:[1,0,3,2] row_mask:0xf bank_mask:0xf bound_ctrl:1
	v_add_f32_dpp v1, v1, v1 quad_perm:[1,0,3,2] row_mask:0xf bank_mask:0xf bound_ctrl:1
	v_add_f32_dpp v26, v25, v24 quad_perm:[1,0,3,2] row_mask:0xf bank_mask:0xf bound_ctrl:1
	v_pk_fma_f32 v[12:13], v[114:115], v[126:127], v[12:13] op_sel_hi:[0,1,1]
	v_pk_fma_f32 v[14:15], v[114:115], v[126:127], v[14:15] op_sel:[1,0,0]
	v_add_f32_dpp v0, v0, v0 quad_perm:[2,3,0,1] row_mask:0xf bank_mask:0xf bound_ctrl:1
	v_add_f32_dpp v1, v1, v1 quad_perm:[2,3,0,1] row_mask:0xf bank_mask:0xf bound_ctrl:1
	v_add_f32_dpp v26, v26, v26 quad_perm:[2,3,0,1] row_mask:0xf bank_mask:0xf bound_ctrl:1
	v_pk_fma_f32 v[16:17], v[116:117], v[126:127], v[16:17] op_sel_hi:[0,1,1]
	v_pk_fma_f32 v[18:19], v[116:117], v[126:127], v[18:19] op_sel:[1,0,0]
	v_add_f32_dpp v0, v0, v0 row_half_mirror row_mask:0xf bank_mask:0xf bound_ctrl:1
	v_add_f32_dpp v1, v1, v1 row_half_mirror row_mask:0xf bank_mask:0xf bound_ctrl:1
	v_add_f32_dpp v26, v26, v26 row_ror:4 row_mask:0xf bank_mask:0xf bound_ctrl:1
	s_nop 0
	v_add_f32_dpp v0, v0, v0 row_mirror row_mask:0xf bank_mask:0xf bound_ctrl:1
	v_add_f32_dpp v1, v1, v1 row_mirror row_mask:0xf bank_mask:0xf bound_ctrl:1
	v_add_f32_dpp v26, v26, v26 row_ror:8 row_mask:0xf bank_mask:0xf bound_ctrl:1
	ds_write_b32 v76, v26 offset:2048
	v_pk_fma_f32 v[8:9], v[118:119], v[0:1], v[12:13] op_sel_hi:[0,1,1]
	v_pk_fma_f32 v[10:11], v[118:119], v[0:1], v[14:15] op_sel:[1,0,0]
	v_pk_fma_f32 v[20:21], v[120:121], v[0:1], v[16:17] op_sel_hi:[0,1,1]
	v_pk_fma_f32 v[22:23], v[120:121], v[0:1], v[18:19] op_sel:[1,0,0]
	v_pk_mul_f32 v[4:5], v[8:9], v[122:123] op_sel_hi:[1,0]
	v_pk_mul_f32 v[6:7], v[10:11], v[122:123] op_sel:[0,1]
	v_pk_fma_f32 v[4:5], v[20:21], v[124:125], v[4:5] op_sel_hi:[1,0,1]
	v_pk_fma_f32 v[6:7], v[22:23], v[124:125], v[6:7] op_sel:[0,1,0]
	ds_read_b128 v[106:109], v74 offset:29440
	ds_read_b128 v[110:113], v74 offset:13056
	ds_read_b128 v[114:117], v74 offset:21248
	ds_read_b128 v[118:121], v74 offset:37632
	ds_read_b128 v[122:125], v74 offset:4864
	ds_read_b64 v[126:127], v75 offset:43392
	s_waitcnt lgkmcnt(7)
; __device__ __forceinline__ void rwkv_scan_phase(Frame& F, const bf16* RKV, const float* WAG, const bf16* AGB, const float* k_k, const float* k_a, const float* r_k, bf16* Y, float* BS, float* ST2) {
;     ...
;                 f32x2 r0[4], w0[4], k0[4], a0[4], b0[4], r1[4], w1[4], k1[4], a1[4], b1[4]; float v0, v1;
;                 SC_LOAD(r0, w0, k0, a0, b0, v0, 0);
; #pragma unroll
;                 for (int t = 0; t < SC_T; t += 2) {
;                     SC_LOAD(r1, w1, k1, a1, b1, v1, t + 1);
;                     SC_STEP(r0, w0, k0, a0, b0, v0, t);
;                     if (t + 2 < SC_T) SC_LOAD(r0, w0, k0, a0, b0, v0, t + 2);
;                     SC_STEP(r1, w1, k1, a1, b1, v1, t + 1);
	v_pk_mul_f32 v[0:1], v[8:9], v[28:29] op_sel_hi:[1,0]
	v_pk_mul_f32 v[2:3], v[10:11], v[28:29] op_sel:[0,1]
	v_pk_fma_f32 v[0:1], v[20:21], v[30:31], v[0:1] op_sel_hi:[1,0,1]
	v_pk_fma_f32 v[2:3], v[22:23], v[30:31], v[2:3] op_sel:[0,1,0]
	v_pk_add_f32 v[4:5], v[4:5], v[6:7]
	v_pk_mul_f32 v[12:13], v[8:9], v[32:33] op_sel_hi:[1,0]
	v_pk_add_f32 v[0:1], v[0:1], v[2:3]
	v_pk_mul_f32 v[14:15], v[10:11], v[32:33] op_sel:[0,1]
	v_cndmask_b32_e32 v24, v4, v5, vcc
	v_cndmask_b32_e32 v25, v5, v4, vcc
	v_pk_mul_f32 v[16:17], v[20:21], v[34:35] op_sel_hi:[1,0]
	v_pk_mul_f32 v[18:19], v[22:23], v[34:35] op_sel:[0,1]
	v_add_f32_dpp v0, v0, v0 quad_perm:[1,0,3,2] row_mask:0xf bank_mask:0xf bound_ctrl:1
	v_add_f32_dpp v1, v1, v1 quad_perm:[1,0,3,2] row_mask:0xf bank_mask:0xf bound_ctrl:1
	v_add_f32_dpp v26, v25, v24 quad_perm:[1,0,3,2] row_mask:0xf bank_mask:0xf bound_ctrl:1
	v_pk_fma_f32 v[12:13], v[36:37], v[48:49], v[12:13] op_sel_hi:[0,1,1]
	v_pk_fma_f32 v[14:15], v[36:37], v[48:49], v[14:15] op_sel:[1,0,0]
	v_add_f32_dpp v0, v0, v0 quad_perm:[2,3,0,1] row_mask:0xf bank_mask:0xf bound_ctrl:1
	v_add_f32_dpp v1, v1, v1 quad_perm:[2,3,0,1] row_mask:0xf bank_mask:0xf bound_ctrl:1
	v_add_f32_dpp v26, v26, v26 quad_perm:[2,3,0,1] row_mask:0xf bank_mask:0xf bound_ctrl:1
	v_pk_fma_f32 v[16:17], v[38:39], v[48:49], v[16:17] op_sel_hi:[0,1,1]
	v_pk_fma_f32 v[18:19], v[38:39], v[48:49], v[18:19] op_sel:[1,0,0]
	v_add_f32_dpp v0, v0, v0 row_half_mirror row_mask:0xf bank_mask:0xf bound_ctrl:1
	v_add_f32_dpp v1, v1, v1 row_half_mirror row_mask:0xf bank_mask:0xf bound_ctrl:1
	v_add_f32_dpp v26, v26, v26 row_ror:4 row_mask:0xf bank_mask:0xf bound_ctrl:1
	s_nop 0
	v_add_f32_dpp v0, v0, v0 row_mirror row_mask:0xf bank_mask:0xf bound_ctrl:1
	v_add_f32_dpp v1, v1, v1 row_mirror row_mask:0xf bank_mask:0xf bound_ctrl:1
	v_add_f32_dpp v26, v26, v26 row_ror:8 row_mask:0xf bank_mask:0xf bound_ctrl:1
	ds_write_b32 v76, v26 offset:2176
	v_pk_fma_f32 v[8:9], v[40:41], v[0:1], v[12:13] op_sel_hi:[0,1,1]
	v_pk_fma_f32 v[10:11], v[40:41], v[0:1], v[14:15] op_sel:[1,0,0]
	v_pk_fma_f32 v[20:21], v[42:43], v[0:1], v[16:17] op_sel_hi:[0,1,1]
	v_pk_fma_f32 v[22:23], v[42:43], v[0:1], v[18:19] op_sel:[1,0,0]
	v_pk_mul_f32 v[4:5], v[8:9], v[44:45] op_sel_hi:[1,0]
	v_pk_mul_f32 v[6:7], v[10:11], v[44:45] op_sel:[0,1]
	v_pk_fma_f32 v[4:5], v[20:21], v[46:47], v[4:5] op_sel_hi:[1,0,1]
	v_pk_fma_f32 v[6:7], v[22:23], v[46:47], v[6:7] op_sel:[0,1,0]
	ds_read_b128 v[28:31], v74 offset:29696
	ds_read_b128 v[32:35], v74 offset:13312
	ds_read_b128 v[36:39], v74 offset:21504
	ds_read_b128 v[40:43], v74 offset:37888
	ds_read_b128 v[44:47], v74 offset:5120
	ds_read_b64 v[48:49], v75 offset:43520
	s_waitcnt lgkmcnt(7)
	v_pk_mul_f32 v[0:1], v[8:9], v[106:107] op_sel_hi:[1,0]
	v_pk_mul_f32 v[2:3], v[10:11], v[106:107] op_sel:[0,1]
	v_pk_fma_f32 v[0:1], v[20:21], v[108:109], v[0:1] op_sel_hi:[1,0,1]
	v_pk_fma_f32 v[2:3], v[22:23], v[108:109], v[2:3] op_sel:[0,1,0]
	v_pk_add_f32 v[4:5], v[4:5], v[6:7]
	v_pk_mul_f32 v[12:13], v[8:9], v[110:111] op_sel_hi:[1,0]
	v_pk_add_f32 v[0:1], v[0:1], v[2:3]
	v_pk_mul_f32 v[14:15], v[10:11], v[110:111] op_sel:[0,1]
	v_cndmask_b32_e32 v24, v4, v5, vcc
	v_cndmask_b32_e32 v25, v5, v4, vcc
	v_pk_mul_f32 v[16:17], v[20:21], v[112:113] op_sel_hi:[1,0]
	v_pk_mul_f32 v[18:19], v[22:23], v[112:113] op_sel:[0,1]
	v_add_f32_dpp v0, v0, v0 quad_perm:[1,0,3,2] row_mask:0xf bank_mask:0xf bound_ctrl:1
	v_add_f32_dpp v1, v1, v1 quad_perm:[1,0,3,2] row_mask:0xf bank_mask:0xf bound_ctrl:1
	v_add_f32_dpp v26, v25, v24 quad_perm:[1,0,3,2] row_mask:0xf bank_mask:0xf bound_ctrl:1
	v_pk_fma_f32 v[12:13], v[114:115], v[126:127], v[12:13] op_sel_hi:[0,1,1]
	v_pk_fma_f32 v[14:15], v[114:115], v[126:127], v[14:15] op_sel:[1,0,0]
	v_add_f32_dpp v0, v0, v0 quad_perm:[2,3,0,1] row_mask:0xf bank_mask:0xf bound_ctrl:1
	v_add_f32_dpp v1, v1, v1 quad_perm:[2,3,0,1] row_mask:0xf bank_mask:0xf bound_ctrl:1
	v_add_f32_dpp v26, v26, v26 quad_perm:[2,3,0,1] row_mask:0xf bank_mask:0xf bound_ctrl:1
	v_pk_fma_f32 v[16:17], v[116:117], v[126:127], v[16:17] op_sel_hi:[0,1,1]
	v_pk_fma_f32 v[18:19], v[116:117], v[126:127], v[18:19] op_sel:[1,0,0]
	v_add_f32_dpp v0, v0, v0 row_half_mirror row_mask:0xf bank_mask:0xf bound_ctrl:1
	v_add_f32_dpp v1, v1, v1 row_half_mirror row_mask:0xf bank_mask:0xf bound_ctrl:1
	v_add_f32_dpp v26, v26, v26 row_ror:4 row_mask:0xf bank_mask:0xf bound_ctrl:1
	s_nop 0
	v_add_f32_dpp v0, v0, v0 row_mirror row_mask:0xf bank_mask:0xf bound_ctrl:1
	v_add_f32_dpp v1, v1, v1 row_mirror row_mask:0xf bank_mask:0xf bound_ctrl:1
	v_add_f32_dpp v26, v26, v26 row_ror:8 row_mask:0xf bank_mask:0xf bound_ctrl:1
	ds_write_b32 v76, v26 offset:2304
	v_pk_fma_f32 v[8:9], v[118:119], v[0:1], v[12:13] op_sel_hi:[0,1,1]
	v_pk_fma_f32 v[10:11], v[118:119], v[0:1], v[14:15] op_sel:[1,0,0]
	v_pk_fma_f32 v[20:21], v[120:121], v[0:1], v[16:17] op_sel_hi:[0,1,1]
	v_pk_fma_f32 v[22:23], v[120:121], v[0:1], v[18:19] op_sel:[1,0,0]
	v_pk_mul_f32 v[4:5], v[8:9], v[122:123] op_sel_hi:[1,0]
	v_pk_mul_f32 v[6:7], v[10:11], v[122:123] op_sel:[0,1]
	v_pk_fma_f32 v[4:5], v[20:21], v[124:125], v[4:5] op_sel_hi:[1,0,1]
	v_pk_fma_f32 v[6:7], v[22:23], v[124:125], v[6:7] op_sel:[0,1,0]
	ds_read_b128 v[106:109], v74 offset:29952
	ds_read_b128 v[110:113], v74 offset:13568
	ds_read_b128 v[114:117], v74 offset:21760
	ds_read_b128 v[118:121], v74 offset:38144
	ds_read_b128 v[122:125], v74 offset:5376
	ds_read_b64 v[126:127], v75 offset:43648
	s_waitcnt lgkmcnt(7)
; __device__ __forceinline__ void rwkv_scan_phase(Frame& F, const bf16* RKV, const float* WAG, const bf16* AGB, const float* k_k, const float* k_a, const float* r_k, bf16* Y, float* BS, float* ST2) {
;     ...
;                 f32x2 r0[4], w0[4], k0[4], a0[4], b0[4], r1[4], w1[4], k1[4], a1[4], b1[4]; float v0, v1;
;                 SC_LOAD(r0, w0, k0, a0, b0, v0, 0);
; #pragma unroll
;                 for (int t = 0; t < SC_T; t += 2) {
;                     SC_LOAD(r1, w1, k1, a1, b1, v1, t + 1);
;                     SC_STEP(r0, w0, k0, a0, b0, v0, t);
;                     if (t + 2 < SC_T) SC_LOAD(r0, w0, k0, a0, b0, v0, t + 2);
;                     SC_STEP(r1, w1, k1, a1, b1, v1, t + 1);
	v_pk_mul_f32 v[0:1], v[8:9], v[28:29] op_sel_hi:[1,0]
	v_pk_mul_f32 v[2:3], v[10:11], v[28:29] op_sel:[0,1]
	v_pk_fma_f32 v[0:1], v[20:21], v[30:31], v[0:1] op_sel_hi:[1,0,1]
	v_pk_fma_f32 v[2:3], v[22:23], v[30:31], v[2:3] op_sel:[0,1,0]
	v_pk_add_f32 v[4:5], v[4:5], v[6:7]
	v_pk_mul_f32 v[12:13], v[8:9], v[32:33] op_sel_hi:[1,0]
	v_pk_add_f32 v[0:1], v[0:1], v[2:3]
	v_pk_mul_f32 v[14:15], v[10:11], v[32:33] op_sel:[0,1]
	v_cndmask_b32_e32 v24, v4, v5, vcc
	v_cndmask_b32_e32 v25, v5, v4, vcc
	v_pk_mul_f32 v[16:17], v[20:21], v[34:35] op_sel_hi:[1,0]
	v_pk_mul_f32 v[18:19], v[22:23], v[34:35] op_sel:[0,1]
	v_add_f32_dpp v0, v0, v0 quad_perm:[1,0,3,2] row_mask:0xf bank_mask:0xf bound_ctrl:1
	v_add_f32_dpp v1, v1, v1 quad_perm:[1,0,3,2] row_mask:0xf bank_mask:0xf bound_ctrl:1
	v_add_f32_dpp v26, v25, v24 quad_perm:[1,0,3,2] row_mask:0xf bank_mask:0xf bound_ctrl:1
	v_pk_fma_f32 v[12:13], v[36:37], v[48:49], v[12:13] op_sel_hi:[0,1,1]
	v_pk_fma_f32 v[14:15], v[36:37], v[48:49], v[14:15] op_sel:[1,0,0]
	v_add_f32_dpp v0, v0, v0 quad_perm:[2,3,0,1] row_mask:0xf bank_mask:0xf bound_ctrl:1
	v_add_f32_dpp v1, v1, v1 quad_perm:[2,3,0,1] row_mask:0xf bank_mask:0xf bound_ctrl:1
	v_add_f32_dpp v26, v26, v26 quad_perm:[2,3,0,1] row_mask:0xf bank_mask:0xf bound_ctrl:1
	v_pk_fma_f32 v[16:17], v[38:39], v[48:49], v[16:17] op_sel_hi:[0,1,1]
	v_pk_fma_f32 v[18:19], v[38:39], v[48:49], v[18:19] op_sel:[1,0,0]
	v_add_f32_dpp v0, v0, v0 row_half_mirror row_mask:0xf bank_mask:0xf bound_ctrl:1
	v_add_f32_dpp v1, v1, v1 row_half_mirror row_mask:0xf bank_mask:0xf bound_ctrl:1
	v_add_f32_dpp v26, v26, v26 row_ror:4 row_mask:0xf bank_mask:0xf bound_ctrl:1
	s_nop 0
	v_add_f32_dpp v0, v0, v0 row_mirror row_mask:0xf bank_mask:0xf bound_ctrl:1
	v_add_f32_dpp v1, v1, v1 row_mirror row_mask:0xf bank_mask:0xf bound_ctrl:1
	v_add_f32_dpp v26, v26, v26 row_ror:8 row_mask:0xf bank_mask:0xf bound_ctrl:1
	ds_write_b32 v76, v26 offset:2432
	v_pk_fma_f32 v[8:9], v[40:41], v[0:1], v[12:13] op_sel_hi:[0,1,1]
	v_pk_fma_f32 v[10:11], v[40:41], v[0:1], v[14:15] op_sel:[1,0,0]
	v_pk_fma_f32 v[20:21], v[42:43], v[0:1], v[16:17] op_sel_hi:[0,1,1]
	v_pk_fma_f32 v[22:23], v[42:43], v[0:1], v[18:19] op_sel:[1,0,0]
	v_pk_mul_f32 v[4:5], v[8:9], v[44:45] op_sel_hi:[1,0]
	v_pk_mul_f32 v[6:7], v[10:11], v[44:45] op_sel:[0,1]
	v_pk_fma_f32 v[4:5], v[20:21], v[46:47], v[4:5] op_sel_hi:[1,0,1]
	v_pk_fma_f32 v[6:7], v[22:23], v[46:47], v[6:7] op_sel:[0,1,0]
	ds_read_b128 v[28:31], v74 offset:30208
	ds_read_b128 v[32:35], v74 offset:13824
	ds_read_b128 v[36:39], v74 offset:22016
	ds_read_b128 v[40:43], v74 offset:38400
	ds_read_b128 v[44:47], v74 offset:5632
	ds_read_b64 v[48:49], v75 offset:43776
	s_waitcnt lgkmcnt(7)
	v_pk_mul_f32 v[0:1], v[8:9], v[106:107] op_sel_hi:[1,0]
	v_pk_mul_f32 v[2:3], v[10:11], v[106:107] op_sel:[0,1]
	v_pk_fma_f32 v[0:1], v[20:21], v[108:109], v[0:1] op_sel_hi:[1,0,1]
	v_pk_fma_f32 v[2:3], v[22:23], v[108:109], v[2:3] op_sel:[0,1,0]
	v_pk_add_f32 v[4:5], v[4:5], v[6:7]
	v_pk_mul_f32 v[12:13], v[8:9], v[110:111] op_sel_hi:[1,0]
	v_pk_add_f32 v[0:1], v[0:1], v[2:3]
	v_pk_mul_f32 v[14:15], v[10:11], v[110:111] op_sel:[0,1]
	v_cndmask_b32_e32 v24, v4, v5, vcc
	v_cndmask_b32_e32 v25, v5, v4, vcc
	v_pk_mul_f32 v[16:17], v[20:21], v[112:113] op_sel_hi:[1,0]
	v_pk_mul_f32 v[18:19], v[22:23], v[112:113] op_sel:[0,1]
	v_add_f32_dpp v0, v0, v0 quad_perm:[1,0,3,2] row_mask:0xf bank_mask:0xf bound_ctrl:1
	v_add_f32_dpp v1, v1, v1 quad_perm:[1,0,3,2] row_mask:0xf bank_mask:0xf bound_ctrl:1
	v_add_f32_dpp v26, v25, v24 quad_perm:[1,0,3,2] row_mask:0xf bank_mask:0xf bound_ctrl:1
	v_pk_fma_f32 v[12:13], v[114:115], v[126:127], v[12:13] op_sel_hi:[0,1,1]
	v_pk_fma_f32 v[14:15], v[114:115], v[126:127], v[14:15] op_sel:[1,0,0]
	v_add_f32_dpp v0, v0, v0 quad_perm:[2,3,0,1] row_mask:0xf bank_mask:0xf bound_ctrl:1
	v_add_f32_dpp v1, v1, v1 quad_perm:[2,3,0,1] row_mask:0xf bank_mask:0xf bound_ctrl:1
	v_add_f32_dpp v26, v26, v26 quad_perm:[2,3,0,1] row_mask:0xf bank_mask:0xf bound_ctrl:1
	v_pk_fma_f32 v[16:17], v[116:117], v[126:127], v[16:17] op_sel_hi:[0,1,1]
	v_pk_fma_f32 v[18:19], v[116:117], v[126:127], v[18:19] op_sel:[1,0,0]
	v_add_f32_dpp v0, v0, v0 row_half_mirror row_mask:0xf bank_mask:0xf bound_ctrl:1
	v_add_f32_dpp v1, v1, v1 row_half_mirror row_mask:0xf bank_mask:0xf bound_ctrl:1
	v_add_f32_dpp v26, v26, v26 row_ror:4 row_mask:0xf bank_mask:0xf bound_ctrl:1
	s_nop 0
	v_add_f32_dpp v0, v0, v0 row_mirror row_mask:0xf bank_mask:0xf bound_ctrl:1
	v_add_f32_dpp v1, v1, v1 row_mirror row_mask:0xf bank_mask:0xf bound_ctrl:1
	v_add_f32_dpp v26, v26, v26 row_ror:8 row_mask:0xf bank_mask:0xf bound_ctrl:1
	ds_write_b32 v76, v26 offset:2560
	v_pk_fma_f32 v[8:9], v[118:119], v[0:1], v[12:13] op_sel_hi:[0,1,1]
	v_pk_fma_f32 v[10:11], v[118:119], v[0:1], v[14:15] op_sel:[1,0,0]
	v_pk_fma_f32 v[20:21], v[120:121], v[0:1], v[16:17] op_sel_hi:[0,1,1]
	v_pk_fma_f32 v[22:23], v[120:121], v[0:1], v[18:19] op_sel:[1,0,0]
	v_pk_mul_f32 v[4:5], v[8:9], v[122:123] op_sel_hi:[1,0]
	v_pk_mul_f32 v[6:7], v[10:11], v[122:123] op_sel:[0,1]
	v_pk_fma_f32 v[4:5], v[20:21], v[124:125], v[4:5] op_sel_hi:[1,0,1]
	v_pk_fma_f32 v[6:7], v[22:23], v[124:125], v[6:7] op_sel:[0,1,0]
	ds_read_b128 v[106:109], v74 offset:30464
	ds_read_b128 v[110:113], v74 offset:14080
	ds_read_b128 v[114:117], v74 offset:22272
	ds_read_b128 v[118:121], v74 offset:38656
	ds_read_b128 v[122:125], v74 offset:5888
	ds_read_b64 v[126:127], v75 offset:43904
	s_waitcnt lgkmcnt(7)
; __device__ __forceinline__ void rwkv_scan_phase(Frame& F, const bf16* RKV, const float* WAG, const bf16* AGB, const float* k_k, const float* k_a, const float* r_k, bf16* Y, float* BS, float* ST2) {
;     ...
;                 f32x2 r0[4], w0[4], k0[4], a0[4], b0[4], r1[4], w1[4], k1[4], a1[4], b1[4]; float v0, v1;
;                 SC_LOAD(r0, w0, k0, a0, b0, v0, 0);
; #pragma unroll
;                 for (int t = 0; t < SC_T; t += 2) {
;                     SC_LOAD(r1, w1, k1, a1, b1, v1, t + 1);
;                     SC_STEP(r0, w0, k0, a0, b0, v0, t);
;                     if (t + 2 < SC_T) SC_LOAD(r0, w0, k0, a0, b0, v0, t + 2);
;                     SC_STEP(r1, w1, k1, a1, b1, v1, t + 1);
	v_pk_mul_f32 v[0:1], v[8:9], v[28:29] op_sel_hi:[1,0]
	v_pk_mul_f32 v[2:3], v[10:11], v[28:29] op_sel:[0,1]
	v_pk_fma_f32 v[0:1], v[20:21], v[30:31], v[0:1] op_sel_hi:[1,0,1]
	v_pk_fma_f32 v[2:3], v[22:23], v[30:31], v[2:3] op_sel:[0,1,0]
	v_pk_add_f32 v[4:5], v[4:5], v[6:7]
	v_pk_mul_f32 v[12:13], v[8:9], v[32:33] op_sel_hi:[1,0]
	v_pk_add_f32 v[0:1], v[0:1], v[2:3]
	v_pk_mul_f32 v[14:15], v[10:11], v[32:33] op_sel:[0,1]
	v_cndmask_b32_e32 v24, v4, v5, vcc
	v_cndmask_b32_e32 v25, v5, v4, vcc
	v_pk_mul_f32 v[16:17], v[20:21], v[34:35] op_sel_hi:[1,0]
	v_pk_mul_f32 v[18:19], v[22:23], v[34:35] op_sel:[0,1]
	v_add_f32_dpp v0, v0, v0 quad_perm:[1,0,3,2] row_mask:0xf bank_mask:0xf bound_ctrl:1
	v_add_f32_dpp v1, v1, v1 quad_perm:[1,0,3,2] row_mask:0xf bank_mask:0xf bound_ctrl:1
	v_add_f32_dpp v26, v25, v24 quad_perm:[1,0,3,2] row_mask:0xf bank_mask:0xf bound_ctrl:1
	v_pk_fma_f32 v[12:13], v[36:37], v[48:49], v[12:13] op_sel_hi:[0,1,1]
	v_pk_fma_f32 v[14:15], v[36:37], v[48:49], v[14:15] op_sel:[1,0,0]
	v_add_f32_dpp v0, v0, v0 quad_perm:[2,3,0,1] row_mask:0xf bank_mask:0xf bound_ctrl:1
	v_add_f32_dpp v1, v1, v1 quad_perm:[2,3,0,1] row_mask:0xf bank_mask:0xf bound_ctrl:1
	v_add_f32_dpp v26, v26, v26 quad_perm:[2,3,0,1] row_mask:0xf bank_mask:0xf bound_ctrl:1
	v_pk_fma_f32 v[16:17], v[38:39], v[48:49], v[16:17] op_sel_hi:[0,1,1]
	v_pk_fma_f32 v[18:19], v[38:39], v[48:49], v[18:19] op_sel:[1,0,0]
	v_add_f32_dpp v0, v0, v0 row_half_mirror row_mask:0xf bank_mask:0xf bound_ctrl:1
	v_add_f32_dpp v1, v1, v1 row_half_mirror row_mask:0xf bank_mask:0xf bound_ctrl:1
	v_add_f32_dpp v26, v26, v26 row_ror:4 row_mask:0xf bank_mask:0xf bound_ctrl:1
	s_nop 0
	v_add_f32_dpp v0, v0, v0 row_mirror row_mask:0xf bank_mask:0xf bound_ctrl:1
	v_add_f32_dpp v1, v1, v1 row_mirror row_mask:0xf bank_mask:0xf bound_ctrl:1
	v_add_f32_dpp v26, v26, v26 row_ror:8 row_mask:0xf bank_mask:0xf bound_ctrl:1
	ds_write_b32 v76, v26 offset:2688
	v_pk_fma_f32 v[8:9], v[40:41], v[0:1], v[12:13] op_sel_hi:[0,1,1]
	v_pk_fma_f32 v[10:11], v[40:41], v[0:1], v[14:15] op_sel:[1,0,0]
	v_pk_fma_f32 v[20:21], v[42:43], v[0:1], v[16:17] op_sel_hi:[0,1,1]
	v_pk_fma_f32 v[22:23], v[42:43], v[0:1], v[18:19] op_sel:[1,0,0]
	v_pk_mul_f32 v[4:5], v[8:9], v[44:45] op_sel_hi:[1,0]
	v_pk_mul_f32 v[6:7], v[10:11], v[44:45] op_sel:[0,1]
	v_pk_fma_f32 v[4:5], v[20:21], v[46:47], v[4:5] op_sel_hi:[1,0,1]
	v_pk_fma_f32 v[6:7], v[22:23], v[46:47], v[6:7] op_sel:[0,1,0]
	ds_read_b128 v[28:31], v74 offset:30720
	ds_read_b128 v[32:35], v74 offset:14336
	ds_read_b128 v[36:39], v74 offset:22528
	ds_read_b128 v[40:43], v74 offset:38912
	ds_read_b128 v[44:47], v74 offset:6144
	ds_read_b64 v[48:49], v75 offset:44032
	s_waitcnt lgkmcnt(7)
	v_pk_mul_f32 v[0:1], v[8:9], v[106:107] op_sel_hi:[1,0]
	v_pk_mul_f32 v[2:3], v[10:11], v[106:107] op_sel:[0,1]
	v_pk_fma_f32 v[0:1], v[20:21], v[108:109], v[0:1] op_sel_hi:[1,0,1]
	v_pk_fma_f32 v[2:3], v[22:23], v[108:109], v[2:3] op_sel:[0,1,0]
	v_pk_add_f32 v[4:5], v[4:5], v[6:7]
	v_pk_mul_f32 v[12:13], v[8:9], v[110:111] op_sel_hi:[1,0]
	v_pk_add_f32 v[0:1], v[0:1], v[2:3]
	v_pk_mul_f32 v[14:15], v[10:11], v[110:111] op_sel:[0,1]
	v_cndmask_b32_e32 v24, v4, v5, vcc
	v_cndmask_b32_e32 v25, v5, v4, vcc
	v_pk_mul_f32 v[16:17], v[20:21], v[112:113] op_sel_hi:[1,0]
	v_pk_mul_f32 v[18:19], v[22:23], v[112:113] op_sel:[0,1]
	v_add_f32_dpp v0, v0, v0 quad_perm:[1,0,3,2] row_mask:0xf bank_mask:0xf bound_ctrl:1
	v_add_f32_dpp v1, v1, v1 quad_perm:[1,0,3,2] row_mask:0xf bank_mask:0xf bound_ctrl:1
	v_add_f32_dpp v26, v25, v24 quad_perm:[1,0,3,2] row_mask:0xf bank_mask:0xf bound_ctrl:1
	v_pk_fma_f32 v[12:13], v[114:115], v[126:127], v[12:13] op_sel_hi:[0,1,1]
	v_pk_fma_f32 v[14:15], v[114:115], v[126:127], v[14:15] op_sel:[1,0,0]
	v_add_f32_dpp v0, v0, v0 quad_perm:[2,3,0,1] row_mask:0xf bank_mask:0xf bound_ctrl:1
	v_add_f32_dpp v1, v1, v1 quad_perm:[2,3,0,1] row_mask:0xf bank_mask:0xf bound_ctrl:1
	v_add_f32_dpp v26, v26, v26 quad_perm:[2,3,0,1] row_mask:0xf bank_mask:0xf bound_ctrl:1
	v_pk_fma_f32 v[16:17], v[116:117], v[126:127], v[16:17] op_sel_hi:[0,1,1]
	v_pk_fma_f32 v[18:19], v[116:117], v[126:127], v[18:19] op_sel:[1,0,0]
	v_add_f32_dpp v0, v0, v0 row_half_mirror row_mask:0xf bank_mask:0xf bound_ctrl:1
	v_add_f32_dpp v1, v1, v1 row_half_mirror row_mask:0xf bank_mask:0xf bound_ctrl:1
	v_add_f32_dpp v26, v26, v26 row_ror:4 row_mask:0xf bank_mask:0xf bound_ctrl:1
	s_nop 0
	v_add_f32_dpp v0, v0, v0 row_mirror row_mask:0xf bank_mask:0xf bound_ctrl:1
	v_add_f32_dpp v1, v1, v1 row_mirror row_mask:0xf bank_mask:0xf bound_ctrl:1
	v_add_f32_dpp v26, v26, v26 row_ror:8 row_mask:0xf bank_mask:0xf bound_ctrl:1
	ds_write_b32 v76, v26 offset:2816
	v_pk_fma_f32 v[8:9], v[118:119], v[0:1], v[12:13] op_sel_hi:[0,1,1]
	v_pk_fma_f32 v[10:11], v[118:119], v[0:1], v[14:15] op_sel:[1,0,0]
	v_pk_fma_f32 v[20:21], v[120:121], v[0:1], v[16:17] op_sel_hi:[0,1,1]
	v_pk_fma_f32 v[22:23], v[120:121], v[0:1], v[18:19] op_sel:[1,0,0]
	v_pk_mul_f32 v[4:5], v[8:9], v[122:123] op_sel_hi:[1,0]
	v_pk_mul_f32 v[6:7], v[10:11], v[122:123] op_sel:[0,1]
	v_pk_fma_f32 v[4:5], v[20:21], v[124:125], v[4:5] op_sel_hi:[1,0,1]
	v_pk_fma_f32 v[6:7], v[22:23], v[124:125], v[6:7] op_sel:[0,1,0]
	ds_read_b128 v[106:109], v74 offset:30976
	ds_read_b128 v[110:113], v74 offset:14592
	ds_read_b128 v[114:117], v74 offset:22784
	ds_read_b128 v[118:121], v74 offset:39168
	ds_read_b128 v[122:125], v74 offset:6400
	ds_read_b64 v[126:127], v75 offset:44160
	s_waitcnt lgkmcnt(7)
; __device__ __forceinline__ void rwkv_scan_phase(Frame& F, const bf16* RKV, const float* WAG, const bf16* AGB, const float* k_k, const float* k_a, const float* r_k, bf16* Y, float* BS, float* ST2) {
;     ...
;                 f32x2 r0[4], w0[4], k0[4], a0[4], b0[4], r1[4], w1[4], k1[4], a1[4], b1[4]; float v0, v1;
;                 SC_LOAD(r0, w0, k0, a0, b0, v0, 0);
; #pragma unroll
;                 for (int t = 0; t < SC_T; t += 2) {
;                     SC_LOAD(r1, w1, k1, a1, b1, v1, t + 1);
;                     SC_STEP(r0, w0, k0, a0, b0, v0, t);
;                     if (t + 2 < SC_T) SC_LOAD(r0, w0, k0, a0, b0, v0, t + 2);
;                     SC_STEP(r1, w1, k1, a1, b1, v1, t + 1);
	v_pk_mul_f32 v[0:1], v[8:9], v[28:29] op_sel_hi:[1,0]
	v_pk_mul_f32 v[2:3], v[10:11], v[28:29] op_sel:[0,1]
	v_pk_fma_f32 v[0:1], v[20:21], v[30:31], v[0:1] op_sel_hi:[1,0,1]
	v_pk_fma_f32 v[2:3], v[22:23], v[30:31], v[2:3] op_sel:[0,1,0]
	v_pk_add_f32 v[4:5], v[4:5], v[6:7]
	v_pk_mul_f32 v[12:13], v[8:9], v[32:33] op_sel_hi:[1,0]
	v_pk_add_f32 v[0:1], v[0:1], v[2:3]
	v_pk_mul_f32 v[14:15], v[10:11], v[32:33] op_sel:[0,1]
	v_cndmask_b32_e32 v24, v4, v5, vcc
	v_cndmask_b32_e32 v25, v5, v4, vcc
	v_pk_mul_f32 v[16:17], v[20:21], v[34:35] op_sel_hi:[1,0]
	v_pk_mul_f32 v[18:19], v[22:23], v[34:35] op_sel:[0,1]
	v_add_f32_dpp v0, v0, v0 quad_perm:[1,0,3,2] row_mask:0xf bank_mask:0xf bound_ctrl:1
	v_add_f32_dpp v1, v1, v1 quad_perm:[1,0,3,2] row_mask:0xf bank_mask:0xf bound_ctrl:1
	v_add_f32_dpp v26, v25, v24 quad_perm:[1,0,3,2] row_mask:0xf bank_mask:0xf bound_ctrl:1
	v_pk_fma_f32 v[12:13], v[36:37], v[48:49], v[12:13] op_sel_hi:[0,1,1]
	v_pk_fma_f32 v[14:15], v[36:37], v[48:49], v[14:15] op_sel:[1,0,0]
	v_add_f32_dpp v0, v0, v0 quad_perm:[2,3,0,1] row_mask:0xf bank_mask:0xf bound_ctrl:1
	v_add_f32_dpp v1, v1, v1 quad_perm:[2,3,0,1] row_mask:0xf bank_mask:0xf bound_ctrl:1
	v_add_f32_dpp v26, v26, v26 quad_perm:[2,3,0,1] row_mask:0xf bank_mask:0xf bound_ctrl:1
	v_pk_fma_f32 v[16:17], v[38:39], v[48:49], v[16:17] op_sel_hi:[0,1,1]
	v_pk_fma_f32 v[18:19], v[38:39], v[48:49], v[18:19] op_sel:[1,0,0]
	v_add_f32_dpp v0, v0, v0 row_half_mirror row_mask:0xf bank_mask:0xf bound_ctrl:1
	v_add_f32_dpp v1, v1, v1 row_half_mirror row_mask:0xf bank_mask:0xf bound_ctrl:1
	v_add_f32_dpp v26, v26, v26 row_ror:4 row_mask:0xf bank_mask:0xf bound_ctrl:1
	s_nop 0
	v_add_f32_dpp v0, v0, v0 row_mirror row_mask:0xf bank_mask:0xf bound_ctrl:1
	v_add_f32_dpp v1, v1, v1 row_mirror row_mask:0xf bank_mask:0xf bound_ctrl:1
	v_add_f32_dpp v26, v26, v26 row_ror:8 row_mask:0xf bank_mask:0xf bound_ctrl:1
	ds_write_b32 v76, v26 offset:2944
	v_pk_fma_f32 v[8:9], v[40:41], v[0:1], v[12:13] op_sel_hi:[0,1,1]
	v_pk_fma_f32 v[10:11], v[40:41], v[0:1], v[14:15] op_sel:[1,0,0]
	v_pk_fma_f32 v[20:21], v[42:43], v[0:1], v[16:17] op_sel_hi:[0,1,1]
	v_pk_fma_f32 v[22:23], v[42:43], v[0:1], v[18:19] op_sel:[1,0,0]
	v_pk_mul_f32 v[4:5], v[8:9], v[44:45] op_sel_hi:[1,0]
	v_pk_mul_f32 v[6:7], v[10:11], v[44:45] op_sel:[0,1]
	v_pk_fma_f32 v[4:5], v[20:21], v[46:47], v[4:5] op_sel_hi:[1,0,1]
	v_pk_fma_f32 v[6:7], v[22:23], v[46:47], v[6:7] op_sel:[0,1,0]
	ds_read_b128 v[28:31], v74 offset:31232
	ds_read_b128 v[32:35], v74 offset:14848
	ds_read_b128 v[36:39], v74 offset:23040
	ds_read_b128 v[40:43], v74 offset:39424
	ds_read_b128 v[44:47], v74 offset:6656
	ds_read_b64 v[48:49], v75 offset:44288
	s_waitcnt lgkmcnt(7)
	v_pk_mul_f32 v[0:1], v[8:9], v[106:107] op_sel_hi:[1,0]
	v_pk_mul_f32 v[2:3], v[10:11], v[106:107] op_sel:[0,1]
	v_pk_fma_f32 v[0:1], v[20:21], v[108:109], v[0:1] op_sel_hi:[1,0,1]
	v_pk_fma_f32 v[2:3], v[22:23], v[108:109], v[2:3] op_sel:[0,1,0]
	v_pk_add_f32 v[4:5], v[4:5], v[6:7]
	v_pk_mul_f32 v[12:13], v[8:9], v[110:111] op_sel_hi:[1,0]
	v_pk_add_f32 v[0:1], v[0:1], v[2:3]
	v_pk_mul_f32 v[14:15], v[10:11], v[110:111] op_sel:[0,1]
	v_cndmask_b32_e32 v24, v4, v5, vcc
	v_cndmask_b32_e32 v25, v5, v4, vcc
	v_pk_mul_f32 v[16:17], v[20:21], v[112:113] op_sel_hi:[1,0]
	v_pk_mul_f32 v[18:19], v[22:23], v[112:113] op_sel:[0,1]
	v_add_f32_dpp v0, v0, v0 quad_perm:[1,0,3,2] row_mask:0xf bank_mask:0xf bound_ctrl:1
	v_add_f32_dpp v1, v1, v1 quad_perm:[1,0,3,2] row_mask:0xf bank_mask:0xf bound_ctrl:1
	v_add_f32_dpp v26, v25, v24 quad_perm:[1,0,3,2] row_mask:0xf bank_mask:0xf bound_ctrl:1
	v_pk_fma_f32 v[12:13], v[114:115], v[126:127], v[12:13] op_sel_hi:[0,1,1]
	v_pk_fma_f32 v[14:15], v[114:115], v[126:127], v[14:15] op_sel:[1,0,0]
	v_add_f32_dpp v0, v0, v0 quad_perm:[2,3,0,1] row_mask:0xf bank_mask:0xf bound_ctrl:1
	v_add_f32_dpp v1, v1, v1 quad_perm:[2,3,0,1] row_mask:0xf bank_mask:0xf bound_ctrl:1
	v_add_f32_dpp v26, v26, v26 quad_perm:[2,3,0,1] row_mask:0xf bank_mask:0xf bound_ctrl:1
	v_pk_fma_f32 v[16:17], v[116:117], v[126:127], v[16:17] op_sel_hi:[0,1,1]
	v_pk_fma_f32 v[18:19], v[116:117], v[126:127], v[18:19] op_sel:[1,0,0]
	v_add_f32_dpp v0, v0, v0 row_half_mirror row_mask:0xf bank_mask:0xf bound_ctrl:1
	v_add_f32_dpp v1, v1, v1 row_half_mirror row_mask:0xf bank_mask:0xf bound_ctrl:1
	v_add_f32_dpp v26, v26, v26 row_ror:4 row_mask:0xf bank_mask:0xf bound_ctrl:1
	s_nop 0
	v_add_f32_dpp v0, v0, v0 row_mirror row_mask:0xf bank_mask:0xf bound_ctrl:1
	v_add_f32_dpp v1, v1, v1 row_mirror row_mask:0xf bank_mask:0xf bound_ctrl:1
	v_add_f32_dpp v26, v26, v26 row_ror:8 row_mask:0xf bank_mask:0xf bound_ctrl:1
	ds_write_b32 v76, v26 offset:3072
	v_pk_fma_f32 v[8:9], v[118:119], v[0:1], v[12:13] op_sel_hi:[0,1,1]
	v_pk_fma_f32 v[10:11], v[118:119], v[0:1], v[14:15] op_sel:[1,0,0]
	v_pk_fma_f32 v[20:21], v[120:121], v[0:1], v[16:17] op_sel_hi:[0,1,1]
	v_pk_fma_f32 v[22:23], v[120:121], v[0:1], v[18:19] op_sel:[1,0,0]
	v_pk_mul_f32 v[4:5], v[8:9], v[122:123] op_sel_hi:[1,0]
	v_pk_mul_f32 v[6:7], v[10:11], v[122:123] op_sel:[0,1]
	v_pk_fma_f32 v[4:5], v[20:21], v[124:125], v[4:5] op_sel_hi:[1,0,1]
	v_pk_fma_f32 v[6:7], v[22:23], v[124:125], v[6:7] op_sel:[0,1,0]
	ds_read_b128 v[106:109], v74 offset:31488
	ds_read_b128 v[110:113], v74 offset:15104
	ds_read_b128 v[114:117], v74 offset:23296
	ds_read_b128 v[118:121], v74 offset:39680
	ds_read_b128 v[122:125], v74 offset:6912
	ds_read_b64 v[126:127], v75 offset:44416
	s_waitcnt lgkmcnt(7)
; __device__ __forceinline__ void rwkv_scan_phase(Frame& F, const bf16* RKV, const float* WAG, const bf16* AGB, const float* k_k, const float* k_a, const float* r_k, bf16* Y, float* BS, float* ST2) {
;     ...
;                 f32x2 r0[4], w0[4], k0[4], a0[4], b0[4], r1[4], w1[4], k1[4], a1[4], b1[4]; float v0, v1;
;                 SC_LOAD(r0, w0, k0, a0, b0, v0, 0);
; #pragma unroll
;                 for (int t = 0; t < SC_T; t += 2) {
;                     SC_LOAD(r1, w1, k1, a1, b1, v1, t + 1);
;                     SC_STEP(r0, w0, k0, a0, b0, v0, t);
;                     if (t + 2 < SC_T) SC_LOAD(r0, w0, k0, a0, b0, v0, t + 2);
;                     SC_STEP(r1, w1, k1, a1, b1, v1, t + 1);
	v_pk_mul_f32 v[0:1], v[8:9], v[28:29] op_sel_hi:[1,0]
	v_pk_mul_f32 v[2:3], v[10:11], v[28:29] op_sel:[0,1]
	v_pk_fma_f32 v[0:1], v[20:21], v[30:31], v[0:1] op_sel_hi:[1,0,1]
	v_pk_fma_f32 v[2:3], v[22:23], v[30:31], v[2:3] op_sel:[0,1,0]
	v_pk_add_f32 v[4:5], v[4:5], v[6:7]
	v_pk_mul_f32 v[12:13], v[8:9], v[32:33] op_sel_hi:[1,0]
	v_pk_add_f32 v[0:1], v[0:1], v[2:3]
	v_pk_mul_f32 v[14:15], v[10:11], v[32:33] op_sel:[0,1]
	v_cndmask_b32_e32 v24, v4, v5, vcc
	v_cndmask_b32_e32 v25, v5, v4, vcc
	v_pk_mul_f32 v[16:17], v[20:21], v[34:35] op_sel_hi:[1,0]
	v_pk_mul_f32 v[18:19], v[22:23], v[34:35] op_sel:[0,1]
	v_add_f32_dpp v0, v0, v0 quad_perm:[1,0,3,2] row_mask:0xf bank_mask:0xf bound_ctrl:1
	v_add_f32_dpp v1, v1, v1 quad_perm:[1,0,3,2] row_mask:0xf bank_mask:0xf bound_ctrl:1
	v_add_f32_dpp v26, v25, v24 quad_perm:[1,0,3,2] row_mask:0xf bank_mask:0xf bound_ctrl:1
	v_pk_fma_f32 v[12:13], v[36:37], v[48:49], v[12:13] op_sel_hi:[0,1,1]
	v_pk_fma_f32 v[14:15], v[36:37], v[48:49], v[14:15] op_sel:[1,0,0]
	v_add_f32_dpp v0, v0, v0 quad_perm:[2,3,0,1] row_mask:0xf bank_mask:0xf bound_ctrl:1
	v_add_f32_dpp v1, v1, v1 quad_perm:[2,3,0,1] row_mask:0xf bank_mask:0xf bound_ctrl:1
	v_add_f32_dpp v26, v26, v26 quad_perm:[2,3,0,1] row_mask:0xf bank_mask:0xf bound_ctrl:1
	v_pk_fma_f32 v[16:17], v[38:39], v[48:49], v[16:17] op_sel_hi:[0,1,1]
	v_pk_fma_f32 v[18:19], v[38:39], v[48:49], v[18:19] op_sel:[1,0,0]
	v_add_f32_dpp v0, v0, v0 row_half_mirror row_mask:0xf bank_mask:0xf bound_ctrl:1
	v_add_f32_dpp v1, v1, v1 row_half_mirror row_mask:0xf bank_mask:0xf bound_ctrl:1
	v_add_f32_dpp v26, v26, v26 row_ror:4 row_mask:0xf bank_mask:0xf bound_ctrl:1
	s_nop 0
	v_add_f32_dpp v0, v0, v0 row_mirror row_mask:0xf bank_mask:0xf bound_ctrl:1
	v_add_f32_dpp v1, v1, v1 row_mirror row_mask:0xf bank_mask:0xf bound_ctrl:1
	v_add_f32_dpp v26, v26, v26 row_ror:8 row_mask:0xf bank_mask:0xf bound_ctrl:1
	ds_write_b32 v76, v26 offset:3200
	v_pk_fma_f32 v[8:9], v[40:41], v[0:1], v[12:13] op_sel_hi:[0,1,1]
	v_pk_fma_f32 v[10:11], v[40:41], v[0:1], v[14:15] op_sel:[1,0,0]
	v_pk_fma_f32 v[20:21], v[42:43], v[0:1], v[16:17] op_sel_hi:[0,1,1]
	v_pk_fma_f32 v[22:23], v[42:43], v[0:1], v[18:19] op_sel:[1,0,0]
	v_pk_mul_f32 v[4:5], v[8:9], v[44:45] op_sel_hi:[1,0]
	v_pk_mul_f32 v[6:7], v[10:11], v[44:45] op_sel:[0,1]
	v_pk_fma_f32 v[4:5], v[20:21], v[46:47], v[4:5] op_sel_hi:[1,0,1]
	v_pk_fma_f32 v[6:7], v[22:23], v[46:47], v[6:7] op_sel:[0,1,0]
	ds_read_b128 v[28:31], v74 offset:31744
	ds_read_b128 v[32:35], v74 offset:15360
	ds_read_b128 v[36:39], v74 offset:23552
	ds_read_b128 v[40:43], v74 offset:39936
	ds_read_b128 v[44:47], v74 offset:7168
	ds_read_b64 v[48:49], v75 offset:44544
	s_waitcnt lgkmcnt(7)
	v_pk_mul_f32 v[0:1], v[8:9], v[106:107] op_sel_hi:[1,0]
	v_pk_mul_f32 v[2:3], v[10:11], v[106:107] op_sel:[0,1]
	v_pk_fma_f32 v[0:1], v[20:21], v[108:109], v[0:1] op_sel_hi:[1,0,1]
	v_pk_fma_f32 v[2:3], v[22:23], v[108:109], v[2:3] op_sel:[0,1,0]
	v_pk_add_f32 v[4:5], v[4:5], v[6:7]
	v_pk_mul_f32 v[12:13], v[8:9], v[110:111] op_sel_hi:[1,0]
	v_pk_add_f32 v[0:1], v[0:1], v[2:3]
	v_pk_mul_f32 v[14:15], v[10:11], v[110:111] op_sel:[0,1]
	v_cndmask_b32_e32 v24, v4, v5, vcc
	v_cndmask_b32_e32 v25, v5, v4, vcc
	v_pk_mul_f32 v[16:17], v[20:21], v[112:113] op_sel_hi:[1,0]
	v_pk_mul_f32 v[18:19], v[22:23], v[112:113] op_sel:[0,1]
	v_add_f32_dpp v0, v0, v0 quad_perm:[1,0,3,2] row_mask:0xf bank_mask:0xf bound_ctrl:1
	v_add_f32_dpp v1, v1, v1 quad_perm:[1,0,3,2] row_mask:0xf bank_mask:0xf bound_ctrl:1
	v_add_f32_dpp v26, v25, v24 quad_perm:[1,0,3,2] row_mask:0xf bank_mask:0xf bound_ctrl:1
	v_pk_fma_f32 v[12:13], v[114:115], v[126:127], v[12:13] op_sel_hi:[0,1,1]
	v_pk_fma_f32 v[14:15], v[114:115], v[126:127], v[14:15] op_sel:[1,0,0]
	v_add_f32_dpp v0, v0, v0 quad_perm:[2,3,0,1] row_mask:0xf bank_mask:0xf bound_ctrl:1
	v_add_f32_dpp v1, v1, v1 quad_perm:[2,3,0,1] row_mask:0xf bank_mask:0xf bound_ctrl:1
	v_add_f32_dpp v26, v26, v26 quad_perm:[2,3,0,1] row_mask:0xf bank_mask:0xf bound_ctrl:1
	v_pk_fma_f32 v[16:17], v[116:117], v[126:127], v[16:17] op_sel_hi:[0,1,1]
	v_pk_fma_f32 v[18:19], v[116:117], v[126:127], v[18:19] op_sel:[1,0,0]
	v_add_f32_dpp v0, v0, v0 row_half_mirror row_mask:0xf bank_mask:0xf bound_ctrl:1
	v_add_f32_dpp v1, v1, v1 row_half_mirror row_mask:0xf bank_mask:0xf bound_ctrl:1
	v_add_f32_dpp v26, v26, v26 row_ror:4 row_mask:0xf bank_mask:0xf bound_ctrl:1
	s_nop 0
	v_add_f32_dpp v0, v0, v0 row_mirror row_mask:0xf bank_mask:0xf bound_ctrl:1
	v_add_f32_dpp v1, v1, v1 row_mirror row_mask:0xf bank_mask:0xf bound_ctrl:1
	v_add_f32_dpp v26, v26, v26 row_ror:8 row_mask:0xf bank_mask:0xf bound_ctrl:1
	ds_write_b32 v76, v26 offset:3328
	v_pk_fma_f32 v[8:9], v[118:119], v[0:1], v[12:13] op_sel_hi:[0,1,1]
	v_pk_fma_f32 v[10:11], v[118:119], v[0:1], v[14:15] op_sel:[1,0,0]
	v_pk_fma_f32 v[20:21], v[120:121], v[0:1], v[16:17] op_sel_hi:[0,1,1]
	v_pk_fma_f32 v[22:23], v[120:121], v[0:1], v[18:19] op_sel:[1,0,0]
	v_pk_mul_f32 v[4:5], v[8:9], v[122:123] op_sel_hi:[1,0]
	v_pk_mul_f32 v[6:7], v[10:11], v[122:123] op_sel:[0,1]
	v_pk_fma_f32 v[4:5], v[20:21], v[124:125], v[4:5] op_sel_hi:[1,0,1]
	v_pk_fma_f32 v[6:7], v[22:23], v[124:125], v[6:7] op_sel:[0,1,0]
	ds_read_b128 v[106:109], v74 offset:32000
	ds_read_b128 v[110:113], v74 offset:15616
	ds_read_b128 v[114:117], v74 offset:23808
	ds_read_b128 v[118:121], v74 offset:40192
	ds_read_b128 v[122:125], v74 offset:7424
	ds_read_b64 v[126:127], v75 offset:44672
	s_waitcnt lgkmcnt(7)
; __device__ __forceinline__ void rwkv_scan_phase(Frame& F, const bf16* RKV, const float* WAG, const bf16* AGB, const float* k_k, const float* k_a, const float* r_k, bf16* Y, float* BS, float* ST2) {
;     ...
;                 f32x2 r0[4], w0[4], k0[4], a0[4], b0[4], r1[4], w1[4], k1[4], a1[4], b1[4]; float v0, v1;
;                 SC_LOAD(r0, w0, k0, a0, b0, v0, 0);
; #pragma unroll
;                 for (int t = 0; t < SC_T; t += 2) {
;                     SC_LOAD(r1, w1, k1, a1, b1, v1, t + 1);
;                     SC_STEP(r0, w0, k0, a0, b0, v0, t);
;                     if (t + 2 < SC_T) SC_LOAD(r0, w0, k0, a0, b0, v0, t + 2);
;                     SC_STEP(r1, w1, k1, a1, b1, v1, t + 1);
	v_pk_mul_f32 v[0:1], v[8:9], v[28:29] op_sel_hi:[1,0]
	v_pk_mul_f32 v[2:3], v[10:11], v[28:29] op_sel:[0,1]
	v_pk_fma_f32 v[0:1], v[20:21], v[30:31], v[0:1] op_sel_hi:[1,0,1]
	v_pk_fma_f32 v[2:3], v[22:23], v[30:31], v[2:3] op_sel:[0,1,0]
	v_pk_add_f32 v[4:5], v[4:5], v[6:7]
	v_pk_mul_f32 v[12:13], v[8:9], v[32:33] op_sel_hi:[1,0]
	v_pk_add_f32 v[0:1], v[0:1], v[2:3]
	v_pk_mul_f32 v[14:15], v[10:11], v[32:33] op_sel:[0,1]
	v_cndmask_b32_e32 v24, v4, v5, vcc
	v_cndmask_b32_e32 v25, v5, v4, vcc
	v_pk_mul_f32 v[16:17], v[20:21], v[34:35] op_sel_hi:[1,0]
	v_pk_mul_f32 v[18:19], v[22:23], v[34:35] op_sel:[0,1]
	v_add_f32_dpp v0, v0, v0 quad_perm:[1,0,3,2] row_mask:0xf bank_mask:0xf bound_ctrl:1
	v_add_f32_dpp v1, v1, v1 quad_perm:[1,0,3,2] row_mask:0xf bank_mask:0xf bound_ctrl:1
	v_add_f32_dpp v26, v25, v24 quad_perm:[1,0,3,2] row_mask:0xf bank_mask:0xf bound_ctrl:1
	v_pk_fma_f32 v[12:13], v[36:37], v[48:49], v[12:13] op_sel_hi:[0,1,1]
	v_pk_fma_f32 v[14:15], v[36:37], v[48:49], v[14:15] op_sel:[1,0,0]
	v_add_f32_dpp v0, v0, v0 quad_perm:[2,3,0,1] row_mask:0xf bank_mask:0xf bound_ctrl:1
	v_add_f32_dpp v1, v1, v1 quad_perm:[2,3,0,1] row_mask:0xf bank_mask:0xf bound_ctrl:1
	v_add_f32_dpp v26, v26, v26 quad_perm:[2,3,0,1] row_mask:0xf bank_mask:0xf bound_ctrl:1
	v_pk_fma_f32 v[16:17], v[38:39], v[48:49], v[16:17] op_sel_hi:[0,1,1]
	v_pk_fma_f32 v[18:19], v[38:39], v[48:49], v[18:19] op_sel:[1,0,0]
	v_add_f32_dpp v0, v0, v0 row_half_mirror row_mask:0xf bank_mask:0xf bound_ctrl:1
	v_add_f32_dpp v1, v1, v1 row_half_mirror row_mask:0xf bank_mask:0xf bound_ctrl:1
	v_add_f32_dpp v26, v26, v26 row_ror:4 row_mask:0xf bank_mask:0xf bound_ctrl:1
	s_nop 0
	v_add_f32_dpp v0, v0, v0 row_mirror row_mask:0xf bank_mask:0xf bound_ctrl:1
	v_add_f32_dpp v1, v1, v1 row_mirror row_mask:0xf bank_mask:0xf bound_ctrl:1
	v_add_f32_dpp v26, v26, v26 row_ror:8 row_mask:0xf bank_mask:0xf bound_ctrl:1
	ds_write_b32 v76, v26 offset:3456
	v_pk_fma_f32 v[8:9], v[40:41], v[0:1], v[12:13] op_sel_hi:[0,1,1]
	v_pk_fma_f32 v[10:11], v[40:41], v[0:1], v[14:15] op_sel:[1,0,0]
	v_pk_fma_f32 v[20:21], v[42:43], v[0:1], v[16:17] op_sel_hi:[0,1,1]
	v_pk_fma_f32 v[22:23], v[42:43], v[0:1], v[18:19] op_sel:[1,0,0]
	v_pk_mul_f32 v[4:5], v[8:9], v[44:45] op_sel_hi:[1,0]
	v_pk_mul_f32 v[6:7], v[10:11], v[44:45] op_sel:[0,1]
	v_pk_fma_f32 v[4:5], v[20:21], v[46:47], v[4:5] op_sel_hi:[1,0,1]
	v_pk_fma_f32 v[6:7], v[22:23], v[46:47], v[6:7] op_sel:[0,1,0]
	ds_read_b128 v[28:31], v74 offset:32256
	ds_read_b128 v[32:35], v74 offset:15872
	ds_read_b128 v[36:39], v74 offset:24064
	ds_read_b128 v[40:43], v74 offset:40448
	ds_read_b128 v[44:47], v74 offset:7680
	ds_read_b64 v[48:49], v75 offset:44800
	s_waitcnt lgkmcnt(7)
	v_pk_mul_f32 v[0:1], v[8:9], v[106:107] op_sel_hi:[1,0]
	v_pk_mul_f32 v[2:3], v[10:11], v[106:107] op_sel:[0,1]
	v_pk_fma_f32 v[0:1], v[20:21], v[108:109], v[0:1] op_sel_hi:[1,0,1]
	v_pk_fma_f32 v[2:3], v[22:23], v[108:109], v[2:3] op_sel:[0,1,0]
	v_pk_add_f32 v[4:5], v[4:5], v[6:7]
	v_pk_mul_f32 v[12:13], v[8:9], v[110:111] op_sel_hi:[1,0]
	v_pk_add_f32 v[0:1], v[0:1], v[2:3]
	v_pk_mul_f32 v[14:15], v[10:11], v[110:111] op_sel:[0,1]
	v_cndmask_b32_e32 v24, v4, v5, vcc
	v_cndmask_b32_e32 v25, v5, v4, vcc
	v_pk_mul_f32 v[16:17], v[20:21], v[112:113] op_sel_hi:[1,0]
	v_pk_mul_f32 v[18:19], v[22:23], v[112:113] op_sel:[0,1]
	v_add_f32_dpp v0, v0, v0 quad_perm:[1,0,3,2] row_mask:0xf bank_mask:0xf bound_ctrl:1
	v_add_f32_dpp v1, v1, v1 quad_perm:[1,0,3,2] row_mask:0xf bank_mask:0xf bound_ctrl:1
	v_add_f32_dpp v26, v25, v24 quad_perm:[1,0,3,2] row_mask:0xf bank_mask:0xf bound_ctrl:1
	v_pk_fma_f32 v[12:13], v[114:115], v[126:127], v[12:13] op_sel_hi:[0,1,1]
	v_pk_fma_f32 v[14:15], v[114:115], v[126:127], v[14:15] op_sel:[1,0,0]
	v_add_f32_dpp v0, v0, v0 quad_perm:[2,3,0,1] row_mask:0xf bank_mask:0xf bound_ctrl:1
	v_add_f32_dpp v1, v1, v1 quad_perm:[2,3,0,1] row_mask:0xf bank_mask:0xf bound_ctrl:1
	v_add_f32_dpp v26, v26, v26 quad_perm:[2,3,0,1] row_mask:0xf bank_mask:0xf bound_ctrl:1
	v_pk_fma_f32 v[16:17], v[116:117], v[126:127], v[16:17] op_sel_hi:[0,1,1]
	v_pk_fma_f32 v[18:19], v[116:117], v[126:127], v[18:19] op_sel:[1,0,0]
	v_add_f32_dpp v0, v0, v0 row_half_mirror row_mask:0xf bank_mask:0xf bound_ctrl:1
	v_add_f32_dpp v1, v1, v1 row_half_mirror row_mask:0xf bank_mask:0xf bound_ctrl:1
	v_add_f32_dpp v26, v26, v26 row_ror:4 row_mask:0xf bank_mask:0xf bound_ctrl:1
	s_nop 0
	v_add_f32_dpp v0, v0, v0 row_mirror row_mask:0xf bank_mask:0xf bound_ctrl:1
	v_add_f32_dpp v1, v1, v1 row_mirror row_mask:0xf bank_mask:0xf bound_ctrl:1
	v_add_f32_dpp v26, v26, v26 row_ror:8 row_mask:0xf bank_mask:0xf bound_ctrl:1
	ds_write_b32 v76, v26 offset:3584
	v_pk_fma_f32 v[8:9], v[118:119], v[0:1], v[12:13] op_sel_hi:[0,1,1]
	v_pk_fma_f32 v[10:11], v[118:119], v[0:1], v[14:15] op_sel:[1,0,0]
	v_pk_fma_f32 v[20:21], v[120:121], v[0:1], v[16:17] op_sel_hi:[0,1,1]
	v_pk_fma_f32 v[22:23], v[120:121], v[0:1], v[18:19] op_sel:[1,0,0]
	v_pk_mul_f32 v[4:5], v[8:9], v[122:123] op_sel_hi:[1,0]
	v_pk_mul_f32 v[6:7], v[10:11], v[122:123] op_sel:[0,1]
	v_pk_fma_f32 v[4:5], v[20:21], v[124:125], v[4:5] op_sel_hi:[1,0,1]
	v_pk_fma_f32 v[6:7], v[22:23], v[124:125], v[6:7] op_sel:[0,1,0]
	ds_read_b128 v[106:109], v74 offset:32512
	ds_read_b128 v[110:113], v74 offset:16128
	ds_read_b128 v[114:117], v74 offset:24320
	ds_read_b128 v[118:121], v74 offset:40704
	ds_read_b128 v[122:125], v74 offset:7936
	ds_read_b64 v[126:127], v75 offset:44928
	s_waitcnt lgkmcnt(7)
; __device__ __forceinline__ void rwkv_scan_phase(Frame& F, const bf16* RKV, const float* WAG, const bf16* AGB, const float* k_k, const float* k_a, const float* r_k, bf16* Y, float* BS, float* ST2) {
;     ...
;                 f32x2 r0[4], w0[4], k0[4], a0[4], b0[4], r1[4], w1[4], k1[4], a1[4], b1[4]; float v0, v1;
;                 SC_LOAD(r0, w0, k0, a0, b0, v0, 0);
; #pragma unroll
;                 for (int t = 0; t < SC_T; t += 2) {
;                     SC_LOAD(r1, w1, k1, a1, b1, v1, t + 1);
;                     SC_STEP(r0, w0, k0, a0, b0, v0, t);
;                     if (t + 2 < SC_T) SC_LOAD(r0, w0, k0, a0, b0, v0, t + 2);
;                     SC_STEP(r1, w1, k1, a1, b1, v1, t + 1);
	v_pk_mul_f32 v[0:1], v[8:9], v[28:29] op_sel_hi:[1,0]
	v_pk_mul_f32 v[2:3], v[10:11], v[28:29] op_sel:[0,1]
	v_pk_fma_f32 v[0:1], v[20:21], v[30:31], v[0:1] op_sel_hi:[1,0,1]
	v_pk_fma_f32 v[2:3], v[22:23], v[30:31], v[2:3] op_sel:[0,1,0]
	v_pk_add_f32 v[4:5], v[4:5], v[6:7]
	v_pk_mul_f32 v[12:13], v[8:9], v[32:33] op_sel_hi:[1,0]
	v_pk_add_f32 v[0:1], v[0:1], v[2:3]
	v_pk_mul_f32 v[14:15], v[10:11], v[32:33] op_sel:[0,1]
	v_cndmask_b32_e32 v24, v4, v5, vcc
	v_cndmask_b32_e32 v25, v5, v4, vcc
	v_pk_mul_f32 v[16:17], v[20:21], v[34:35] op_sel_hi:[1,0]
	v_pk_mul_f32 v[18:19], v[22:23], v[34:35] op_sel:[0,1]
	v_add_f32_dpp v0, v0, v0 quad_perm:[1,0,3,2] row_mask:0xf bank_mask:0xf bound_ctrl:1
	v_add_f32_dpp v1, v1, v1 quad_perm:[1,0,3,2] row_mask:0xf bank_mask:0xf bound_ctrl:1
	v_add_f32_dpp v26, v25, v24 quad_perm:[1,0,3,2] row_mask:0xf bank_mask:0xf bound_ctrl:1
	v_pk_fma_f32 v[12:13], v[36:37], v[48:49], v[12:13] op_sel_hi:[0,1,1]
	v_pk_fma_f32 v[14:15], v[36:37], v[48:49], v[14:15] op_sel:[1,0,0]
	v_add_f32_dpp v0, v0, v0 quad_perm:[2,3,0,1] row_mask:0xf bank_mask:0xf bound_ctrl:1
	v_add_f32_dpp v1, v1, v1 quad_perm:[2,3,0,1] row_mask:0xf bank_mask:0xf bound_ctrl:1
	v_add_f32_dpp v26, v26, v26 quad_perm:[2,3,0,1] row_mask:0xf bank_mask:0xf bound_ctrl:1
	v_pk_fma_f32 v[16:17], v[38:39], v[48:49], v[16:17] op_sel_hi:[0,1,1]
	v_pk_fma_f32 v[18:19], v[38:39], v[48:49], v[18:19] op_sel:[1,0,0]
	v_add_f32_dpp v0, v0, v0 row_half_mirror row_mask:0xf bank_mask:0xf bound_ctrl:1
	v_add_f32_dpp v1, v1, v1 row_half_mirror row_mask:0xf bank_mask:0xf bound_ctrl:1
	v_add_f32_dpp v26, v26, v26 row_ror:4 row_mask:0xf bank_mask:0xf bound_ctrl:1
	s_nop 0
	v_add_f32_dpp v0, v0, v0 row_mirror row_mask:0xf bank_mask:0xf bound_ctrl:1
	v_add_f32_dpp v1, v1, v1 row_mirror row_mask:0xf bank_mask:0xf bound_ctrl:1
	v_add_f32_dpp v26, v26, v26 row_ror:8 row_mask:0xf bank_mask:0xf bound_ctrl:1
	ds_write_b32 v76, v26 offset:3712
	v_pk_fma_f32 v[8:9], v[40:41], v[0:1], v[12:13] op_sel_hi:[0,1,1]
	v_pk_fma_f32 v[10:11], v[40:41], v[0:1], v[14:15] op_sel:[1,0,0]
	v_pk_fma_f32 v[20:21], v[42:43], v[0:1], v[16:17] op_sel_hi:[0,1,1]
	v_pk_fma_f32 v[22:23], v[42:43], v[0:1], v[18:19] op_sel:[1,0,0]
	v_pk_mul_f32 v[4:5], v[8:9], v[44:45] op_sel_hi:[1,0]
	v_pk_mul_f32 v[6:7], v[10:11], v[44:45] op_sel:[0,1]
	v_pk_fma_f32 v[4:5], v[20:21], v[46:47], v[4:5] op_sel_hi:[1,0,1]
	v_pk_fma_f32 v[6:7], v[22:23], v[46:47], v[6:7] op_sel:[0,1,0]
	s_waitcnt lgkmcnt(1)
	v_pk_mul_f32 v[0:1], v[8:9], v[106:107] op_sel_hi:[1,0]
	v_pk_mul_f32 v[2:3], v[10:11], v[106:107] op_sel:[0,1]
	v_pk_fma_f32 v[0:1], v[20:21], v[108:109], v[0:1] op_sel_hi:[1,0,1]
	v_pk_fma_f32 v[2:3], v[22:23], v[108:109], v[2:3] op_sel:[0,1,0]
	v_pk_add_f32 v[4:5], v[4:5], v[6:7]
	v_pk_mul_f32 v[12:13], v[8:9], v[110:111] op_sel_hi:[1,0]
	v_pk_add_f32 v[0:1], v[0:1], v[2:3]
	v_pk_mul_f32 v[14:15], v[10:11], v[110:111] op_sel:[0,1]
	v_cndmask_b32_e32 v24, v4, v5, vcc
	v_cndmask_b32_e32 v25, v5, v4, vcc
	v_pk_mul_f32 v[16:17], v[20:21], v[112:113] op_sel_hi:[1,0]
	v_pk_mul_f32 v[18:19], v[22:23], v[112:113] op_sel:[0,1]
	v_add_f32_dpp v0, v0, v0 quad_perm:[1,0,3,2] row_mask:0xf bank_mask:0xf bound_ctrl:1
	v_add_f32_dpp v1, v1, v1 quad_perm:[1,0,3,2] row_mask:0xf bank_mask:0xf bound_ctrl:1
	v_add_f32_dpp v26, v25, v24 quad_perm:[1,0,3,2] row_mask:0xf bank_mask:0xf bound_ctrl:1
	v_pk_fma_f32 v[12:13], v[114:115], v[126:127], v[12:13] op_sel_hi:[0,1,1]
	v_pk_fma_f32 v[14:15], v[114:115], v[126:127], v[14:15] op_sel:[1,0,0]
	v_add_f32_dpp v0, v0, v0 quad_perm:[2,3,0,1] row_mask:0xf bank_mask:0xf bound_ctrl:1
	v_add_f32_dpp v1, v1, v1 quad_perm:[2,3,0,1] row_mask:0xf bank_mask:0xf bound_ctrl:1
	v_add_f32_dpp v26, v26, v26 quad_perm:[2,3,0,1] row_mask:0xf bank_mask:0xf bound_ctrl:1
	v_pk_fma_f32 v[16:17], v[116:117], v[126:127], v[16:17] op_sel_hi:[0,1,1]
	v_pk_fma_f32 v[18:19], v[116:117], v[126:127], v[18:19] op_sel:[1,0,0]
	v_add_f32_dpp v0, v0, v0 row_half_mirror row_mask:0xf bank_mask:0xf bound_ctrl:1
	v_add_f32_dpp v1, v1, v1 row_half_mirror row_mask:0xf bank_mask:0xf bound_ctrl:1
	v_add_f32_dpp v26, v26, v26 row_ror:4 row_mask:0xf bank_mask:0xf bound_ctrl:1
	s_nop 0
	v_add_f32_dpp v0, v0, v0 row_mirror row_mask:0xf bank_mask:0xf bound_ctrl:1
	v_add_f32_dpp v1, v1, v1 row_mirror row_mask:0xf bank_mask:0xf bound_ctrl:1
	v_add_f32_dpp v26, v26, v26 row_ror:8 row_mask:0xf bank_mask:0xf bound_ctrl:1
	ds_write_b32 v76, v26 offset:3840
	v_pk_fma_f32 v[8:9], v[118:119], v[0:1], v[12:13] op_sel_hi:[0,1,1]
	v_pk_fma_f32 v[10:11], v[118:119], v[0:1], v[14:15] op_sel:[1,0,0]
	v_pk_fma_f32 v[20:21], v[120:121], v[0:1], v[16:17] op_sel_hi:[0,1,1]
	v_pk_fma_f32 v[22:23], v[120:121], v[0:1], v[18:19] op_sel:[1,0,0]
	v_pk_mul_f32 v[4:5], v[8:9], v[122:123] op_sel_hi:[1,0]
	v_pk_mul_f32 v[6:7], v[10:11], v[122:123] op_sel:[0,1]
	v_pk_fma_f32 v[4:5], v[20:21], v[124:125], v[4:5] op_sel_hi:[1,0,1]
	v_pk_fma_f32 v[6:7], v[22:23], v[124:125], v[6:7] op_sel:[0,1,0]
	v_pk_add_f32 v[4:5], v[4:5], v[6:7]
	v_cndmask_b32_e32 v24, v4, v5, vcc
	v_cndmask_b32_e32 v25, v5, v4, vcc
	s_nop 1
	v_add_f32_dpp v26, v25, v24 quad_perm:[1,0,3,2] row_mask:0xf bank_mask:0xf bound_ctrl:1
	s_nop 1
	v_add_f32_dpp v26, v26, v26 quad_perm:[2,3,0,1] row_mask:0xf bank_mask:0xf bound_ctrl:1
	s_nop 1
	v_add_f32_dpp v26, v26, v26 row_ror:4 row_mask:0xf bank_mask:0xf bound_ctrl:1
	s_nop 1
	v_add_f32_dpp v26, v26, v26 row_ror:8 row_mask:0xf bank_mask:0xf bound_ctrl:1
	ds_write_b32 v76, v26 offset:3968
	s_mov_b64 s[6:7], 0
	s_branch .LBB0_1691

; #define GAS __attribute__((address_space(1)))
; __device__ __forceinline__ void rwkv_scan_phase(Frame& F, const bf16* RKV, const float* WAG, const bf16* AGB, const float* k_k, const float* k_a, const float* r_k, bf16* Y, float* BS, float* ST2) {
;     ...
;         if (wave >= 4) {
;             const int st = tid - 256, ts = st >> 4, c4 = st & 15;
;             const f32x4 kkc = *(const GAS f32x4*)(k_k + h * 64 + 4 * c4), kac = *(const GAS f32x4*)(k_a + h * 64 + 4 * c4), rkc = *(const GAS f32x4*)(r_k + h * 64 + 4 * c4);
;     ...
;             constexpr int NCH = SEQ / SC_T;
;             v2u RAh[2][4], RBh[2][4]; f32x4 RAw[2], RBw[2];
;             ST_LOAD(RA, 0); ST_LOAD(RB, 1);
;             ST_PROC(RA, 0);
.LBB0_1758:
	s_mul_i32 s70, s52, 3
	s_mul_i32 s65, s96, 3
	s_add_u32 s65, s65, s80
	s_sub_u32 s65, s65, 5
	s_sub_u32 s65, s65, s70
	s_mov_b32 s66, 1
	s_mov_b32 s67, 0
	s_mov_b32 s68, 0
	s_mov_b32 s69, 0
	s_mov_b32 s71, 0
	s_ashr_i32 s48, s55, 6
	s_bfe_u32 s6, s55, 0x50001
	s_ashr_i32 s49, s48, 31
	s_lshl_b64 s[44:45], s[48:49], 22
	s_lshl_b32 s0, s6, 6
	s_or_b32 s44, s44, s0
	s_waitcnt vmcnt(5)
	v_mov_b32_e32 v61, s45
	v_or_b32_e32 v60, s44, v90
	v_lshl_add_u64 v[12:13], v[60:61], 0, v[108:109]
	v_lshlrev_b64 v[14:15], 1, v[12:13]
	s_lshl_b32 s0, s6, 8
	v_lshl_add_u64 v[16:17], s[12:13], 0, v[14:15]
	v_lshl_add_u64 v[0:1], v[94:95], 0, s[0:1]
	v_lshl_add_u64 v[4:5], v[96:97], 0, s[0:1]
	v_lshl_add_u64 v[8:9], v[98:99], 0, s[0:1]
	global_load_dwordx2 v[30:31], v[16:17], off
	v_lshl_add_u64 v[16:17], s[24:25], 0, v[14:15]
	v_lshl_add_u64 v[18:19], s[26:27], 0, v[14:15]
	v_lshl_add_u64 v[12:13], v[12:13], 2, s[14:15]
	global_load_dwordx4 v[0:3], v[0:1], off
	v_lshl_add_u64 v[14:15], s[16:17], 0, v[14:15]
	global_load_dwordx4 v[4:7], v[4:5], off
	s_and_b32 s0, s55, 1
	global_load_dwordx4 v[8:11], v[8:9], off
	s_nop 0
	global_load_dwordx2 v[32:33], v[16:17], off
	global_load_dwordx2 v[42:43], v[18:19], off
	s_nop 0
	global_load_dwordx4 v[16:19], v[12:13], off
	global_load_dwordx2 v[34:35], v[14:15], off
	v_lshl_add_u64 v[12:13], v[60:61], 0, v[112:113]
	v_lshlrev_b64 v[14:15], 1, v[12:13]
	v_lshl_add_u64 v[20:21], s[12:13], 0, v[14:15]
	global_load_dwordx2 v[38:39], v[20:21], off
	v_lshl_add_u64 v[20:21], s[24:25], 0, v[14:15]
	v_lshl_add_u64 v[22:23], s[26:27], 0, v[14:15]
	global_load_dwordx2 v[40:41], v[20:21], off
	global_load_dwordx2 v[36:37], v[22:23], off
	v_lshl_add_u64 v[12:13], v[12:13], 2, s[14:15]
	v_lshl_add_u64 v[20:21], s[16:17], 0, v[14:15]
	global_load_dwordx4 v[12:15], v[12:13], off
	s_nop 0
	global_load_dwordx2 v[44:45], v[20:21], off
	v_lshl_add_u64 v[20:21], v[60:61], 0, v[114:115]
	v_lshlrev_b64 v[22:23], 1, v[20:21]
	s_waitcnt vmcnt(15)
	v_lshl_add_u64 v[24:25], s[12:13], 0, v[22:23]
	global_load_dwordx2 v[64:65], v[24:25], off
	v_lshl_add_u64 v[24:25], s[24:25], 0, v[22:23]
	v_lshl_add_u64 v[26:27], s[26:27], 0, v[22:23]
	v_lshl_add_u64 v[20:21], v[20:21], 2, s[14:15]
	global_load_dwordx2 v[66:67], v[24:25], off
	global_load_dwordx2 v[58:59], v[26:27], off
	v_lshl_add_u64 v[22:23], s[16:17], 0, v[22:23]
	global_load_dwordx4 v[24:27], v[20:21], off
	global_load_dwordx2 v[68:69], v[22:23], off
	v_lshl_add_u64 v[20:21], v[60:61], 0, v[116:117]
	v_lshlrev_b64 v[22:23], 1, v[20:21]
	v_lshl_add_u64 v[28:29], s[12:13], 0, v[22:23]
	global_load_dwordx2 v[54:55], v[28:29], off
	v_lshl_add_u64 v[28:29], s[24:25], 0, v[22:23]
	v_lshl_add_u64 v[20:21], v[20:21], 2, s[14:15]
	v_lshl_add_u64 v[46:47], s[26:27], 0, v[22:23]
	global_load_dwordx2 v[56:57], v[28:29], off
	global_load_dwordx2 v[52:53], v[46:47], off
	v_lshl_add_u64 v[28:29], s[16:17], 0, v[22:23]
	global_load_dwordx4 v[20:23], v[20:21], off
	s_nop 0
	global_load_dwordx2 v[62:63], v[28:29], off
	v_or_b32_e32 v28, s0, v146
	s_lshl_b32 s33, s6, 2
	v_cmp_eq_u32_e64 s[6:7], 0, v28
	s_lshl_b64 s[46:47], s[48:49], 11
	s_add_u32 s50, s3, s33
	s_addc_u32 s51, s34, 0
	s_waitcnt vmcnt(22)
	v_lshlrev_b32_e32 v28, 16, v30
	v_and_b32_e32 v29, 0xffff0000, v30
	v_lshlrev_b32_e32 v30, 16, v31
	v_and_b32_e32 v31, 0xffff0000, v31
	s_waitcnt vmcnt(18)
	v_lshlrev_b32_e32 v74, 16, v32
	v_and_b32_e32 v75, 0xffff0000, v32
	s_waitcnt vmcnt(15)
	v_lshlrev_b32_e32 v46, 16, v34
	v_and_b32_e32 v47, 0xffff0000, v34
	v_lshlrev_b32_e32 v48, 16, v35
	v_and_b32_e32 v49, 0xffff0000, v35
	v_lshlrev_b32_e32 v32, 16, v33
	v_and_b32_e32 v33, 0xffff0000, v33
	v_pk_add_f32 v[34:35], v[48:49], -1.0 op_sel_hi:[1,0]
	v_pk_add_f32 v[72:73], v[46:47], -1.0 op_sel_hi:[1,0]
	v_pk_mul_f32 v[50:51], v[2:3], v[32:33]
	v_pk_mul_f32 v[70:71], v[0:1], v[74:75]
	v_pk_fma_f32 v[80:81], v[4:5], v[72:73], 1.0 op_sel_hi:[1,1,0]
	v_pk_fma_f32 v[34:35], v[6:7], v[34:35], 1.0 op_sel_hi:[1,1,0]
	v_pk_mul_f32 v[76:77], v[50:51], v[50:51]
	v_pk_mul_f32 v[78:79], v[70:71], v[70:71]
	v_pk_mul_f32 v[34:35], v[34:35], v[32:33]
	v_pk_mul_f32 v[32:33], v[80:81], v[74:75]
	v_pk_mov_b32 v[72:73], v[78:79], v[76:77] op_sel:[1,0]
	v_mov_b32_e32 v79, v77
	v_pk_mul_f32 v[74:75], v[32:33], v[28:29]
	v_pk_mul_f32 v[76:77], v[34:35], v[30:31]
	v_pk_mul_f32 v[74:75], v[8:9], v[74:75]
	v_pk_mul_f32 v[76:77], v[10:11], v[76:77]
	v_pk_add_f32 v[72:73], v[72:73], v[78:79]
	v_add_f32_e32 v74, v74, v75
	v_add_f32_e32 v75, v76, v77
	v_add_f32_e32 v72, v72, v73
	v_add_f32_e32 v74, v74, v75
	s_nop 0
	v_add_f32_dpp v72, v72, v72 quad_perm:[1,0,3,2] row_mask:0xf bank_mask:0xf bound_ctrl:1
	v_add_f32_dpp v74, v74, v74 quad_perm:[1,0,3,2] row_mask:0xf bank_mask:0xf bound_ctrl:1
	s_nop 0
	v_add_f32_dpp v72, v72, v72 quad_perm:[2,3,0,1] row_mask:0xf bank_mask:0xf bound_ctrl:1
	v_add_f32_dpp v74, v74, v74 quad_perm:[2,3,0,1] row_mask:0xf bank_mask:0xf bound_ctrl:1
	s_nop 0
	v_add_f32_dpp v72, v72, v72 row_half_mirror row_mask:0xf bank_mask:0xf bound_ctrl:1
	v_add_f32_dpp v74, v74, v74 row_half_mirror row_mask:0xf bank_mask:0xf bound_ctrl:1
	s_nop 0
	v_mov_b32_dpp v73, v72 row_mirror row_mask:0xf bank_mask:0xf bound_ctrl:1
	v_mov_b32_dpp v75, v74 row_mirror row_mask:0xf bank_mask:0xf bound_ctrl:1
	s_and_saveexec_b64 s[8:9], s[6:7]
	s_cbranch_execz .LBB0_1760
	v_lshl_add_u64 v[76:77], s[46:47], 0, v[88:89]
	v_lshlrev_b64 v[76:77], 7, v[76:77]
	v_lshl_add_u64 v[76:77], s[50:51], 0, v[76:77]
	v_add_f32_e32 v74, v74, v75
	global_store_dword v[76:77], v74, off

; #define GAS __attribute__((address_space(1)))
; #define LAS __attribute__((address_space(3)))
; __device__ __forceinline__ void conv_proc(f32x4 (&v)[2][8], const float* gain, int K, int Kp, int Np, int ilv, bf16* WT, LAS float* scr, int item, int lane) {
;     const int nblk = Np / 64, kb = item / nblk, nb = item % nblk, k0 = 64 * kb, n0 = 64 * nb;
;     const int d0 = ilv ? (((n0 % ilv) >> 7) * 256 + (n0 / ilv) * 128 + ((n0 % ilv) & 127)) : n0;
;     const int kr = lane >> 3, n4 = lane & 7;
;     if (gain) {
; #pragma unroll
;         for (int i = 0; i < 8; ++i) { const int k = k0 + 8 * i + kr; const float g = k < K ? gain[k] : 0.f; v[0][i] *= g; v[1][i] *= g; } }
;     const int c = lane & 7;
; #pragma unroll
;     for (int hf = 0; hf < 2; ++hf) {
; #pragma unroll
;         for (int i = 0; i < 8; ++i) { LAS float* d = scr + (8 * i + kr) * 33 + 4 * n4; d[0] = v[hf][i][0]; d[1] = v[hf][i][1]; d[2] = v[hf][i][2]; d[3] = v[hf][i][3]; }
;         LDS_WAIT(); asm volatile("" ::: "memory");
; #pragma unroll
;         for (int j = 0; j < 4; ++j) { const int nn = (lane >> 3) + 8 * j; const LAS float* sp = scr + (8 * c) * 33 + nn;
;             v4u o; o.x = pk2(sp[0 * 33], sp[1 * 33]); o.y = pk2(sp[2 * 33], sp[3 * 33]); o.z = pk2(sp[4 * 33], sp[5 * 33]); o.w = pk2(sp[6 * 33], sp[7 * 33]);
;             __builtin_nontemporal_store(o, (GAS v4u*)(WT + (size_t)(d0 + 32 * hf + nn) * Kp + k0 + 8 * c)); }
;         LDS_WAIT(); asm volatile("" ::: "memory");
;     }
; }
; __device__ __forceinline__ void convert_mats(Frame& F, int m_lo, int m_hi, int gw, int NGW) {
;     LAS float* scr = (LAS float*)(F.lds + F.wave * 16384);
;     int it = gw, base = 0;
;     for (int mi = m_lo; mi < m_hi; ++mi) {
;         const MatI mt = kMats[mi]; const int cnt = (mt.Kp / 64) * (mt.Np / 64);
;         const float* src = in_ptr(F, mt.in_idx) + mt.src_off; const float* gain = mt.gain_idx >= 0 ? in_ptr(F, mt.gain_idx) + mt.gain_off : nullptr; bf16* dst = (bf16*)((unsigned char*)in_ptr(F, T_WS) + mt.dst_off);
;         while (it < base + cnt) {
;             f32x4 va[2][8], vb[2][8];
;             const int lim = base + cnt, i1 = it + NGW;
;             conv_load(src, mt.K, mt.N, mt.Np, it - base, F.lane, va);
;             if (i1 < lim) conv_load(src, mt.K, mt.N, mt.Np, i1 - base, F.lane, vb);
;             conv_proc(va, gain, mt.K, mt.Kp, mt.Np, mt.ilv, dst, scr, it - base, F.lane);
.LBB0_1787:
	s_cmp_lt_u32 s80, 5
	s_cbranch_scc1 .Lcsa_end
	s_cmp_eq_u32 s69, 0
	s_cbranch_scc1 .Lcsa_adv
	v_mbcnt_lo_u32_b32 v243, -1, 0
	v_mbcnt_hi_u32_b32 v243, -1, v243
	s_sub_u32 s92, s80, 5
	s_mul_i32 s92, s92, 0x2100
	s_add_u32 s92, s92, 0x19200
	v_lshrrev_b32_e32 v241, 3, v243
	v_and_b32_e32 v242, 7, v243
	v_mul_u32_u24_e32 v243, 132, v241
	v_lshl_add_u32 v243, v242, 4, v243
	v_add_u32_e32 v238, s92, v243
	v_mul_u32_u24_e32 v243, 0x420, v242
	v_lshl_add_u32 v243, v241, 2, v243
	v_add_u32_e32 v239, s92, v243
	v_mul_lo_u32 v243, v241, s81
	v_lshl_add_u32 v240, v242, 4, v243
	s_waitcnt vmcnt(0)
	s_cmp_eq_u32 s71, 0
	s_cbranch_scc1 .Lcsa_nogain
	v_pk_mul_f32 v[188:189], v[188:189], v[220:221] op_sel_hi:[1,0]
	v_pk_mul_f32 v[190:191], v[190:191], v[220:221] op_sel_hi:[1,0]
	v_pk_mul_f32 v[192:193], v[192:193], v[220:221] op_sel:[0,1] op_sel_hi:[1,1]
	v_pk_mul_f32 v[194:195], v[194:195], v[220:221] op_sel:[0,1] op_sel_hi:[1,1]
	v_pk_mul_f32 v[196:197], v[196:197], v[222:223] op_sel_hi:[1,0]
	v_pk_mul_f32 v[198:199], v[198:199], v[222:223] op_sel_hi:[1,0]
	v_pk_mul_f32 v[200:201], v[200:201], v[222:223] op_sel:[0,1] op_sel_hi:[1,1]
	v_pk_mul_f32 v[202:203], v[202:203], v[222:223] op_sel:[0,1] op_sel_hi:[1,1]
	v_pk_mul_f32 v[204:205], v[204:205], v[224:225] op_sel_hi:[1,0]
	v_pk_mul_f32 v[206:207], v[206:207], v[224:225] op_sel_hi:[1,0]
	v_pk_mul_f32 v[208:209], v[208:209], v[224:225] op_sel:[0,1] op_sel_hi:[1,1]
	v_pk_mul_f32 v[210:211], v[210:211], v[224:225] op_sel:[0,1] op_sel_hi:[1,1]
	v_pk_mul_f32 v[212:213], v[212:213], v[226:227] op_sel_hi:[1,0]
	v_pk_mul_f32 v[214:215], v[214:215], v[226:227] op_sel_hi:[1,0]
	v_pk_mul_f32 v[216:217], v[216:217], v[226:227] op_sel:[0,1] op_sel_hi:[1,1]
	v_pk_mul_f32 v[218:219], v[218:219], v[226:227] op_sel:[0,1] op_sel_hi:[1,1]
.Lcsa_nogain:
	ds_write_b32 v238, v188 offset:0
	ds_write_b32 v238, v189 offset:4
	ds_write_b32 v238, v190 offset:8
	ds_write_b32 v238, v191 offset:12
	ds_write_b32 v238, v192 offset:1056
	ds_write_b32 v238, v193 offset:1060
	ds_write_b32 v238, v194 offset:1064
	ds_write_b32 v238, v195 offset:1068
	ds_write_b32 v238, v196 offset:2112
	ds_write_b32 v238, v197 offset:2116
	ds_write_b32 v238, v198 offset:2120
	ds_write_b32 v238, v199 offset:2124
	ds_write_b32 v238, v200 offset:3168
	ds_write_b32 v238, v201 offset:3172
	ds_write_b32 v238, v202 offset:3176
	ds_write_b32 v238, v203 offset:3180
	ds_write_b32 v238, v204 offset:4224
	ds_write_b32 v238, v205 offset:4228
	ds_write_b32 v238, v206 offset:4232
	ds_write_b32 v238, v207 offset:4236
	ds_write_b32 v238, v208 offset:5280
	ds_write_b32 v238, v209 offset:5284
	ds_write_b32 v238, v210 offset:5288
	ds_write_b32 v238, v211 offset:5292
	ds_write_b32 v238, v212 offset:6336
	ds_write_b32 v238, v213 offset:6340
	ds_write_b32 v238, v214 offset:6344
	ds_write_b32 v238, v215 offset:6348
	ds_write_b32 v238, v216 offset:7392
	ds_write_b32 v238, v217 offset:7396
	ds_write_b32 v238, v218 offset:7400
	ds_write_b32 v238, v219 offset:7404
	s_waitcnt lgkmcnt(0)
	ds_read2_b32 v[148:149], v239 offset0:0 offset1:33
	ds_read2_b32 v[150:151], v239 offset0:66 offset1:99
	ds_read2_b32 v[152:153], v239 offset0:132 offset1:165
	ds_read2_b32 v[154:155], v239 offset0:198 offset1:231
	ds_read2_b32 v[156:157], v239 offset0:8 offset1:41
	ds_read2_b32 v[158:159], v239 offset0:74 offset1:107
	ds_read2_b32 v[160:161], v239 offset0:140 offset1:173
	ds_read2_b32 v[162:163], v239 offset0:206 offset1:239
	s_waitcnt lgkmcnt(4)
	v_cvt_pk_bf16_f32 v228, v148, v149
	v_cvt_pk_bf16_f32 v229, v150, v151
	v_cvt_pk_bf16_f32 v230, v152, v153
	v_cvt_pk_bf16_f32 v231, v154, v155
	global_store_dwordx4 v240, v[228:231], s[78:79] nt
	ds_read2_b32 v[148:149], v239 offset0:16 offset1:49
	ds_read2_b32 v[150:151], v239 offset0:82 offset1:115
	ds_read2_b32 v[152:153], v239 offset0:148 offset1:181
	ds_read2_b32 v[154:155], v239 offset0:214 offset1:247
	s_waitcnt lgkmcnt(4)
	v_cvt_pk_bf16_f32 v232, v156, v157
	v_cvt_pk_bf16_f32 v233, v158, v159
	v_cvt_pk_bf16_f32 v234, v160, v161
	v_cvt_pk_bf16_f32 v235, v162, v163
	s_mul_i32 s92, s81, 8
	s_add_u32 s94, s78, s92
	s_addc_u32 s95, s79, 0
	global_store_dwordx4 v240, v[232:235], s[94:95] nt
	ds_read2_b32 v[156:157], v239 offset0:24 offset1:57
	ds_read2_b32 v[158:159], v239 offset0:90 offset1:123
	ds_read2_b32 v[160:161], v239 offset0:156 offset1:189
	ds_read2_b32 v[162:163], v239 offset0:222 offset1:255
	s_waitcnt lgkmcnt(4)
	v_cvt_pk_bf16_f32 v228, v148, v149
	v_cvt_pk_bf16_f32 v229, v150, v151
	v_cvt_pk_bf16_f32 v230, v152, v153
	v_cvt_pk_bf16_f32 v231, v154, v155
	s_mul_i32 s92, s81, 16
	s_add_u32 s94, s78, s92
	s_addc_u32 s95, s79, 0
	global_store_dwordx4 v240, v[228:231], s[94:95] nt
	s_waitcnt lgkmcnt(0)
	v_cvt_pk_bf16_f32 v232, v156, v157
	v_cvt_pk_bf16_f32 v233, v158, v159
	v_cvt_pk_bf16_f32 v234, v160, v161
	v_cvt_pk_bf16_f32 v235, v162, v163
	s_mul_i32 s92, s81, 24
	s_add_u32 s94, s78, s92
	s_addc_u32 s95, s79, 0
	global_store_dwordx4 v240, v[232:235], s[94:95] nt
.Lcsa_adv:
	s_cmp_eq_u32 s66, 0
	s_cbranch_scc0 .Lcsa_nexttile
	s_mov_b32 s66, 1
	s_branch .Lcsa_find
.Lcsa_nexttile:
	s_mov_b32 s66, 0
	s_add_u32 s65, s65, s70
.Lcsa_find:
	s_cmp_lt_u32 s67, 7
	s_cbranch_scc1 .Lcsa_setup
	s_mov_b32 s69, 0
	s_branch .Lcsa_end
; #define GAS __attribute__((address_space(1)))
; #define LAS __attribute__((address_space(3)))
; __device__ __forceinline__ void conv_load(const float* W, int K, int N, int Np, int item, int lane, f32x4 (&v)[2][8]) {
;     const int nblk = Np / 64, kb = item / nblk, nb = item % nblk, k0 = 64 * kb, n0 = 64 * nb;
;     const int kr = lane >> 3, n4 = lane & 7;
; #pragma unroll
;     for (int hf = 0; hf < 2; ++hf)
; #pragma unroll
;         for (int i = 0; i < 8; ++i) { const int k = k0 + 8 * i + kr, n = n0 + 32 * hf + 4 * n4;
;             v[hf][i] = (k < K && n < N) ? __builtin_nontemporal_load((const GAS f32x4*)(W + (size_t)k * N + n)) : (f32x4){0.f, 0.f, 0.f, 0.f}; }
; }
; __device__ __forceinline__ void convert_mats(Frame& F, int m_lo, int m_hi, int gw, int NGW) {
;     LAS float* scr = (LAS float*)(F.lds + F.wave * 16384);
;     int it = gw, base = 0;
;     for (int mi = m_lo; mi < m_hi; ++mi) {
;         const MatI mt = kMats[mi]; const int cnt = (mt.Kp / 64) * (mt.Np / 64);
;         const float* src = in_ptr(F, mt.in_idx) + mt.src_off; const float* gain = mt.gain_idx >= 0 ? in_ptr(F, mt.gain_idx) + mt.gain_off : nullptr; bf16* dst = (bf16*)((unsigned char*)in_ptr(F, T_WS) + mt.dst_off);
;         while (it < base + cnt) {
;             f32x4 va[2][8], vb[2][8];
;             const int lim = base + cnt, i1 = it + NGW;
;             conv_load(src, mt.K, mt.N, mt.Np, it - base, F.lane, va);
;             if (i1 < lim) conv_load(src, mt.K, mt.N, mt.Np, i1 - base, F.lane, vb);
;             conv_proc(va, gain, mt.K, mt.Kp, mt.Np, mt.ilv, dst, scr, it - base, F.lane);
;             if (i1 < lim) conv_proc(vb, gain, mt.K, mt.Kp, mt.Np, mt.ilv, dst, scr, i1 - base, F.lane);
;             it = (i1 < lim) ? i1 + NGW : i1;
;         }
;         base += cnt;
;     }
.Lcsa_setup:
	s_cmp_lg_u32 s67, 0
	s_cbranch_scc1 .Lcsa_m1
	s_mov_b32 s82, 96
	s_mov_b32 s83, 0x2aaaaab
	s_mov_b32 s84, 0x6000
	s_mov_b32 s85, 0x1000
	s_mov_b32 s86, 0
	s_mov_b32 s87, 3072
	s_mov_b32 s88, 0x0
	s_mov_b32 s90, 0xc700000
	s_mov_b32 s93, 0x204b8
	s_mov_b32 s89, 0x0
	s_mov_b32 s94, 0x204b0
	s_branch .Lcsa_have
.Lcsa_m1:
	s_cmp_lg_u32 s67, 1
	s_cbranch_scc1 .Lcsa_m2
	s_mov_b32 s82, 32
	s_mov_b32 s83, 0x8000000
	s_mov_b32 s84, 0x2000
	s_mov_b32 s85, 0x1000
	s_mov_b32 s86, 0
	s_mov_b32 s87, 1024
	s_mov_b32 s88, 0x0
	s_mov_b32 s90, 0xdf00000
	s_mov_b32 s93, 0x204c8
	s_mov_b32 s94, 0
	s_branch .Lcsa_have
.Lcsa_m2:
	s_cmp_lg_u32 s67, 2
	s_cbranch_scc1 .Lcsa_m3
	s_mov_b32 s82, 176
	s_mov_b32 s83, 0x1745d18
	s_mov_b32 s84, 0xb000
	s_mov_b32 s85, 0x1000
	s_mov_b32 s86, 5632
	s_mov_b32 s87, 5632
	s_mov_b32 s88, 0xb000000
	s_mov_b32 s90, 0x13f00000
	s_mov_b32 s93, 0x204d8
	s_mov_b32 s89, 0x4000
	s_mov_b32 s94, 0x204d0
	s_branch .Lcsa_have
.Lcsa_m3:
	s_cmp_lg_u32 s67, 3
	s_cbranch_scc1 .Lcsa_m4
	s_mov_b32 s82, 32
	s_mov_b32 s83, 0x8000000
	s_mov_b32 s84, 0x2000
	s_mov_b32 s85, 0x2c00
	s_mov_b32 s86, 0
	s_mov_b32 s87, 2816
	s_mov_b32 s88, 0x5800000
	s_mov_b32 s90, 0x1c300000
	s_mov_b32 s93, 0x204f0
	s_mov_b32 s94, 0
	s_branch .Lcsa_have
.Lcsa_m4:
	s_cmp_lg_u32 s67, 4
	s_cbranch_scc1 .Lcsa_m5
	s_mov_b32 s82, 32
	s_mov_b32 s83, 0x8000000
	s_mov_b32 s84, 0x2000
	s_mov_b32 s85, 0x1000
	s_mov_b32 s86, 0
	s_mov_b32 s87, 1024
	s_mov_b32 s88, 0x2000000
	s_mov_b32 s90, 0x1ff00000
	s_mov_b32 s93, 0x20508
	s_mov_b32 s89, 0x4000
	s_mov_b32 s94, 0x20500
	s_branch .Lcsa_have
.Lcsa_m5:
	s_cmp_lg_u32 s67, 5
	s_cbranch_scc1 .Lcsa_m6
	s_mov_b32 s82, 288
	s_mov_b32 s83, 0xe38e39
	s_mov_b32 s84, 0x12000
	s_mov_b32 s85, 0x1000
	s_mov_b32 s86, 0
	s_mov_b32 s87, 9216
	s_mov_b32 s88, 0x9000000
	s_mov_b32 s90, 0x4900000
	s_mov_b32 s93, 0x20418
	s_mov_b32 s89, 0x2000
	s_mov_b32 s94, 0x20410
	s_branch .Lcsa_have
.Lcsa_m6:
	s_mov_b32 s82, 32
	s_mov_b32 s83, 0x8000000
	s_mov_b32 s84, 0x2000
	s_mov_b32 s85, 0x1000
	s_mov_b32 s86, 0
	s_mov_b32 s87, 1024
	s_mov_b32 s88, 0x1000000
	s_mov_b32 s90, 0x9900000
	s_mov_b32 s93, 0x20420
	s_mov_b32 s94, 0
.Lcsa_have:
	s_add_u32 s91, s68, s87
	s_cmp_lt_u32 s65, s91
	s_cbranch_scc1 .Lcsa_found
	s_mov_b32 s68, s91
	s_add_u32 s67, s67, 1
	s_branch .Lcsa_find
.Lcsa_found:
	v_mov_b32_e32 v243, s93
	ds_read_b64 v[244:245], v243
	s_waitcnt lgkmcnt(0)
	s_nop 0
	v_readfirstlane_b32 s74, v244
	v_readfirstlane_b32 s75, v245
	s_nop 0
	s_add_u32 s74, s74, s88
	s_addc_u32 s75, s75, 0
	s_mov_b32 s71, 0
	s_cmp_eq_u32 s94, 0
	s_cbranch_scc1 .Lcsa_nog2
	v_mov_b32_e32 v243, s94
	ds_read_b64 v[244:245], v243
	s_waitcnt lgkmcnt(0)
	s_nop 0
	v_readfirstlane_b32 s76, v244
	v_readfirstlane_b32 s77, v245
	s_nop 0
	s_add_u32 s76, s76, s89
	s_addc_u32 s77, s77, 0
	s_mov_b32 s71, 1
.Lcsa_nog2:
	s_add_i32 s92, 0, 0x20520
	v_mov_b32_e32 v243, s92
	ds_read_b64 v[244:245], v243
	s_waitcnt lgkmcnt(0)
	s_nop 0
	v_readfirstlane_b32 s78, v244
	v_readfirstlane_b32 s79, v245
	s_nop 0
	s_add_u32 s78, s78, s90
	s_addc_u32 s79, s79, 0
	s_sub_u32 s92, s65, s68
	s_mul_hi_u32 s93, s92, s83
	s_mul_i32 s94, s93, s82
	s_sub_u32 s94, s92, s94
	s_lshl_b32 s92, s84, 6
	s_mul_i32 s92, s92, s93
	s_lshl_b32 s95, s94, 8
	s_add_u32 s92, s92, s95
	s_lshl_b32 s95, s66, 7
	s_add_u32 s92, s92, s95
	s_add_u32 s74, s74, s92
	s_addc_u32 s75, s75, 0
	s_lshl_b32 s92, s93, 8
	s_add_u32 s76, s76, s92
	s_addc_u32 s77, s77, 0
	s_lshl_b32 s95, s94, 6
	s_cmp_eq_u32 s86, 0
	s_cbranch_scc1 .Lcsa_noilv
	s_cmp_ge_u32 s95, s86
	s_cselect_b32 s92, s86, 0
	s_cselect_b32 s97, 128, 0
	s_sub_u32 s95, s95, s92
	s_lshr_b32 s92, s95, 7
	s_lshl_b32 s92, s92, 8
	s_and_b32 s95, s95, 127
	s_add_u32 s95, s95, s92
	s_add_u32 s95, s95, s97
.Lcsa_noilv:
	s_lshl_b32 s92, s66, 5
	s_add_u32 s95, s95, s92
	s_mul_i32 s95, s95, s85
	s_lshl_b32 s92, s93, 7
	s_add_u32 s95, s95, s92
	s_add_u32 s78, s78, s95
	s_addc_u32 s79, s79, 0
	s_mov_b32 s81, s85
	s_mov_b32 s69, 1
	v_mbcnt_lo_u32_b32 v243, -1, 0
	v_mbcnt_hi_u32_b32 v243, -1, v243
	v_lshrrev_b32_e32 v241, 3, v243
	v_and_b32_e32 v242, 7, v243
	v_mul_lo_u32 v243, v241, s84
	v_lshl_add_u32 v236, v242, 4, v243
	v_lshlrev_b32_e32 v237, 2, v241
	s_lshl_b32 s92, s84, 3
	global_load_dwordx4 v[188:191], v236, s[74:75] nt
	s_add_u32 s74, s74, s92
	s_addc_u32 s75, s75, 0
	global_load_dwordx4 v[192:195], v236, s[74:75] nt
	s_add_u32 s74, s74, s92
	s_addc_u32 s75, s75, 0
	global_load_dwordx4 v[196:199], v236, s[74:75] nt
	s_add_u32 s74, s74, s92
	s_addc_u32 s75, s75, 0
	global_load_dwordx4 v[200:203], v236, s[74:75] nt
	s_add_u32 s74, s74, s92
	s_addc_u32 s75, s75, 0
	global_load_dwordx4 v[204:207], v236, s[74:75] nt
	s_add_u32 s74, s74, s92
	s_addc_u32 s75, s75, 0
	global_load_dwordx4 v[208:211], v236, s[74:75] nt
	s_add_u32 s74, s74, s92
	s_addc_u32 s75, s75, 0
	global_load_dwordx4 v[212:215], v236, s[74:75] nt
	s_add_u32 s74, s74, s92
	s_addc_u32 s75, s75, 0
	global_load_dwordx4 v[216:219], v236, s[74:75] nt
	s_cmp_eq_u32 s71, 0
	s_cbranch_scc1 .Lcsa_end
	s_cmp_eq_u32 s66, 0
	s_cbranch_scc0 .Lcsa_end
	global_load_dword v220, v237, s[76:77]
	global_load_dword v221, v237, s[76:77] offset:32
	global_load_dword v222, v237, s[76:77] offset:64
	global_load_dword v223, v237, s[76:77] offset:96
	global_load_dword v224, v237, s[76:77] offset:128
	global_load_dword v225, v237, s[76:77] offset:160
	global_load_dword v226, v237, s[76:77] offset:192
	global_load_dword v227, v237, s[76:77] offset:224

; #define LAS __attribute__((address_space(3)))
; __device__ __forceinline__ void conv_proc(f32x4 (&v)[2][8], const float* gain, int K, int Kp, int Np, int ilv, bf16* WT, LAS float* scr, int item, int lane) {
;     const int nblk = Np / 64, kb = item / nblk, nb = item % nblk, k0 = 64 * kb, n0 = 64 * nb;
;     const int d0 = ilv ? (((n0 % ilv) >> 7) * 256 + (n0 / ilv) * 128 + ((n0 % ilv) & 127)) : n0;
;     const int kr = lane >> 3, n4 = lane & 7;
;     if (gain) {
; #pragma unroll
;         for (int i = 0; i < 8; ++i) { const int k = k0 + 8 * i + kr; const float g = k < K ? gain[k] : 0.f; v[0][i] *= g; v[1][i] *= g; } }
.LBB0_1797:
	s_or_b64 exec, exec, s[60:61]
	v_add_f32_e32 v181, v181, v182
	v_rsq_f32_e32 v181, v181
	ds_write_b128 v172, v[28:31] offset:45056
	ds_write_b128 v172, v[24:27] offset:53248
	ds_write_b128 v172, v[32:35] offset:61440
	v_max_f32_e64 v28, -v181, s35
	v_pk_mul_f32 v[30:31], v[142:143], v[28:29] op_sel_hi:[1,0]
	v_pk_mul_f32 v[28:29], v[144:145], v[28:29] op_sel_hi:[1,0]
	ds_write_b128 v178, v[28:31]
	v_pk_mul_f32 v[30:31], v[30:31], v[140:141] neg_lo:[1,0] neg_hi:[1,0]
	v_pk_mul_f32 v[28:29], v[28:29], v[138:139] neg_lo:[1,0] neg_hi:[1,0]
	ds_write_b128 v179, v[28:31]
	s_and_saveexec_b64 s[60:61], s[8:9]
	v_lshlrev_b32_e32 v28, 16, v64
	v_and_b32_e32 v29, 0xffff0000, v64
	v_lshlrev_b32_e32 v30, 16, v65
	v_and_b32_e32 v31, 0xffff0000, v65
	ds_write_b128 v180, v[28:31]
	s_or_b64 exec, exec, s[60:61]
	s_waitcnt lgkmcnt(0)
	s_barrier
	s_cmp_lt_u32 s80, 5
	s_cbranch_scc1 .Lcsb_end
	s_cmp_eq_u32 s69, 0
	s_cbranch_scc1 .Lcsb_adv
	v_mbcnt_lo_u32_b32 v243, -1, 0
	v_mbcnt_hi_u32_b32 v243, -1, v243
	s_sub_u32 s92, s80, 5
	s_mul_i32 s92, s92, 0x2100
	s_add_u32 s92, s92, 0x19200
	v_lshrrev_b32_e32 v241, 3, v243
	v_and_b32_e32 v242, 7, v243
	v_mul_u32_u24_e32 v243, 132, v241
	v_lshl_add_u32 v243, v242, 4, v243
	v_add_u32_e32 v238, s92, v243
	v_mul_u32_u24_e32 v243, 0x420, v242
	v_lshl_add_u32 v243, v241, 2, v243
	v_add_u32_e32 v239, s92, v243
	v_mul_lo_u32 v243, v241, s81
	v_lshl_add_u32 v240, v242, 4, v243
	s_waitcnt vmcnt(0)
	s_cmp_eq_u32 s71, 0
	s_cbranch_scc1 .Lcsb_nogain
	v_pk_mul_f32 v[188:189], v[188:189], v[220:221] op_sel_hi:[1,0]
	v_pk_mul_f32 v[190:191], v[190:191], v[220:221] op_sel_hi:[1,0]
	v_pk_mul_f32 v[192:193], v[192:193], v[220:221] op_sel:[0,1] op_sel_hi:[1,1]
	v_pk_mul_f32 v[194:195], v[194:195], v[220:221] op_sel:[0,1] op_sel_hi:[1,1]
	v_pk_mul_f32 v[196:197], v[196:197], v[222:223] op_sel_hi:[1,0]
	v_pk_mul_f32 v[198:199], v[198:199], v[222:223] op_sel_hi:[1,0]
	v_pk_mul_f32 v[200:201], v[200:201], v[222:223] op_sel:[0,1] op_sel_hi:[1,1]
	v_pk_mul_f32 v[202:203], v[202:203], v[222:223] op_sel:[0,1] op_sel_hi:[1,1]
	v_pk_mul_f32 v[204:205], v[204:205], v[224:225] op_sel_hi:[1,0]
	v_pk_mul_f32 v[206:207], v[206:207], v[224:225] op_sel_hi:[1,0]
	v_pk_mul_f32 v[208:209], v[208:209], v[224:225] op_sel:[0,1] op_sel_hi:[1,1]
	v_pk_mul_f32 v[210:211], v[210:211], v[224:225] op_sel:[0,1] op_sel_hi:[1,1]
	v_pk_mul_f32 v[212:213], v[212:213], v[226:227] op_sel_hi:[1,0]
	v_pk_mul_f32 v[214:215], v[214:215], v[226:227] op_sel_hi:[1,0]
	v_pk_mul_f32 v[216:217], v[216:217], v[226:227] op_sel:[0,1] op_sel_hi:[1,1]
	v_pk_mul_f32 v[218:219], v[218:219], v[226:227] op_sel:[0,1] op_sel_hi:[1,1]

.Lcsb_end:
	ds_read_b128 v[28:31], v168
	v_add_co_u32_e32 v34, vcc, 0x49140000, v86
	s_waitcnt lgkmcnt(0)
	v_cvt_pk_bf16_f32 v32, v28, v29
	v_cvt_pk_bf16_f32 v33, v30, v31
	v_mul_f32_e32 v139, v31, v31
	v_addc_co_u32_e32 v35, vcc, 0, v87, vcc
	global_store_dwordx2 v[34:35], v[32:33], off
	v_mul_f32_e32 v33, v28, v28
	v_mul_f32_e32 v35, v29, v29
	v_mul_f32_e32 v87, v30, v30
	v_mov_b32_e32 v32, v28
	v_mov_b32_e32 v34, v29
	v_mov_b32_e32 v86, v30
	v_mov_b32_e32 v138, v31
	v_pk_add_f32 v[28:29], v[32:33], v[34:35]
	v_pk_add_f32 v[30:31], v[86:87], v[138:139]
	s_nop 0
	v_pk_add_f32 v[28:29], v[28:29], v[30:31]
	s_nop 1
	v_mov_b32_dpp v30, v28 quad_perm:[1,0,3,2] row_mask:0xf bank_mask:0xf bound_ctrl:1
	v_mov_b32_dpp v31, v29 quad_perm:[1,0,3,2] row_mask:0xf bank_mask:0xf bound_ctrl:1
	v_pk_add_f32 v[28:29], v[28:29], v[30:31]
	s_nop 1
	v_mov_b32_dpp v30, v28 quad_perm:[2,3,0,1] row_mask:0xf bank_mask:0xf bound_ctrl:1
	v_mov_b32_dpp v31, v29 quad_perm:[2,3,0,1] row_mask:0xf bank_mask:0xf bound_ctrl:1
	v_pk_add_f32 v[28:29], v[28:29], v[30:31]
	s_nop 1
	v_mov_b32_dpp v30, v28 row_half_mirror row_mask:0xf bank_mask:0xf bound_ctrl:1
	v_mov_b32_dpp v31, v29 row_half_mirror row_mask:0xf bank_mask:0xf bound_ctrl:1
	s_and_saveexec_b64 s[60:61], s[4:5]
	s_cbranch_execz .LBB0_1802
	v_pk_add_f32 v[28:29], v[28:29], v[30:31]
	v_add_co_u32_e32 v30, vcc, 0x48708000, v84
	s_nop 1
	v_addc_co_u32_e32 v31, vcc, 0, v85, vcc
	global_store_dwordx2 v[30:31], v[28:29], off
	s_or_b64 exec, exec, s[60:61]
	s_cmp_gt_u32 s58, 60
	s_cbranch_scc0 .LBB0_1803

; #define LAS __attribute__((address_space(3)))
; __device__ __forceinline__ void conv_proc(f32x4 (&v)[2][8], const float* gain, int K, int Kp, int Np, int ilv, bf16* WT, LAS float* scr, int item, int lane) {
;     const int nblk = Np / 64, kb = item / nblk, nb = item % nblk, k0 = 64 * kb, n0 = 64 * nb;
;     const int d0 = ilv ? (((n0 % ilv) >> 7) * 256 + (n0 / ilv) * 128 + ((n0 % ilv) & 127)) : n0;
;     const int kr = lane >> 3, n4 = lane & 7;
;     if (gain) {
; #pragma unroll
;         for (int i = 0; i < 8; ++i) { const int k = k0 + 8 * i + kr; const float g = k < K ? gain[k] : 0.f; v[0][i] *= g; v[1][i] *= g; } }
; __device__ __forceinline__ void convert_mats(Frame& F, int m_lo, int m_hi, int gw, int NGW) {
;     ...
;     for (int mi = m_lo; mi < m_hi; ++mi) {
;         const MatI mt = kMats[mi]; const int cnt = (mt.Kp / 64) * (mt.Np / 64);
;         const float* src = in_ptr(F, mt.in_idx) + mt.src_off; const float* gain = mt.gain_idx >= 0 ? in_ptr(F, mt.gain_idx) + mt.gain_off : nullptr; bf16* dst = (bf16*)((unsigned char*)in_ptr(F, T_WS) + mt.dst_off);
;         while (it < base + cnt) {
;             f32x4 va[2][8], vb[2][8];
;             const int lim = base + cnt, i1 = it + NGW;
;             conv_load(src, mt.K, mt.N, mt.Np, it - base, F.lane, va);
;             if (i1 < lim) conv_load(src, mt.K, mt.N, mt.Np, i1 - base, F.lane, vb);
;             conv_proc(va, gain, mt.K, mt.Kp, mt.Np, mt.ilv, dst, scr, it - base, F.lane);
;             if (i1 < lim) conv_proc(vb, gain, mt.K, mt.Kp, mt.Np, mt.ilv, dst, scr, i1 - base, F.lane);
;             it = (i1 < lim) ? i1 + NGW : i1;
;         }
.LBB0_1812:
	s_cmp_lt_u32 s80, 5
	s_cbranch_scc1 .Lcsd_dskip
.Lcsd_dloop:
	s_cmp_eq_u32 s69, 0
	s_cbranch_scc1 .Lcsd_adv
	v_mbcnt_lo_u32_b32 v243, -1, 0
	v_mbcnt_hi_u32_b32 v243, -1, v243
	s_sub_u32 s92, s80, 5
	s_mul_i32 s92, s92, 0x2100
	s_add_u32 s92, s92, 0x19200
	v_lshrrev_b32_e32 v241, 3, v243
	v_and_b32_e32 v242, 7, v243
	v_mul_u32_u24_e32 v243, 132, v241
	v_lshl_add_u32 v243, v242, 4, v243
	v_add_u32_e32 v238, s92, v243
	v_mul_u32_u24_e32 v243, 0x420, v242
	v_lshl_add_u32 v243, v241, 2, v243
	v_add_u32_e32 v239, s92, v243
	v_mul_lo_u32 v243, v241, s81
	v_lshl_add_u32 v240, v242, 4, v243
	s_waitcnt vmcnt(0)
	s_cmp_eq_u32 s71, 0
	s_cbranch_scc1 .Lcsd_nogain
	v_pk_mul_f32 v[188:189], v[188:189], v[220:221] op_sel_hi:[1,0]
	v_pk_mul_f32 v[190:191], v[190:191], v[220:221] op_sel_hi:[1,0]
	v_pk_mul_f32 v[192:193], v[192:193], v[220:221] op_sel:[0,1] op_sel_hi:[1,1]
	v_pk_mul_f32 v[194:195], v[194:195], v[220:221] op_sel:[0,1] op_sel_hi:[1,1]
	v_pk_mul_f32 v[196:197], v[196:197], v[222:223] op_sel_hi:[1,0]
	v_pk_mul_f32 v[198:199], v[198:199], v[222:223] op_sel_hi:[1,0]
	v_pk_mul_f32 v[200:201], v[200:201], v[222:223] op_sel:[0,1] op_sel_hi:[1,1]
	v_pk_mul_f32 v[202:203], v[202:203], v[222:223] op_sel:[0,1] op_sel_hi:[1,1]
	v_pk_mul_f32 v[204:205], v[204:205], v[224:225] op_sel_hi:[1,0]
	v_pk_mul_f32 v[206:207], v[206:207], v[224:225] op_sel_hi:[1,0]
	v_pk_mul_f32 v[208:209], v[208:209], v[224:225] op_sel:[0,1] op_sel_hi:[1,1]
	v_pk_mul_f32 v[210:211], v[210:211], v[224:225] op_sel:[0,1] op_sel_hi:[1,1]
	v_pk_mul_f32 v[212:213], v[212:213], v[226:227] op_sel_hi:[1,0]
	v_pk_mul_f32 v[214:215], v[214:215], v[226:227] op_sel_hi:[1,0]
	v_pk_mul_f32 v[216:217], v[216:217], v[226:227] op_sel:[0,1] op_sel_hi:[1,1]
	v_pk_mul_f32 v[218:219], v[218:219], v[226:227] op_sel:[0,1] op_sel_hi:[1,1]

; __device__ __forceinline__ void convert_mats(Frame& F, int m_lo, int m_hi, int gw, int NGW) {
;     ...
;         while (it < base + cnt) {
;             f32x4 va[2][8], vb[2][8];
;             const int lim = base + cnt, i1 = it + NGW;
;             conv_load(src, mt.K, mt.N, mt.Np, it - base, F.lane, va);
;             if (i1 < lim) conv_load(src, mt.K, mt.N, mt.Np, i1 - base, F.lane, vb);
;             conv_proc(va, gain, mt.K, mt.Kp, mt.Np, mt.ilv, dst, scr, it - base, F.lane);
;             if (i1 < lim) conv_proc(vb, gain, mt.K, mt.Kp, mt.Np, mt.ilv, dst, scr, i1 - base, F.lane);
;             it = (i1 < lim) ? i1 + NGW : i1;
;         }
.Lcsd_end:
	s_cmp_eq_u32 s69, 1
	s_cbranch_scc1 .Lcsd_dloop

;     __device__ __forceinline__ void ids() { lane = fresh_lane(); tid = wave * 64 + lane; }
; #define ws ((unsigned char*)in_ptr(F, T_WS))
; template <int L> __device__ __forceinline__ void layer_phases(Frame& F, const int lo, const int hi, const XcdBarrier& bar, const int bid) {
;     ...
;         {
;             const int rem = (M / 256) * (2 * FF / 256) % F.G, nidle = rem ? F.G - rem : 0, ci = bid - rem;
;             if (nidle > 0 && ci >= 0) {
;                 if constexpr (L == 0) {
;                     pg8::Gemm g2{(const bf16*)(ws + WS_PB), (const bf16*)(ws + WS_WPP), M, 4 * D, PLE, (size_t)M * PLE * 2, 8, 1 << 30};
;                     pg8::StaticOrder S2; S2.init(M, 4 * D, nidle, ci);
;                     pg8::EpiScaleBf16<false> E2{(bf16*)(ws + WS_PPO), D, nullptr, D, (size_t)M * D, nullptr};
;                     pg8::gemm_phase<pg8::EpiScaleBf16<false>, pg8::StaticOrder, false, true>(F.lds, g2, S2, E2, F.wave);
;                 } else if constexpr (L == 1) { F.ids(); convert_mats(F, 27, 29, ci * NWAVES + F.wave, nidle * NWAVES); }
;                 else if constexpr (L == 2) { F.ids(); convert_mats(F, 29, 32, ci * NWAVES + F.wave, nidle * NWAVES); }
;             } else if (nidle == 0) {
;                 if constexpr (L == 0) {
;                     pg8::Gemm g2{(const bf16*)(ws + WS_PB), (const bf16*)(ws + WS_WPP), M, 4 * D, PLE, (size_t)M * PLE * 2, 8, 1 << 30};
;                     pg8::StaticOrder S2; S2.init(M, 4 * D, F.G, bid);
;                     pg8::EpiScaleBf16<false> E2{(bf16*)(ws + WS_PPO), D, nullptr, D, (size_t)M * D, nullptr};
;                     pg8::gemm_phase<pg8::EpiScaleBf16<false>, pg8::StaticOrder, false, true>(F.lds, g2, S2, E2, F.wave);
;                 } else if constexpr (L == 1) { F.ids(); convert_mats(F, 27, 29, bid * NWAVES + F.wave, F.G * NWAVES); }
;                 else if constexpr (L == 2) { F.ids(); convert_mats(F, 29, 32, bid * NWAVES + F.wave, F.G * NWAVES); }
;             }
.LBB0_2066:
	s_andn2_b64 vcc, exec, s[0:1]
	s_cbranch_vccnz .LBB0_2182
	v_mbcnt_lo_u32_b32 v0, -1, 0
	v_mbcnt_hi_u32_b32 v0, -1, v0
	s_lshl_b32 s0, s33, 3
	s_add_i32 s20, s0, s80
	s_lshl_b32 s0, s80, 14
	v_ashrrev_i32_e32 v141, 3, v0
	v_lshlrev_b32_e32 v1, 2, v0
	v_and_b32_e32 v0, 7, v0
	s_add_i32 s0, s0, 0
	v_mul_u32_u24_e32 v3, 0x420, v0
	s_waitcnt lgkmcnt(6)
	v_lshlrev_b32_e32 v4, 2, v141
	v_and_b32_e32 v143, 28, v1
	v_lshl_add_u32 v1, v0, 4, s0
	v_add3_u32 v145, s0, v3, v4
	s_movk_i32 s0, 0x84
	v_lshlrev_b32_e32 v2, 3, v0
	v_mul_lo_u32 v3, v141, s0
	s_lshl_b32 s3, s3, 3
	s_mov_b32 s39, 0
	v_mov_b32_e32 v0, 0
	v_add_u32_e32 v147, 8, v141
	v_add_u32_e32 v149, 16, v141
	v_add_u32_e32 v151, 24, v141
	s_mov_b64 s[0:1], 30
	s_mov_b64 s[44:45], 0
	s_add_i32 s33, 0, 0x20520
	v_lshlrev_b32_e32 v132, 1, v2
	v_add_u32_e32 v152, v1, v3
	s_mov_b32 s34, 0
	s_branch .LBB0_2069
.LBB0_2068:
	s_mov_b64 s[0:1], 31
	s_and_b64 vcc, exec, s[44:45]
	s_mov_b32 s34, s35
	s_mov_b64 s[44:45], -1
	s_cbranch_vccnz .LBB0_2182

;     __device__ __forceinline__ void ids() { lane = fresh_lane(); tid = wave * 64 + lane; }
; #define SEAM(k) do { } while (0)
; #define SEAM(k) do { if ((k) + 1 < hi) { XcdBarrier b_; b_.bar = (unsigned*)(ws + WS_CTL) + CW_BAR; b_.x = xb_xcc_id(); b_.st = (volatile LAS unsigned*)(F.lds + MISC_OFF) + 8; xcd_barrier(b_); } } while (0)
; #define ws ((unsigned char*)in_ptr(F, T_WS))
; template <int L> __device__ __forceinline__ void layer_phases(Frame& F, const int lo, const int hi, const XcdBarrier& bar, const int bid) {
;     ...
;         {
;             const int rem = (M / 256) * (2 * FF / 256) % F.G, nidle = rem ? F.G - rem : 0, ci = bid - rem;
;             if (nidle > 0 && ci >= 0) {
;                 if constexpr (L == 0) {
;                     pg8::Gemm g2{(const bf16*)(ws + WS_PB), (const bf16*)(ws + WS_WPP), M, 4 * D, PLE, (size_t)M * PLE * 2, 8, 1 << 30};
;                     pg8::StaticOrder S2; S2.init(M, 4 * D, nidle, ci);
;                     pg8::EpiScaleBf16<false> E2{(bf16*)(ws + WS_PPO), D, nullptr, D, (size_t)M * D, nullptr};
;                     pg8::gemm_phase<pg8::EpiScaleBf16<false>, pg8::StaticOrder, false, true>(F.lds, g2, S2, E2, F.wave);
;                 } else if constexpr (L == 1) { F.ids(); convert_mats(F, 27, 29, ci * NWAVES + F.wave, nidle * NWAVES); }
;                 else if constexpr (L == 2) { F.ids(); convert_mats(F, 29, 32, ci * NWAVES + F.wave, nidle * NWAVES); }
;             } else if (nidle == 0) {
;                 if constexpr (L == 0) {
;                     pg8::Gemm g2{(const bf16*)(ws + WS_PB), (const bf16*)(ws + WS_WPP), M, 4 * D, PLE, (size_t)M * PLE * 2, 8, 1 << 30};
;                     pg8::StaticOrder S2; S2.init(M, 4 * D, F.G, bid);
;                     pg8::EpiScaleBf16<false> E2{(bf16*)(ws + WS_PPO), D, nullptr, D, (size_t)M * D, nullptr};
;                     pg8::gemm_phase<pg8::EpiScaleBf16<false>, pg8::StaticOrder, false, true>(F.lds, g2, S2, E2, F.wave);
;                 } else if constexpr (L == 1) { F.ids(); convert_mats(F, 27, 29, bid * NWAVES + F.wave, F.G * NWAVES); }
;                 else if constexpr (L == 2) { F.ids(); convert_mats(F, 29, 32, bid * NWAVES + F.wave, F.G * NWAVES); }
;             }
;         }
;         SEAM(pb + 6);
.LBB0_2842:
	s_andn2_b64 vcc, exec, s[0:1]
	s_cbranch_vccnz .LBB0_2958
.LBB0_2958:
	s_cmp_lt_i32 s57, 30
	s_cbranch_scc1 .LBB0_3127
	s_add_i32 s0, 0, 0x20520
	v_mov_b32_e32 v0, s0
	ds_read_b64 v[0:1], v0
	s_getreg_b32 s3, hwreg(HW_REG_XCC_ID, 0, 4)
	s_waitcnt vmcnt(0)
	s_waitcnt vmcnt(16) lgkmcnt(0)
	s_barrier
	v_readfirstlane_b32 s4, v0
	v_readfirstlane_b32 s5, v1
	s_mov_b64 s[0:1], exec
	v_readlane_b32 s6, v246, 2
	v_readlane_b32 s7, v246, 3
	s_and_b64 s[6:7], s[0:1], s[6:7]
	s_mov_b64 exec, s[6:7]
	s_cbranch_execz .LBB0_3126
	s_add_i32 s6, 0, 0x20160
	v_mov_b32_e32 v0, s6
	s_waitcnt vmcnt(0) expcnt(0) lgkmcnt(0)
	ds_read_b32 v2, v0
	s_add_i32 s6, 0, 0x20164
	v_mov_b32_e32 v0, s6
	ds_read_b32 v0, v0
	s_and_b32 s3, s3, 15
	s_waitcnt lgkmcnt(1)
	v_cmp_ne_u32_e32 vcc, 0, v2
	s_cbranch_vccnz .LBB0_3090
	v_readlane_b32 s6, v246, 0
	v_readlane_b32 s7, v246, 1
	s_load_dwordx2 s[10:11], s[6:7], 0x4
	s_add_u32 s6, s4, 0x4200
	s_addc_u32 s7, s5, 0
	s_add_u32 s8, s4, 0x4400
	s_addc_u32 s9, s5, 0
	s_waitcnt lgkmcnt(0)
	s_mul_i32 s33, s10, s52
	s_add_u32 s10, s4, 0x4500
	s_mul_i32 s33, s33, s11
	s_addc_u32 s11, s5, 0
	s_add_u32 s12, s4, 0x4600
	s_addc_u32 s13, s5, 0
	s_add_u32 s14, s4, 0x4700
	s_addc_u32 s15, s5, 0
	s_add_u32 s16, s4, 0x4800
	s_addc_u32 s17, s5, 0
	s_add_u32 s18, s4, 0x4900
	s_addc_u32 s19, s5, 0
	s_add_u32 s20, s4, 0x4a00
	s_addc_u32 s21, s5, 0
	s_add_u32 s22, s4, 0x4b00
	s_addc_u32 s23, s5, 0
	s_add_u32 s24, s4, 0x4c00
	s_addc_u32 s25, s5, 0
	s_add_u32 s26, s4, 0x4d00
	s_addc_u32 s27, s5, 0
	s_add_u32 s28, s4, 0x4e00
	s_addc_u32 s29, s5, 0
	s_add_u32 s30, s4, 0x4f00
	s_addc_u32 s31, s5, 0
	s_add_u32 s36, s4, 0x5000
	s_addc_u32 s37, s5, 0
	s_add_u32 s38, s4, 0x5100
	s_addc_u32 s39, s5, 0
	s_add_u32 s40, s4, 0x5200
	s_addc_u32 s41, s5, 0
	s_add_u32 s42, s4, 0x5300
	s_addc_u32 s43, s5, 0
	s_mov_b32 s34, 1
	v_mov_b32_e32 v16, 0
	s_branch .LBB0_2963
